# K1 saddr DMA + first grid sync via own XCD barrier + half-barrier K-loops (lead keeps pre-MFMA barriers, trail post-MFMA) without setprio in FFN-up, W_in, residual GEMMs
# speedup vs baseline: 1.0222x; 1.0050x over previous
; #define PG8_STAGE(bufoff, gbase, voff) do { _Pragma("unroll") for (int _i = 0; _i < 2; ++_i) \
;         __builtin_amdgcn_global_load_lds((const unsigned*)((const char*)(gbase) + (voff)[_i]), (PG8_LAS unsigned*)(lds + (bufoff) + ldsw + _i * 8192), 16, 0, 0); } while (0)
; #define PG8_WAIT_V(n) asm volatile("s_waitcnt vmcnt(" #n ")" ::: "memory")
; #define PG8_BAR __builtin_amdgcn_s_barrier()
; template <class Epi, class Sched, bool ALIGN_EPI = false, bool SP2 = false>
; __device__ __forceinline__ void gemm_phase(PG8_LAS unsigned char* lds, const Gemm g, const Sched& S, const Epi& E) {
;     ...
;         PG8_STAGE(PG8_SB(0, 0), cB, voffB); PG8_STAGE(PG8_SB(0, 1), cB + hstep, voffB); PG8_STAGE(PG8_SA(0, 0), cA, voffA); PG8_STAGE(PG8_SA(0, 1), cA + hstep, voffA);
;         if (wr == 1) PG8_BAR;
;         PG8_WAIT_V(2); PG8_BAR;
;         PG8_STAGE(PG8_SB(1, 0), cB + kstep, voffB); PG8_STAGE(PG8_SA(1, 0), cA + kstep, voffA); PG8_STAGE(PG8_SB(1, 1), cB + hstep + kstep, voffB);
;         PG8_WAIT_V(6); PG8_BAR;
;     } else {
;         PG8_STAGE(PG8_SB(0, 0), cB, voffB); PG8_STAGE(PG8_SA(0, 0), cA, voffA); PG8_STAGE(PG8_SB(0, 1), cB + hstep, voffB); PG8_STAGE(PG8_SA(0, 1), cA + hstep, voffA);
;         if (wr == 1) PG8_BAR;
;         PG8_WAIT_V(4); PG8_BAR;
;         PG8_STAGE(PG8_SB(1, 0), cB + kstep, voffB); PG8_STAGE(PG8_SA(1, 0), cA + kstep, voffA); PG8_STAGE(PG8_SB(1, 1), cB + hstep + kstep, voffB);
;         PG8_WAIT_V(6); PG8_BAR;
;     }
.LBB0_1124:
	s_add_u32 s12, s62, 0xa400000
	s_addc_u32 s13, s63, 0
	s_add_u32 s28, s62, 0x17400000
	s_addc_u32 s52, s63, 0
	s_add_u32 s54, s62, 0x18400000
	s_addc_u32 s41, s63, 0
	s_add_u32 s14, s62, 0x1dc00000
	v_readlane_b32 s18, v255, 13
	s_addc_u32 s15, s63, 0
	s_lshl_b32 s1, s18, 6
	s_add_u32 s1, s62, s1
	s_addc_u32 s5, s63, 0
	s_add_u32 s16, s1, 0x1e500000
	s_addc_u32 s17, s5, 0
	s_lshl_b32 s1, s18, 7
	s_add_u32 s1, s62, s1
	s_addc_u32 s5, s63, 0
	v_readlane_b32 s19, v255, 14
	s_add_u32 s18, s1, 0x1dd00000
	s_addc_u32 s19, s5, 0
	s_add_u32 s20, s1, 0x1e100000
	s_addc_u32 s21, s5, 0
	s_lshl_b32 s30, s78, 3
	s_lshl_b64 s[50:51], s[30:31], 2
	s_add_u32 s66, s22, s50
	s_addc_u32 s67, s3, s51
	s_and_b32 s51, s23, 3
	s_lshl_b32 s1, s0, 6
	s_lshl_b32 s3, s0, 13
	s_lshl_b32 s68, s51, 5
	s_lshl_b32 s5, s51, 12
	s_add_u32 s0, s10, 0x8000
	v_mov_b32_e32 v171, v221
	v_writelane_b32 v255, s1, 18
	s_addc_u32 s1, s11, 0
	s_add_i32 m0, s33, 0x18000
	v_lshl_add_u64 v[8:9], s[0:1], 0, v[170:171]
	v_mov_b32_e32 v175, v221
	s_waitcnt vmcnt(2)
	global_load_lds_dwordx4 v[8:9], off
	s_add_i32 m0, s33, 0x1a000
	v_lshl_add_u64 v[8:9], s[0:1], 0, v[174:175]
	s_add_u32 s0, s6, 0x8000
	v_mov_b32_e32 v169, v221
	s_addc_u32 s1, s7, 0
	s_add_i32 s53, s33, 0x8000
	v_mov_b32_e32 v173, v221
	global_load_lds_dwordx4 v[8:9], off
	s_mov_b32 m0, s53
	s_add_i32 s27, s33, 0xa000
	global_load_lds_dwordx4 v168, s[0:1]
	v_lshl_add_u64 v[8:9], s[0:1], 0, v[172:173]
	s_add_u32 s0, s10, 0xc000
	s_mov_b32 m0, s27
	s_addc_u32 s1, s11, 0
	global_load_lds_dwordx4 v[8:9], off
	s_add_i32 m0, s33, 0x1c000
	s_nop 0
	global_load_lds_dwordx4 v170, s[0:1]
	s_add_i32 m0, s33, 0x1e000
	v_and_b32_e32 v7, 48, v0
	global_load_lds_dwordx4 v174, s[0:1]
	v_lshlrev_b32_e32 v8, 6, v0
	s_movk_i32 s0, 0x3c0
	v_lshlrev_b32_e32 v0, 2, v0
	s_cmpk_lt_u32 s2, 0x100
	v_and_or_b32 v7, v8, s0, v7
	v_and_b32_e32 v0, 32, v0
	s_cselect_b64 s[70:71], -1, 0
	s_lshl_b32 s0, s23, 11
	v_bitop3_b32 v8, v7, s3, v0 bitop3:0xde
	v_bitop3_b32 v192, v7, s5, v0 bitop3:0xde
	s_and_b32 s0, s0, 0x1000
	v_lshlrev_b32_e32 v0, 10, v1
	s_or_b32 s0, s0, 0xfffdc000
	v_and_b32_e32 v0, 0xfffff800, v0
	s_cmp_eq_u32 s51, 0
	v_lshl_add_u32 v0, v2, 7, v0
	v_and_b32_e32 v1, 1, v1
	s_cselect_b64 s[72:73], -1, 0
	s_lshl_b32 s2, s23, 6
	v_lshl_or_b32 v0, v1, 6, v0
	s_ashr_i32 s39, s60, 31
	s_ashr_i32 s50, s58, 31
	s_and_b32 s2, s2, 64
	v_lshl_add_u32 v176, v3, 1, v0
	v_lshlrev_b32_e32 v0, 10, v4
	s_add_u32 s2, s62, s2
	v_and_b32_e32 v0, 0xfffff800, v0
	s_waitcnt vmcnt(6)
	s_addc_u32 s3, s63, 0
	v_lshl_add_u32 v0, v5, 7, v0
	v_and_b32_e32 v1, 1, v4
	s_add_u32 s74, s2, 0x19400000
	v_lshl_or_b32 v0, v1, 6, v0
	s_mov_b32 s69, s31
	s_mov_b32 s1, 0
	s_addc_u32 s75, s3, 0
	v_mov_b32_e32 v177, v221
	v_lshl_add_u32 v178, v6, 1, v0
	v_mov_b32_e32 v179, v221
	v_add_u32_e32 v193, 0, v8
	s_barrier
	s_branch .LBB0_1127

; #define PG8_STAGE(bufoff, gbase, voff) do { _Pragma("unroll") for (int _i = 0; _i < 2; ++_i) \
;         __builtin_amdgcn_global_load_lds((const unsigned*)((const char*)(gbase) + (voff)[_i]), (PG8_LAS unsigned*)(lds + (bufoff) + ldsw + _i * 8192), 16, 0, 0); } while (0)
; #define PG8_LDA(dst, b, h) do { _Pragma("unroll") for (int m = 0; m < 4; ++m) _Pragma("unroll") for (int k = 0; k < 2; ++k) dst[m][k] = *(const PG8_LAS bf16x8*)(lds + PG8_SA(b, h) + aoff + m * 2048 + k * 1024); } while (0)
; #define PG8_LDB(dst, b, h) do { _Pragma("unroll") for (int n = 0; n < 2; ++n) _Pragma("unroll") for (int k = 0; k < 2; ++k) dst[n][k] = *(const PG8_LAS bf16x8*)(lds + PG8_SB(b, h) + boff + n * 2048 + k * 1024); } while (0)
; #define PG8_MMA(ai, bj, At, Bt) do { __builtin_amdgcn_s_setprio(1); _Pragma("unroll") for (int m = 0; m < 4; ++m) _Pragma("unroll") for (int n = 0; n < 2; ++n) _Pragma("unroll") for (int k = 0; k < 2; ++k) \
;         acc[ai][bj][m][n] = __builtin_amdgcn_mfma_f32_16x16x32_bf16(Bt[n][k], At[m][k], acc[ai][bj][m][n], 0, 0, 0); __builtin_amdgcn_s_setprio(0); } while (0)
; #define PG8_WAIT_V(n) asm volatile("s_waitcnt vmcnt(" #n ")" ::: "memory")
; #define PG8_BAR __builtin_amdgcn_s_barrier()
; template <class Epi, class Sched, bool ALIGN_EPI = false, bool SP2 = false>
; __device__ __forceinline__ void gemm_phase(PG8_LAS unsigned char* lds, const Gemm g, const Sched& S, const Epi& E) {
;     ...
;         for (int t = 0; t < nt; t += 2) {
;             const bool last = (t == nt - 2);
;             const char* a1 = cA + (size_t)(t + 1) * kstep;
;             const char* a2 = last ? nA : cA + (size_t)(t + 2) * kstep; const char* b2 = last ? nB : cB + (size_t)(t + 2) * kstep;
;             const char* a3 = a2 + kstep; const char* b3 = b2 + kstep;
;             if (last && has_next) S.a_ready(nxt);
;             if constexpr (SP2) {
;             PG8_LDB(B0, 0, 0); PG8_LDB(B1, 0, 1); PG8_SCHED; PG8_LDA(At, 0, 0); PG8_STAGE(PG8_SA(1, 1), a1 + hstep, voffA);
;             PG8_WAIT_V(8); PG8_WAIT_L(0); PG8_BAR; PG8_MMA(0, 0, At, B0); PG8_MMA(0, 1, At, B1); PG8_BAR; PG8_SCHED;
;             PG8_LDA(At, 0, 1); PG8_STAGE(PG8_SB(0, 0), b2, voffB); PG8_STAGE(PG8_SB(0, 1), b2 + hstep, voffB); PG8_STAGE(PG8_SA(0, 0), a2, voffA);
;             PG8_WAIT_V(8); PG8_WAIT_L(0); PG8_BAR; PG8_MMA(1, 0, At, B0); PG8_MMA(1, 1, At, B1); PG8_BAR; PG8_SCHED;
.LBB0_1130:
	s_and_b64 vcc, exec, s[70:71]
	s_cbranch_vccz .Lk2_trail
.Lk2_lead:
	s_add_u32 s10, s6, 0x4000
	s_addc_u32 s11, s7, 0
	s_cmp_eq_u32 s40, 12
	s_cselect_b32 s86, s9, s10
	s_cselect_b32 s87, s5, s11
	s_cselect_b32 s84, s23, s30
	s_cselect_b32 s85, s22, s37
	s_add_u32 s10, s86, 0x8000
	s_addc_u32 s11, s87, 0
	s_add_i32 s77, 0, 0x10000
	s_add_i32 s79, 0, 0x14000
	v_add_u32_e32 v32, s77, v192
	v_add_u32_e32 v60, s79, v192
	ds_read_b128 v[16:19], v32
	ds_read_b128 v[20:23], v32 offset:1024
	ds_read_b128 v[24:27], v32 offset:2048
	ds_read_b128 v[32:35], v32 offset:3072
	ds_read_b128 v[48:51], v60
	ds_read_b128 v[52:55], v60 offset:1024
	ds_read_b128 v[56:59], v60 offset:2048
	ds_read_b128 v[60:63], v60 offset:3072
	s_add_i32 m0, s33, 0xc000
	ds_read_b128 v[160:163], v193
	ds_read_b128 v[164:167], v193 offset:1024
	ds_read_b128 v[180:183], v193 offset:2048
	ds_read_b128 v[184:187], v193 offset:3072
	ds_read_b128 v[188:191], v193 offset:4096
	ds_read_b128 v[194:197], v193 offset:5120
	ds_read_b128 v[198:201], v193 offset:6144
	ds_read_b128 v[202:205], v193 offset:7168
	global_load_lds_dwordx4 v176, s[6:7]
	s_add_i32 m0, s33, 0xe000
	s_nop 0
	global_load_lds_dwordx4 v178, s[6:7]
	s_waitcnt vmcnt(8)
	s_waitcnt lgkmcnt(0)
	s_barrier
	s_waitcnt lgkmcnt(0)
	v_mfma_f32_16x16x32_bf16 v[156:159], v[16:19], v[160:163], v[156:159]
	v_mfma_f32_16x16x32_bf16 v[152:155], v[24:27], v[160:163], v[152:155]
	v_mfma_f32_16x16x32_bf16 v[140:143], v[16:19], v[180:183], v[140:143]
	v_mfma_f32_16x16x32_bf16 v[136:139], v[24:27], v[180:183], v[136:139]
	v_mfma_f32_16x16x32_bf16 v[124:127], v[16:19], v[188:191], v[124:127]
	v_mfma_f32_16x16x32_bf16 v[120:123], v[24:27], v[188:191], v[120:123]
	v_mfma_f32_16x16x32_bf16 v[108:111], v[16:19], v[198:201], v[108:111]
	v_mfma_f32_16x16x32_bf16 v[104:107], v[24:27], v[198:201], v[104:107]
	v_mfma_f32_16x16x32_bf16 v[156:159], v[20:23], v[164:167], v[156:159]
	v_mfma_f32_16x16x32_bf16 v[152:155], v[32:35], v[164:167], v[152:155]
	v_mfma_f32_16x16x32_bf16 v[140:143], v[20:23], v[184:187], v[140:143]
	v_mfma_f32_16x16x32_bf16 v[136:139], v[32:35], v[184:187], v[136:139]
	v_mfma_f32_16x16x32_bf16 v[124:127], v[20:23], v[194:197], v[124:127]
	v_mfma_f32_16x16x32_bf16 v[120:123], v[32:35], v[194:197], v[120:123]
	v_mfma_f32_16x16x32_bf16 v[108:111], v[20:23], v[202:205], v[108:111]
	v_mfma_f32_16x16x32_bf16 v[104:107], v[32:35], v[202:205], v[104:107]
	v_mfma_f32_16x16x32_bf16 v[148:151], v[48:51], v[160:163], v[148:151]
	v_mfma_f32_16x16x32_bf16 v[144:147], v[56:59], v[160:163], v[144:147]
	v_mfma_f32_16x16x32_bf16 v[132:135], v[48:51], v[180:183], v[132:135]
	v_mfma_f32_16x16x32_bf16 v[128:131], v[56:59], v[180:183], v[128:131]
	v_mfma_f32_16x16x32_bf16 v[116:119], v[48:51], v[188:191], v[116:119]
	v_mfma_f32_16x16x32_bf16 v[112:115], v[56:59], v[188:191], v[112:115]
	v_mfma_f32_16x16x32_bf16 v[100:103], v[48:51], v[198:201], v[100:103]
	v_mfma_f32_16x16x32_bf16 v[96:99], v[56:59], v[198:201], v[96:99]
	v_mfma_f32_16x16x32_bf16 v[148:151], v[52:55], v[164:167], v[148:151]
	v_mfma_f32_16x16x32_bf16 v[144:147], v[60:63], v[164:167], v[144:147]
	v_mfma_f32_16x16x32_bf16 v[132:135], v[52:55], v[184:187], v[132:135]
	v_mfma_f32_16x16x32_bf16 v[128:131], v[60:63], v[184:187], v[128:131]
	v_mfma_f32_16x16x32_bf16 v[116:119], v[52:55], v[194:197], v[116:119]
	v_mfma_f32_16x16x32_bf16 v[112:115], v[60:63], v[194:197], v[112:115]
	v_mfma_f32_16x16x32_bf16 v[100:103], v[52:55], v[202:205], v[100:103]
	v_mfma_f32_16x16x32_bf16 v[96:99], v[60:63], v[202:205], v[96:99]
	s_add_i32 s77, s77, s57
	s_mov_b32 m0, s77
	ds_read_b128 v[160:163], v193 offset:16384
	ds_read_b128 v[164:167], v193 offset:17408
	ds_read_b128 v[180:183], v193 offset:18432
	ds_read_b128 v[184:187], v193 offset:19456
	ds_read_b128 v[188:191], v193 offset:20480
	ds_read_b128 v[194:197], v193 offset:21504
	ds_read_b128 v[198:201], v193 offset:22528
	ds_read_b128 v[202:205], v193 offset:23552
	global_load_lds_dwordx4 v170, s[84:85]
	s_add_i32 m0, s77, 0x2000
	s_add_u32 s88, s84, 0x4000
	s_addc_u32 s89, s85, 0
	s_add_i32 s77, s79, s57
	global_load_lds_dwordx4 v174, s[84:85]
	s_mov_b32 m0, s77
	s_nop 0
	global_load_lds_dwordx4 v170, s[88:89]
	s_add_i32 m0, s77, 0x2000
	s_nop 0
	global_load_lds_dwordx4 v174, s[88:89]
	s_mov_b32 m0, s33
	s_nop 0
	global_load_lds_dwordx4 v168, s[86:87]
	s_mov_b32 m0, s42
	s_nop 0
	global_load_lds_dwordx4 v172, s[86:87]
	s_waitcnt vmcnt(8)
	s_waitcnt lgkmcnt(0)
	s_barrier
; #define PG8_STAGE(bufoff, gbase, voff) do { _Pragma("unroll") for (int _i = 0; _i < 2; ++_i) \
;         __builtin_amdgcn_global_load_lds((const unsigned*)((const char*)(gbase) + (voff)[_i]), (PG8_LAS unsigned*)(lds + (bufoff) + ldsw + _i * 8192), 16, 0, 0); } while (0)
; #define PG8_LDA(dst, b, h) do { _Pragma("unroll") for (int m = 0; m < 4; ++m) _Pragma("unroll") for (int k = 0; k < 2; ++k) dst[m][k] = *(const PG8_LAS bf16x8*)(lds + PG8_SA(b, h) + aoff + m * 2048 + k * 1024); } while (0)
; #define PG8_LDB(dst, b, h) do { _Pragma("unroll") for (int n = 0; n < 2; ++n) _Pragma("unroll") for (int k = 0; k < 2; ++k) dst[n][k] = *(const PG8_LAS bf16x8*)(lds + PG8_SB(b, h) + boff + n * 2048 + k * 1024); } while (0)
; #define PG8_MMA(ai, bj, At, Bt) do { __builtin_amdgcn_s_setprio(1); _Pragma("unroll") for (int m = 0; m < 4; ++m) _Pragma("unroll") for (int n = 0; n < 2; ++n) _Pragma("unroll") for (int k = 0; k < 2; ++k) \
;         acc[ai][bj][m][n] = __builtin_amdgcn_mfma_f32_16x16x32_bf16(Bt[n][k], At[m][k], acc[ai][bj][m][n], 0, 0, 0); __builtin_amdgcn_s_setprio(0); } while (0)
; #define PG8_WAIT_V(n) asm volatile("s_waitcnt vmcnt(" #n ")" ::: "memory")
; #define PG8_WAIT_L(n) asm volatile("s_waitcnt lgkmcnt(" #n ")" ::: "memory")
; #define PG8_BAR __builtin_amdgcn_s_barrier()
; #define PG8_SCHED __builtin_amdgcn_sched_barrier(0)
; template <class Epi, class Sched, bool ALIGN_EPI = false, bool SP2 = false>
; __device__ __forceinline__ void gemm_phase(PG8_LAS unsigned char* lds, const Gemm g, const Sched& S, const Epi& E) {
;     ...
;             PG8_WAIT_V(8); PG8_WAIT_L(0); PG8_BAR; PG8_MMA(1, 0, At, B0); PG8_MMA(1, 1, At, B1); PG8_BAR; PG8_SCHED;
;             PG8_LDB(B0, 1, 0); PG8_LDB(B1, 1, 1); PG8_SCHED; PG8_LDA(At, 1, 0); PG8_STAGE(PG8_SA(0, 1), a2 + hstep, voffA);
;             PG8_WAIT_V(8); PG8_WAIT_L(0); PG8_BAR; PG8_MMA(0, 0, At, B0); PG8_MMA(0, 1, At, B1); PG8_BAR; PG8_SCHED;
;             PG8_LDA(At, 1, 1); PG8_STAGE(PG8_SB(1, 0), b3, voffB); PG8_STAGE(PG8_SB(1, 1), b3 + hstep, voffB); PG8_STAGE(PG8_SA(1, 0), a3, voffA);
;             PG8_WAIT_V(8); PG8_WAIT_L(0); PG8_BAR; PG8_MMA(1, 0, At, B0); PG8_MMA(1, 1, At, B1); PG8_BAR; PG8_SCHED;
	s_waitcnt lgkmcnt(0)
	v_mfma_f32_16x16x32_bf16 v[92:95], v[16:19], v[160:163], v[92:95]
	v_mfma_f32_16x16x32_bf16 v[88:91], v[24:27], v[160:163], v[88:91]
	v_mfma_f32_16x16x32_bf16 v[76:79], v[16:19], v[180:183], v[76:79]
	v_mfma_f32_16x16x32_bf16 v[72:75], v[24:27], v[180:183], v[72:75]
	v_mfma_f32_16x16x32_bf16 v[44:47], v[16:19], v[188:191], v[44:47]
	v_mfma_f32_16x16x32_bf16 v[40:43], v[24:27], v[188:191], v[40:43]
	v_mfma_f32_16x16x32_bf16 v[12:15], v[16:19], v[198:201], v[12:15]
	v_mfma_f32_16x16x32_bf16 v[8:11], v[24:27], v[198:201], v[8:11]
	v_mfma_f32_16x16x32_bf16 v[92:95], v[20:23], v[164:167], v[92:95]
	v_mfma_f32_16x16x32_bf16 v[88:91], v[32:35], v[164:167], v[88:91]
	v_mfma_f32_16x16x32_bf16 v[76:79], v[20:23], v[184:187], v[76:79]
	v_mfma_f32_16x16x32_bf16 v[72:75], v[32:35], v[184:187], v[72:75]
	v_mfma_f32_16x16x32_bf16 v[44:47], v[20:23], v[194:197], v[44:47]
	v_mfma_f32_16x16x32_bf16 v[40:43], v[32:35], v[194:197], v[40:43]
	v_mfma_f32_16x16x32_bf16 v[12:15], v[20:23], v[202:205], v[12:15]
	v_mfma_f32_16x16x32_bf16 v[8:11], v[32:35], v[202:205], v[8:11]
	v_mfma_f32_16x16x32_bf16 v[36:39], v[48:51], v[188:191], v[36:39]
	v_mfma_f32_16x16x32_bf16 v[28:31], v[56:59], v[188:191], v[28:31]
	v_mfma_f32_16x16x32_bf16 v[4:7], v[48:51], v[198:201], v[4:7]
	v_mfma_f32_16x16x32_bf16 v[0:3], v[56:59], v[198:201], v[0:3]
	v_mfma_f32_16x16x32_bf16 v[16:19], v[48:51], v[160:163], v[84:87]
	v_mfma_f32_16x16x32_bf16 v[20:23], v[56:59], v[160:163], v[80:83]
	v_mfma_f32_16x16x32_bf16 v[24:27], v[48:51], v[180:183], v[68:71]
	v_mfma_f32_16x16x32_bf16 v[32:35], v[56:59], v[180:183], v[64:67]
	v_mfma_f32_16x16x32_bf16 v[36:39], v[52:55], v[194:197], v[36:39]
	v_mfma_f32_16x16x32_bf16 v[28:31], v[60:63], v[194:197], v[28:31]
	v_mfma_f32_16x16x32_bf16 v[4:7], v[52:55], v[202:205], v[4:7]
	v_mfma_f32_16x16x32_bf16 v[0:3], v[60:63], v[202:205], v[0:3]
	v_mfma_f32_16x16x32_bf16 v[16:19], v[52:55], v[164:167], v[16:19]
	v_mfma_f32_16x16x32_bf16 v[20:23], v[60:63], v[164:167], v[20:23]
	v_mfma_f32_16x16x32_bf16 v[24:27], v[52:55], v[184:187], v[24:27]
	v_mfma_f32_16x16x32_bf16 v[32:35], v[60:63], v[184:187], v[32:35]
	s_add_i32 s77, 0, 0x18000
	s_add_i32 s79, 0, 0x1c000
	v_add_u32_e32 v60, s77, v192
	v_add_u32_e32 v64, s79, v192
	ds_read_b128 v[48:51], v60
	ds_read_b128 v[52:55], v60 offset:1024
	ds_read_b128 v[56:59], v60 offset:2048
	ds_read_b128 v[60:63], v60 offset:3072
	ds_read_b128 v[160:163], v64
	ds_read_b128 v[164:167], v64 offset:1024
	ds_read_b128 v[180:183], v64 offset:2048
	ds_read_b128 v[184:187], v64 offset:3072
	s_add_u32 s86, s86, 0x4000
	s_addc_u32 s87, s87, 0
	s_mov_b32 m0, s64
	ds_read_b128 v[64:67], v193 offset:32768
	ds_read_b128 v[68:71], v193 offset:33792
	ds_read_b128 v[80:83], v193 offset:34816
	ds_read_b128 v[84:87], v193 offset:35840
	ds_read_b128 v[188:191], v193 offset:36864
	ds_read_b128 v[194:197], v193 offset:37888
	ds_read_b128 v[198:201], v193 offset:38912
	ds_read_b128 v[202:205], v193 offset:39936
	global_load_lds_dwordx4 v168, s[86:87]
	s_mov_b32 m0, s65
	s_nop 0
	global_load_lds_dwordx4 v172, s[86:87]
	s_waitcnt vmcnt(8)
	s_waitcnt lgkmcnt(0)
	s_barrier
	s_waitcnt lgkmcnt(0)
	v_mfma_f32_16x16x32_bf16 v[156:159], v[48:51], v[64:67], v[156:159]
	v_mfma_f32_16x16x32_bf16 v[152:155], v[56:59], v[64:67], v[152:155]
	v_mfma_f32_16x16x32_bf16 v[140:143], v[48:51], v[80:83], v[140:143]
	v_mfma_f32_16x16x32_bf16 v[136:139], v[56:59], v[80:83], v[136:139]
	v_mfma_f32_16x16x32_bf16 v[124:127], v[48:51], v[188:191], v[124:127]
	v_mfma_f32_16x16x32_bf16 v[120:123], v[56:59], v[188:191], v[120:123]
	v_mfma_f32_16x16x32_bf16 v[108:111], v[48:51], v[198:201], v[108:111]
	v_mfma_f32_16x16x32_bf16 v[104:107], v[56:59], v[198:201], v[104:107]
	v_mfma_f32_16x16x32_bf16 v[156:159], v[52:55], v[68:71], v[156:159]
	v_mfma_f32_16x16x32_bf16 v[152:155], v[60:63], v[68:71], v[152:155]
	v_mfma_f32_16x16x32_bf16 v[140:143], v[52:55], v[84:87], v[140:143]
	v_mfma_f32_16x16x32_bf16 v[136:139], v[60:63], v[84:87], v[136:139]
	v_mfma_f32_16x16x32_bf16 v[124:127], v[52:55], v[194:197], v[124:127]
	v_mfma_f32_16x16x32_bf16 v[120:123], v[60:63], v[194:197], v[120:123]
	v_mfma_f32_16x16x32_bf16 v[108:111], v[52:55], v[202:205], v[108:111]
	v_mfma_f32_16x16x32_bf16 v[104:107], v[60:63], v[202:205], v[104:107]
	v_mfma_f32_16x16x32_bf16 v[148:151], v[160:163], v[64:67], v[148:151]
	v_mfma_f32_16x16x32_bf16 v[64:67], v[180:183], v[64:67], v[144:147]
	v_mfma_f32_16x16x32_bf16 v[144:147], v[184:187], v[68:71], v[64:67]
	v_mfma_f32_16x16x32_bf16 v[64:67], v[160:163], v[80:83], v[132:135]
	v_mfma_f32_16x16x32_bf16 v[132:135], v[164:167], v[84:87], v[64:67]
	v_mfma_f32_16x16x32_bf16 v[64:67], v[180:183], v[80:83], v[128:131]
	v_mfma_f32_16x16x32_bf16 v[128:131], v[184:187], v[84:87], v[64:67]
	v_mfma_f32_16x16x32_bf16 v[64:67], v[160:163], v[188:191], v[116:119]
	v_mfma_f32_16x16x32_bf16 v[116:119], v[164:167], v[194:197], v[64:67]
	v_mfma_f32_16x16x32_bf16 v[64:67], v[180:183], v[188:191], v[112:115]
	v_mfma_f32_16x16x32_bf16 v[112:115], v[184:187], v[194:197], v[64:67]
	v_mfma_f32_16x16x32_bf16 v[64:67], v[160:163], v[198:201], v[100:103]
	v_mfma_f32_16x16x32_bf16 v[100:103], v[164:167], v[202:205], v[64:67]
	v_mfma_f32_16x16x32_bf16 v[64:67], v[180:183], v[198:201], v[96:99]
	v_mfma_f32_16x16x32_bf16 v[148:151], v[164:167], v[68:71], v[148:151]
	v_mfma_f32_16x16x32_bf16 v[96:99], v[184:187], v[202:205], v[64:67]
	s_add_u32 s86, s84, 0x8000
	s_addc_u32 s87, s85, 0
	s_add_i32 s77, s77, s57
	s_mov_b32 m0, s77
	ds_read_b128 v[64:67], v193 offset:49152
	ds_read_b128 v[68:71], v193 offset:50176
	ds_read_b128 v[188:191], v193 offset:51200
	ds_read_b128 v[194:197], v193 offset:52224
	ds_read_b128 v[198:201], v193 offset:53248
	ds_read_b128 v[202:205], v193 offset:54272
	ds_read_b128 v[206:209], v193 offset:55296
	ds_read_b128 v[210:213], v193 offset:56320
	global_load_lds_dwordx4 v170, s[86:87]
	s_add_i32 m0, s77, 0x2000
	s_add_u32 s84, s84, 0xc000
	s_addc_u32 s85, s85, 0
	s_add_i32 s77, s79, s57
	global_load_lds_dwordx4 v174, s[86:87]
	s_mov_b32 m0, s77
	s_nop 0
	global_load_lds_dwordx4 v170, s[84:85]
	s_add_i32 m0, s77, 0x2000
	s_nop 0
	global_load_lds_dwordx4 v174, s[84:85]
	s_mov_b32 m0, s53
	s_nop 0
	global_load_lds_dwordx4 v168, s[10:11]
	s_mov_b32 m0, s27
	s_nop 0
	global_load_lds_dwordx4 v172, s[10:11]
	s_waitcnt vmcnt(8)
	s_waitcnt lgkmcnt(0)
	s_barrier
; #define PG8_STAGE(bufoff, gbase, voff) do { _Pragma("unroll") for (int _i = 0; _i < 2; ++_i) \
;         __builtin_amdgcn_global_load_lds((const unsigned*)((const char*)(gbase) + (voff)[_i]), (PG8_LAS unsigned*)(lds + (bufoff) + ldsw + _i * 8192), 16, 0, 0); } while (0)
; #define PG8_LDA(dst, b, h) do { _Pragma("unroll") for (int m = 0; m < 4; ++m) _Pragma("unroll") for (int k = 0; k < 2; ++k) dst[m][k] = *(const PG8_LAS bf16x8*)(lds + PG8_SA(b, h) + aoff + m * 2048 + k * 1024); } while (0)
; #define PG8_LDB(dst, b, h) do { _Pragma("unroll") for (int n = 0; n < 2; ++n) _Pragma("unroll") for (int k = 0; k < 2; ++k) dst[n][k] = *(const PG8_LAS bf16x8*)(lds + PG8_SB(b, h) + boff + n * 2048 + k * 1024); } while (0)
; template <class Epi, class Sched, bool ALIGN_EPI = false, bool SP2 = false>
; __device__ __forceinline__ void gemm_phase(PG8_LAS unsigned char* lds, const Gemm g, const Sched& S, const Epi& E) {
;     ...
;         for (int t = 0; t < nt; t += 2) {
;             const bool last = (t == nt - 2);
;             const char* a1 = cA + (size_t)(t + 1) * kstep;
;             const char* a2 = last ? nA : cA + (size_t)(t + 2) * kstep; const char* b2 = last ? nB : cB + (size_t)(t + 2) * kstep;
;             const char* a3 = a2 + kstep; const char* b3 = b2 + kstep;
;             if (last && has_next) S.a_ready(nxt);
;             if constexpr (SP2) {
;             PG8_LDB(B0, 0, 0); PG8_LDB(B1, 0, 1); PG8_SCHED; PG8_LDA(At, 0, 0); PG8_STAGE(PG8_SA(1, 1), a1 + hstep, voffA);
;             PG8_WAIT_V(8); PG8_WAIT_L(0); PG8_BAR; PG8_MMA(0, 0, At, B0); PG8_MMA(0, 1, At, B1); PG8_BAR; PG8_SCHED;
;             PG8_LDA(At, 0, 1); PG8_STAGE(PG8_SB(0, 0), b2, voffB); PG8_STAGE(PG8_SB(0, 1), b2 + hstep, voffB); PG8_STAGE(PG8_SA(0, 0), a2, voffA);
;             PG8_WAIT_V(8); PG8_WAIT_L(0); PG8_BAR; PG8_MMA(1, 0, At, B0); PG8_MMA(1, 1, At, B1); PG8_BAR; PG8_SCHED;
;             PG8_LDB(B0, 1, 0); PG8_LDB(B1, 1, 1); PG8_SCHED; PG8_LDA(At, 1, 0); PG8_STAGE(PG8_SA(0, 1), a2 + hstep, voffA);
;             PG8_WAIT_V(8); PG8_WAIT_L(0); PG8_BAR; PG8_MMA(0, 0, At, B0); PG8_MMA(0, 1, At, B1); PG8_BAR; PG8_SCHED;
;             PG8_LDA(At, 1, 1); PG8_STAGE(PG8_SB(1, 0), b3, voffB); PG8_STAGE(PG8_SB(1, 1), b3 + hstep, voffB); PG8_STAGE(PG8_SA(1, 0), a3, voffA);
;             PG8_WAIT_V(8); PG8_WAIT_L(0); PG8_BAR; PG8_MMA(1, 0, At, B0); PG8_MMA(1, 1, At, B1); PG8_BAR; PG8_SCHED;
	s_waitcnt lgkmcnt(0)
	v_mfma_f32_16x16x32_bf16 v[80:83], v[48:51], v[64:67], v[92:95]
	v_mfma_f32_16x16x32_bf16 v[92:95], v[52:55], v[68:71], v[80:83]
	v_mfma_f32_16x16x32_bf16 v[80:83], v[56:59], v[64:67], v[88:91]
	v_mfma_f32_16x16x32_bf16 v[76:79], v[48:51], v[188:191], v[76:79]
	v_mfma_f32_16x16x32_bf16 v[72:75], v[56:59], v[188:191], v[72:75]
	v_mfma_f32_16x16x32_bf16 v[44:47], v[48:51], v[198:201], v[44:47]
	v_mfma_f32_16x16x32_bf16 v[40:43], v[56:59], v[198:201], v[40:43]
	v_mfma_f32_16x16x32_bf16 v[12:15], v[48:51], v[206:209], v[12:15]
	v_mfma_f32_16x16x32_bf16 v[8:11], v[56:59], v[206:209], v[8:11]
	v_mfma_f32_16x16x32_bf16 v[88:91], v[60:63], v[68:71], v[80:83]
	v_mfma_f32_16x16x32_bf16 v[76:79], v[52:55], v[194:197], v[76:79]
	v_mfma_f32_16x16x32_bf16 v[72:75], v[60:63], v[194:197], v[72:75]
	v_mfma_f32_16x16x32_bf16 v[44:47], v[52:55], v[202:205], v[44:47]
	v_mfma_f32_16x16x32_bf16 v[40:43], v[60:63], v[202:205], v[40:43]
	v_mfma_f32_16x16x32_bf16 v[12:15], v[52:55], v[210:213], v[12:15]
	v_mfma_f32_16x16x32_bf16 v[8:11], v[60:63], v[210:213], v[8:11]
	v_mfma_f32_16x16x32_bf16 v[16:19], v[160:163], v[64:67], v[16:19]
	v_mfma_f32_16x16x32_bf16 v[84:87], v[164:167], v[68:71], v[16:19]
	v_mfma_f32_16x16x32_bf16 v[16:19], v[180:183], v[64:67], v[20:23]
	v_mfma_f32_16x16x32_bf16 v[80:83], v[184:187], v[68:71], v[16:19]
	v_mfma_f32_16x16x32_bf16 v[16:19], v[160:163], v[188:191], v[24:27]
	v_mfma_f32_16x16x32_bf16 v[68:71], v[164:167], v[194:197], v[16:19]
	v_mfma_f32_16x16x32_bf16 v[16:19], v[180:183], v[188:191], v[32:35]
	v_mfma_f32_16x16x32_bf16 v[64:67], v[184:187], v[194:197], v[16:19]
	v_mfma_f32_16x16x32_bf16 v[16:19], v[160:163], v[198:201], v[36:39]
	v_mfma_f32_16x16x32_bf16 v[36:39], v[164:167], v[202:205], v[16:19]
	v_mfma_f32_16x16x32_bf16 v[16:19], v[180:183], v[198:201], v[28:31]
	v_mfma_f32_16x16x32_bf16 v[4:7], v[160:163], v[206:209], v[4:7]
	v_mfma_f32_16x16x32_bf16 v[0:3], v[180:183], v[206:209], v[0:3]
	v_mfma_f32_16x16x32_bf16 v[28:31], v[184:187], v[202:205], v[16:19]
	v_mfma_f32_16x16x32_bf16 v[4:7], v[164:167], v[210:213], v[4:7]
	v_mfma_f32_16x16x32_bf16 v[0:3], v[184:187], v[210:213], v[0:3]
	s_add_i32 s40, s40, 2
	s_add_u32 s6, s6, 0x10000
	s_addc_u32 s7, s7, 0
	s_add_u32 s30, s30, 0x10000
	s_addc_u32 s37, s37, 0
	s_cmp_gt_u32 s40, 13
	s_cbranch_scc0 .Lk2_lead
	s_branch .Lk2_done
.Lk2_trail:
	s_add_u32 s10, s6, 0x4000
	s_addc_u32 s11, s7, 0
	s_cmp_eq_u32 s40, 12
	s_cselect_b32 s86, s9, s10
	s_cselect_b32 s87, s5, s11
	s_cselect_b32 s84, s23, s30
	s_cselect_b32 s85, s22, s37
	s_add_u32 s10, s86, 0x8000
	s_addc_u32 s11, s87, 0
	s_add_i32 s77, 0, 0x10000
	s_add_i32 s79, 0, 0x14000
	v_add_u32_e32 v32, s77, v192
	v_add_u32_e32 v60, s79, v192
	ds_read_b128 v[16:19], v32
	ds_read_b128 v[20:23], v32 offset:1024
	ds_read_b128 v[24:27], v32 offset:2048
	ds_read_b128 v[32:35], v32 offset:3072
	ds_read_b128 v[48:51], v60
	ds_read_b128 v[52:55], v60 offset:1024
	ds_read_b128 v[56:59], v60 offset:2048
	ds_read_b128 v[60:63], v60 offset:3072
	s_add_i32 m0, s33, 0xc000
	ds_read_b128 v[160:163], v193
	ds_read_b128 v[164:167], v193 offset:1024
	ds_read_b128 v[180:183], v193 offset:2048
	ds_read_b128 v[184:187], v193 offset:3072
	ds_read_b128 v[188:191], v193 offset:4096
	ds_read_b128 v[194:197], v193 offset:5120
	ds_read_b128 v[198:201], v193 offset:6144
	ds_read_b128 v[202:205], v193 offset:7168
	global_load_lds_dwordx4 v176, s[6:7]
	s_add_i32 m0, s33, 0xe000
	s_nop 0
	global_load_lds_dwordx4 v178, s[6:7]
	s_waitcnt vmcnt(8)
	s_waitcnt lgkmcnt(0)
	s_waitcnt lgkmcnt(0)
	v_mfma_f32_16x16x32_bf16 v[156:159], v[16:19], v[160:163], v[156:159]
	v_mfma_f32_16x16x32_bf16 v[152:155], v[24:27], v[160:163], v[152:155]
	v_mfma_f32_16x16x32_bf16 v[140:143], v[16:19], v[180:183], v[140:143]
	v_mfma_f32_16x16x32_bf16 v[136:139], v[24:27], v[180:183], v[136:139]
	v_mfma_f32_16x16x32_bf16 v[124:127], v[16:19], v[188:191], v[124:127]
	v_mfma_f32_16x16x32_bf16 v[120:123], v[24:27], v[188:191], v[120:123]
	v_mfma_f32_16x16x32_bf16 v[108:111], v[16:19], v[198:201], v[108:111]
	v_mfma_f32_16x16x32_bf16 v[104:107], v[24:27], v[198:201], v[104:107]
	v_mfma_f32_16x16x32_bf16 v[156:159], v[20:23], v[164:167], v[156:159]
	v_mfma_f32_16x16x32_bf16 v[152:155], v[32:35], v[164:167], v[152:155]
	v_mfma_f32_16x16x32_bf16 v[140:143], v[20:23], v[184:187], v[140:143]
	v_mfma_f32_16x16x32_bf16 v[136:139], v[32:35], v[184:187], v[136:139]
	v_mfma_f32_16x16x32_bf16 v[124:127], v[20:23], v[194:197], v[124:127]
	v_mfma_f32_16x16x32_bf16 v[120:123], v[32:35], v[194:197], v[120:123]
	v_mfma_f32_16x16x32_bf16 v[108:111], v[20:23], v[202:205], v[108:111]
	v_mfma_f32_16x16x32_bf16 v[104:107], v[32:35], v[202:205], v[104:107]
	v_mfma_f32_16x16x32_bf16 v[148:151], v[48:51], v[160:163], v[148:151]
	v_mfma_f32_16x16x32_bf16 v[144:147], v[56:59], v[160:163], v[144:147]
	v_mfma_f32_16x16x32_bf16 v[132:135], v[48:51], v[180:183], v[132:135]
	v_mfma_f32_16x16x32_bf16 v[128:131], v[56:59], v[180:183], v[128:131]
	v_mfma_f32_16x16x32_bf16 v[116:119], v[48:51], v[188:191], v[116:119]
	v_mfma_f32_16x16x32_bf16 v[112:115], v[56:59], v[188:191], v[112:115]
	v_mfma_f32_16x16x32_bf16 v[100:103], v[48:51], v[198:201], v[100:103]
	v_mfma_f32_16x16x32_bf16 v[96:99], v[56:59], v[198:201], v[96:99]
	v_mfma_f32_16x16x32_bf16 v[148:151], v[52:55], v[164:167], v[148:151]
	v_mfma_f32_16x16x32_bf16 v[144:147], v[60:63], v[164:167], v[144:147]
	v_mfma_f32_16x16x32_bf16 v[132:135], v[52:55], v[184:187], v[132:135]
	v_mfma_f32_16x16x32_bf16 v[128:131], v[60:63], v[184:187], v[128:131]
	v_mfma_f32_16x16x32_bf16 v[116:119], v[52:55], v[194:197], v[116:119]
	v_mfma_f32_16x16x32_bf16 v[112:115], v[60:63], v[194:197], v[112:115]
	v_mfma_f32_16x16x32_bf16 v[100:103], v[52:55], v[202:205], v[100:103]
	v_mfma_f32_16x16x32_bf16 v[96:99], v[60:63], v[202:205], v[96:99]
	s_barrier
; #define PG8_STAGE(bufoff, gbase, voff) do { _Pragma("unroll") for (int _i = 0; _i < 2; ++_i) \
;         __builtin_amdgcn_global_load_lds((const unsigned*)((const char*)(gbase) + (voff)[_i]), (PG8_LAS unsigned*)(lds + (bufoff) + ldsw + _i * 8192), 16, 0, 0); } while (0)
; #define PG8_LDA(dst, b, h) do { _Pragma("unroll") for (int m = 0; m < 4; ++m) _Pragma("unroll") for (int k = 0; k < 2; ++k) dst[m][k] = *(const PG8_LAS bf16x8*)(lds + PG8_SA(b, h) + aoff + m * 2048 + k * 1024); } while (0)
; #define PG8_LDB(dst, b, h) do { _Pragma("unroll") for (int n = 0; n < 2; ++n) _Pragma("unroll") for (int k = 0; k < 2; ++k) dst[n][k] = *(const PG8_LAS bf16x8*)(lds + PG8_SB(b, h) + boff + n * 2048 + k * 1024); } while (0)
; #define PG8_MMA(ai, bj, At, Bt) do { __builtin_amdgcn_s_setprio(1); _Pragma("unroll") for (int m = 0; m < 4; ++m) _Pragma("unroll") for (int n = 0; n < 2; ++n) _Pragma("unroll") for (int k = 0; k < 2; ++k) \
;         acc[ai][bj][m][n] = __builtin_amdgcn_mfma_f32_16x16x32_bf16(Bt[n][k], At[m][k], acc[ai][bj][m][n], 0, 0, 0); __builtin_amdgcn_s_setprio(0); } while (0)
; #define PG8_WAIT_V(n) asm volatile("s_waitcnt vmcnt(" #n ")" ::: "memory")
; #define PG8_WAIT_L(n) asm volatile("s_waitcnt lgkmcnt(" #n ")" ::: "memory")
; #define PG8_BAR __builtin_amdgcn_s_barrier()
; template <class Epi, class Sched, bool ALIGN_EPI = false, bool SP2 = false>
; __device__ __forceinline__ void gemm_phase(PG8_LAS unsigned char* lds, const Gemm g, const Sched& S, const Epi& E) {
;     ...
;             PG8_WAIT_V(8); PG8_WAIT_L(0); PG8_BAR; PG8_MMA(0, 0, At, B0); PG8_MMA(0, 1, At, B1); PG8_BAR; PG8_SCHED;
;             PG8_LDA(At, 0, 1); PG8_STAGE(PG8_SB(0, 0), b2, voffB); PG8_STAGE(PG8_SB(0, 1), b2 + hstep, voffB); PG8_STAGE(PG8_SA(0, 0), a2, voffA);
;             PG8_WAIT_V(8); PG8_WAIT_L(0); PG8_BAR; PG8_MMA(1, 0, At, B0); PG8_MMA(1, 1, At, B1); PG8_BAR; PG8_SCHED;
;             PG8_LDB(B0, 1, 0); PG8_LDB(B1, 1, 1); PG8_SCHED; PG8_LDA(At, 1, 0); PG8_STAGE(PG8_SA(0, 1), a2 + hstep, voffA);
;             PG8_WAIT_V(8); PG8_WAIT_L(0); PG8_BAR; PG8_MMA(0, 0, At, B0); PG8_MMA(0, 1, At, B1); PG8_BAR; PG8_SCHED;
;             PG8_LDA(At, 1, 1); PG8_STAGE(PG8_SB(1, 0), b3, voffB); PG8_STAGE(PG8_SB(1, 1), b3 + hstep, voffB); PG8_STAGE(PG8_SA(1, 0), a3, voffA);
;             PG8_WAIT_V(8); PG8_WAIT_L(0); PG8_BAR; PG8_MMA(1, 0, At, B0); PG8_MMA(1, 1, At, B1); PG8_BAR; PG8_SCHED;
	s_add_i32 s77, s77, s57
	s_mov_b32 m0, s77
	ds_read_b128 v[160:163], v193 offset:16384
	ds_read_b128 v[164:167], v193 offset:17408
	ds_read_b128 v[180:183], v193 offset:18432
	ds_read_b128 v[184:187], v193 offset:19456
	ds_read_b128 v[188:191], v193 offset:20480
	ds_read_b128 v[194:197], v193 offset:21504
	ds_read_b128 v[198:201], v193 offset:22528
	ds_read_b128 v[202:205], v193 offset:23552
	global_load_lds_dwordx4 v170, s[84:85]
	s_add_i32 m0, s77, 0x2000
	s_add_u32 s88, s84, 0x4000
	s_addc_u32 s89, s85, 0
	s_add_i32 s77, s79, s57
	global_load_lds_dwordx4 v174, s[84:85]
	s_mov_b32 m0, s77
	s_nop 0
	global_load_lds_dwordx4 v170, s[88:89]
	s_add_i32 m0, s77, 0x2000
	s_nop 0
	global_load_lds_dwordx4 v174, s[88:89]
	s_mov_b32 m0, s33
	s_nop 0
	global_load_lds_dwordx4 v168, s[86:87]
	s_mov_b32 m0, s42
	s_nop 0
	global_load_lds_dwordx4 v172, s[86:87]
	s_waitcnt vmcnt(8)
	s_waitcnt lgkmcnt(0)
	s_waitcnt lgkmcnt(0)
	v_mfma_f32_16x16x32_bf16 v[92:95], v[16:19], v[160:163], v[92:95]
	v_mfma_f32_16x16x32_bf16 v[88:91], v[24:27], v[160:163], v[88:91]
	v_mfma_f32_16x16x32_bf16 v[76:79], v[16:19], v[180:183], v[76:79]
	v_mfma_f32_16x16x32_bf16 v[72:75], v[24:27], v[180:183], v[72:75]
	v_mfma_f32_16x16x32_bf16 v[44:47], v[16:19], v[188:191], v[44:47]
	v_mfma_f32_16x16x32_bf16 v[40:43], v[24:27], v[188:191], v[40:43]
	v_mfma_f32_16x16x32_bf16 v[12:15], v[16:19], v[198:201], v[12:15]
	v_mfma_f32_16x16x32_bf16 v[8:11], v[24:27], v[198:201], v[8:11]
	v_mfma_f32_16x16x32_bf16 v[92:95], v[20:23], v[164:167], v[92:95]
	v_mfma_f32_16x16x32_bf16 v[88:91], v[32:35], v[164:167], v[88:91]
	v_mfma_f32_16x16x32_bf16 v[76:79], v[20:23], v[184:187], v[76:79]
	v_mfma_f32_16x16x32_bf16 v[72:75], v[32:35], v[184:187], v[72:75]
	v_mfma_f32_16x16x32_bf16 v[44:47], v[20:23], v[194:197], v[44:47]
	v_mfma_f32_16x16x32_bf16 v[40:43], v[32:35], v[194:197], v[40:43]
	v_mfma_f32_16x16x32_bf16 v[12:15], v[20:23], v[202:205], v[12:15]
	v_mfma_f32_16x16x32_bf16 v[8:11], v[32:35], v[202:205], v[8:11]
	v_mfma_f32_16x16x32_bf16 v[36:39], v[48:51], v[188:191], v[36:39]
	v_mfma_f32_16x16x32_bf16 v[28:31], v[56:59], v[188:191], v[28:31]
	v_mfma_f32_16x16x32_bf16 v[4:7], v[48:51], v[198:201], v[4:7]
	v_mfma_f32_16x16x32_bf16 v[0:3], v[56:59], v[198:201], v[0:3]
	v_mfma_f32_16x16x32_bf16 v[16:19], v[48:51], v[160:163], v[84:87]
	v_mfma_f32_16x16x32_bf16 v[20:23], v[56:59], v[160:163], v[80:83]
	v_mfma_f32_16x16x32_bf16 v[24:27], v[48:51], v[180:183], v[68:71]
	v_mfma_f32_16x16x32_bf16 v[32:35], v[56:59], v[180:183], v[64:67]
	v_mfma_f32_16x16x32_bf16 v[36:39], v[52:55], v[194:197], v[36:39]
	v_mfma_f32_16x16x32_bf16 v[28:31], v[60:63], v[194:197], v[28:31]
	v_mfma_f32_16x16x32_bf16 v[4:7], v[52:55], v[202:205], v[4:7]
	v_mfma_f32_16x16x32_bf16 v[0:3], v[60:63], v[202:205], v[0:3]
	v_mfma_f32_16x16x32_bf16 v[16:19], v[52:55], v[164:167], v[16:19]
	v_mfma_f32_16x16x32_bf16 v[20:23], v[60:63], v[164:167], v[20:23]
	v_mfma_f32_16x16x32_bf16 v[24:27], v[52:55], v[184:187], v[24:27]
	v_mfma_f32_16x16x32_bf16 v[32:35], v[60:63], v[184:187], v[32:35]
	s_barrier
	s_add_i32 s77, 0, 0x18000
	s_add_i32 s79, 0, 0x1c000
	v_add_u32_e32 v60, s77, v192
	v_add_u32_e32 v64, s79, v192
	ds_read_b128 v[48:51], v60
	ds_read_b128 v[52:55], v60 offset:1024
	ds_read_b128 v[56:59], v60 offset:2048
	ds_read_b128 v[60:63], v60 offset:3072
	ds_read_b128 v[160:163], v64
	ds_read_b128 v[164:167], v64 offset:1024
	ds_read_b128 v[180:183], v64 offset:2048
	ds_read_b128 v[184:187], v64 offset:3072
	s_add_u32 s86, s86, 0x4000
	s_addc_u32 s87, s87, 0
	s_mov_b32 m0, s64
	ds_read_b128 v[64:67], v193 offset:32768
	ds_read_b128 v[68:71], v193 offset:33792
	ds_read_b128 v[80:83], v193 offset:34816
	ds_read_b128 v[84:87], v193 offset:35840
	ds_read_b128 v[188:191], v193 offset:36864
	ds_read_b128 v[194:197], v193 offset:37888
	ds_read_b128 v[198:201], v193 offset:38912
	ds_read_b128 v[202:205], v193 offset:39936
	global_load_lds_dwordx4 v168, s[86:87]
	s_mov_b32 m0, s65
	s_nop 0
	global_load_lds_dwordx4 v172, s[86:87]
	s_waitcnt vmcnt(8)
	s_waitcnt lgkmcnt(0)
	s_waitcnt lgkmcnt(0)
	v_mfma_f32_16x16x32_bf16 v[156:159], v[48:51], v[64:67], v[156:159]
	v_mfma_f32_16x16x32_bf16 v[152:155], v[56:59], v[64:67], v[152:155]
	v_mfma_f32_16x16x32_bf16 v[140:143], v[48:51], v[80:83], v[140:143]
	v_mfma_f32_16x16x32_bf16 v[136:139], v[56:59], v[80:83], v[136:139]
	v_mfma_f32_16x16x32_bf16 v[124:127], v[48:51], v[188:191], v[124:127]
	v_mfma_f32_16x16x32_bf16 v[120:123], v[56:59], v[188:191], v[120:123]
	v_mfma_f32_16x16x32_bf16 v[108:111], v[48:51], v[198:201], v[108:111]
	v_mfma_f32_16x16x32_bf16 v[104:107], v[56:59], v[198:201], v[104:107]
	v_mfma_f32_16x16x32_bf16 v[156:159], v[52:55], v[68:71], v[156:159]
	v_mfma_f32_16x16x32_bf16 v[152:155], v[60:63], v[68:71], v[152:155]
	v_mfma_f32_16x16x32_bf16 v[140:143], v[52:55], v[84:87], v[140:143]
	v_mfma_f32_16x16x32_bf16 v[136:139], v[60:63], v[84:87], v[136:139]
	v_mfma_f32_16x16x32_bf16 v[124:127], v[52:55], v[194:197], v[124:127]
	v_mfma_f32_16x16x32_bf16 v[120:123], v[60:63], v[194:197], v[120:123]
	v_mfma_f32_16x16x32_bf16 v[108:111], v[52:55], v[202:205], v[108:111]
	v_mfma_f32_16x16x32_bf16 v[104:107], v[60:63], v[202:205], v[104:107]
	v_mfma_f32_16x16x32_bf16 v[148:151], v[160:163], v[64:67], v[148:151]
	v_mfma_f32_16x16x32_bf16 v[64:67], v[180:183], v[64:67], v[144:147]
	v_mfma_f32_16x16x32_bf16 v[144:147], v[184:187], v[68:71], v[64:67]
	v_mfma_f32_16x16x32_bf16 v[64:67], v[160:163], v[80:83], v[132:135]
	v_mfma_f32_16x16x32_bf16 v[132:135], v[164:167], v[84:87], v[64:67]
	v_mfma_f32_16x16x32_bf16 v[64:67], v[180:183], v[80:83], v[128:131]
	v_mfma_f32_16x16x32_bf16 v[128:131], v[184:187], v[84:87], v[64:67]
	v_mfma_f32_16x16x32_bf16 v[64:67], v[160:163], v[188:191], v[116:119]
	v_mfma_f32_16x16x32_bf16 v[116:119], v[164:167], v[194:197], v[64:67]
	v_mfma_f32_16x16x32_bf16 v[64:67], v[180:183], v[188:191], v[112:115]
	v_mfma_f32_16x16x32_bf16 v[112:115], v[184:187], v[194:197], v[64:67]
	v_mfma_f32_16x16x32_bf16 v[64:67], v[160:163], v[198:201], v[100:103]
	v_mfma_f32_16x16x32_bf16 v[100:103], v[164:167], v[202:205], v[64:67]
	v_mfma_f32_16x16x32_bf16 v[64:67], v[180:183], v[198:201], v[96:99]
	v_mfma_f32_16x16x32_bf16 v[148:151], v[164:167], v[68:71], v[148:151]
	v_mfma_f32_16x16x32_bf16 v[96:99], v[184:187], v[202:205], v[64:67]
	s_barrier
; #define PG8_STAGE(bufoff, gbase, voff) do { _Pragma("unroll") for (int _i = 0; _i < 2; ++_i) \
;         __builtin_amdgcn_global_load_lds((const unsigned*)((const char*)(gbase) + (voff)[_i]), (PG8_LAS unsigned*)(lds + (bufoff) + ldsw + _i * 8192), 16, 0, 0); } while (0)
; #define PG8_LDA(dst, b, h) do { _Pragma("unroll") for (int m = 0; m < 4; ++m) _Pragma("unroll") for (int k = 0; k < 2; ++k) dst[m][k] = *(const PG8_LAS bf16x8*)(lds + PG8_SA(b, h) + aoff + m * 2048 + k * 1024); } while (0)
; #define PG8_MMA(ai, bj, At, Bt) do { __builtin_amdgcn_s_setprio(1); _Pragma("unroll") for (int m = 0; m < 4; ++m) _Pragma("unroll") for (int n = 0; n < 2; ++n) _Pragma("unroll") for (int k = 0; k < 2; ++k) \
;         acc[ai][bj][m][n] = __builtin_amdgcn_mfma_f32_16x16x32_bf16(Bt[n][k], At[m][k], acc[ai][bj][m][n], 0, 0, 0); __builtin_amdgcn_s_setprio(0); } while (0)
; #define PG8_WAIT_V(n) asm volatile("s_waitcnt vmcnt(" #n ")" ::: "memory")
; #define PG8_WAIT_L(n) asm volatile("s_waitcnt lgkmcnt(" #n ")" ::: "memory")
; #define PG8_BAR __builtin_amdgcn_s_barrier()
; #define PG8_SCHED __builtin_amdgcn_sched_barrier(0)
; template <class Epi, class Sched, bool ALIGN_EPI = false, bool SP2 = false>
; __device__ __forceinline__ void gemm_phase(PG8_LAS unsigned char* lds, const Gemm g, const Sched& S, const Epi& E) {
;     ...
;             PG8_WAIT_V(8); PG8_WAIT_L(0); PG8_BAR; PG8_MMA(0, 0, At, B0); PG8_MMA(0, 1, At, B1); PG8_BAR; PG8_SCHED;
;             PG8_LDA(At, 1, 1); PG8_STAGE(PG8_SB(1, 0), b3, voffB); PG8_STAGE(PG8_SB(1, 1), b3 + hstep, voffB); PG8_STAGE(PG8_SA(1, 0), a3, voffA);
;             PG8_WAIT_V(8); PG8_WAIT_L(0); PG8_BAR; PG8_MMA(1, 0, At, B0); PG8_MMA(1, 1, At, B1); PG8_BAR; PG8_SCHED;
	s_add_u32 s86, s84, 0x8000
	s_addc_u32 s87, s85, 0
	s_add_i32 s77, s77, s57
	s_mov_b32 m0, s77
	ds_read_b128 v[64:67], v193 offset:49152
	ds_read_b128 v[68:71], v193 offset:50176
	ds_read_b128 v[188:191], v193 offset:51200
	ds_read_b128 v[194:197], v193 offset:52224
	ds_read_b128 v[198:201], v193 offset:53248
	ds_read_b128 v[202:205], v193 offset:54272
	ds_read_b128 v[206:209], v193 offset:55296
	ds_read_b128 v[210:213], v193 offset:56320
	global_load_lds_dwordx4 v170, s[86:87]
	s_add_i32 m0, s77, 0x2000
	s_add_u32 s84, s84, 0xc000
	s_addc_u32 s85, s85, 0
	s_add_i32 s77, s79, s57
	global_load_lds_dwordx4 v174, s[86:87]
	s_mov_b32 m0, s77
	s_nop 0
	global_load_lds_dwordx4 v170, s[84:85]
	s_add_i32 m0, s77, 0x2000
	s_nop 0
	global_load_lds_dwordx4 v174, s[84:85]
	s_mov_b32 m0, s53
	s_nop 0
	global_load_lds_dwordx4 v168, s[10:11]
	s_mov_b32 m0, s27
	s_nop 0
	global_load_lds_dwordx4 v172, s[10:11]
	s_waitcnt vmcnt(8)
	s_waitcnt lgkmcnt(0)
	s_waitcnt lgkmcnt(0)
	v_mfma_f32_16x16x32_bf16 v[80:83], v[48:51], v[64:67], v[92:95]
	v_mfma_f32_16x16x32_bf16 v[92:95], v[52:55], v[68:71], v[80:83]
	v_mfma_f32_16x16x32_bf16 v[80:83], v[56:59], v[64:67], v[88:91]
	v_mfma_f32_16x16x32_bf16 v[76:79], v[48:51], v[188:191], v[76:79]
	v_mfma_f32_16x16x32_bf16 v[72:75], v[56:59], v[188:191], v[72:75]
	v_mfma_f32_16x16x32_bf16 v[44:47], v[48:51], v[198:201], v[44:47]
	v_mfma_f32_16x16x32_bf16 v[40:43], v[56:59], v[198:201], v[40:43]
	v_mfma_f32_16x16x32_bf16 v[12:15], v[48:51], v[206:209], v[12:15]
	v_mfma_f32_16x16x32_bf16 v[8:11], v[56:59], v[206:209], v[8:11]
	v_mfma_f32_16x16x32_bf16 v[88:91], v[60:63], v[68:71], v[80:83]
	v_mfma_f32_16x16x32_bf16 v[76:79], v[52:55], v[194:197], v[76:79]
	v_mfma_f32_16x16x32_bf16 v[72:75], v[60:63], v[194:197], v[72:75]
	v_mfma_f32_16x16x32_bf16 v[44:47], v[52:55], v[202:205], v[44:47]
	v_mfma_f32_16x16x32_bf16 v[40:43], v[60:63], v[202:205], v[40:43]
	v_mfma_f32_16x16x32_bf16 v[12:15], v[52:55], v[210:213], v[12:15]
	v_mfma_f32_16x16x32_bf16 v[8:11], v[60:63], v[210:213], v[8:11]
	v_mfma_f32_16x16x32_bf16 v[16:19], v[160:163], v[64:67], v[16:19]
	v_mfma_f32_16x16x32_bf16 v[84:87], v[164:167], v[68:71], v[16:19]
	v_mfma_f32_16x16x32_bf16 v[16:19], v[180:183], v[64:67], v[20:23]
	v_mfma_f32_16x16x32_bf16 v[80:83], v[184:187], v[68:71], v[16:19]
	v_mfma_f32_16x16x32_bf16 v[16:19], v[160:163], v[188:191], v[24:27]
	v_mfma_f32_16x16x32_bf16 v[68:71], v[164:167], v[194:197], v[16:19]
	v_mfma_f32_16x16x32_bf16 v[16:19], v[180:183], v[188:191], v[32:35]
	v_mfma_f32_16x16x32_bf16 v[64:67], v[184:187], v[194:197], v[16:19]
	v_mfma_f32_16x16x32_bf16 v[16:19], v[160:163], v[198:201], v[36:39]
	v_mfma_f32_16x16x32_bf16 v[36:39], v[164:167], v[202:205], v[16:19]
	v_mfma_f32_16x16x32_bf16 v[16:19], v[180:183], v[198:201], v[28:31]
	v_mfma_f32_16x16x32_bf16 v[4:7], v[160:163], v[206:209], v[4:7]
	v_mfma_f32_16x16x32_bf16 v[0:3], v[180:183], v[206:209], v[0:3]
	v_mfma_f32_16x16x32_bf16 v[28:31], v[184:187], v[202:205], v[16:19]
	v_mfma_f32_16x16x32_bf16 v[4:7], v[164:167], v[210:213], v[4:7]
	v_mfma_f32_16x16x32_bf16 v[0:3], v[184:187], v[210:213], v[0:3]
	s_barrier
	s_add_i32 s40, s40, 2
	s_add_u32 s6, s6, 0x10000
	s_addc_u32 s7, s7, 0
	s_add_u32 s30, s30, 0x10000
	s_addc_u32 s37, s37, 0
	s_cmp_gt_u32 s40, 13
	s_cbranch_scc0 .Lk2_trail

; #define PG8_BAR __builtin_amdgcn_s_barrier()
;     static __device__ __forceinline__ bool keep_acc(const Unit& u) { return (u.pm >> 6) == 2; }
; template <class Epi, class Sched, bool ALIGN_EPI = false, bool SP2 = false>
; __device__ __forceinline__ void gemm_phase(PG8_LAS unsigned char* lds, const Gemm g, const Sched& S, const Epi& E) {
;     ...
;         if constexpr (ALIGN_EPI) { if (wr == 0) PG8_BAR; }
;         const bool keep = Epi::keep_acc(cur);
;         if constexpr (!Epi::AFTER_DRAIN) { if (!keep) E(acc, cur, wr, wc, fr, fq); S.done(cur); }
;         if (!has_next) break;
;         if (!keep)
; #pragma unroll
;         for (int a = 0; a < 2; ++a)
; #pragma unroll
;             for (int b = 0; b < 2; ++b)
; #pragma unroll
;                 for (int m = 0; m < 4; ++m)
; #pragma unroll
;                     for (int n = 0; n < 2; ++n) acc[a][b][m][n] = (f32x4){0.f, 0.f, 0.f, 0.f};
;         cur = nxt; cA = nA; cB = nB; ++ui;
;         if constexpr (ALIGN_EPI) { if (wr == 1) PG8_BAR; }
.LBB0_1293:
	s_andn2_b64 vcc, exec, s[2:3]
	s_mov_b64 s[2:3], -1
	s_movk_i32 s90, 0x80
	s_movk_i32 s84, 0x33c0
	s_movk_i32 s85, 0x1000
	s_movk_i32 s86, 0x3fc0
	s_mov_b32 s87, 0x42000
	s_movk_i32 s88, 0x37c0
	s_movk_i32 s89, 0x3bc0
	s_cbranch_vccnz .LBB0_1126
	v_readlane_b32 s2, v255, 16
	v_readlane_b32 s3, v255, 17
	s_andn2_b64 vcc, exec, s[2:3]
	s_cbranch_vccnz .LBB0_1125
	s_branch .LBB0_1125

; #define PG8_STAGE(bufoff, gbase, voff) do { _Pragma("unroll") for (int _i = 0; _i < 2; ++_i) \
;         __builtin_amdgcn_global_load_lds((const unsigned*)((const char*)(gbase) + (voff)[_i]), (PG8_LAS unsigned*)(lds + (bufoff) + ldsw + _i * 8192), 16, 0, 0); } while (0)
; #define PG8_WAIT_V(n) asm volatile("s_waitcnt vmcnt(" #n ")" ::: "memory")
; #define PG8_BAR __builtin_amdgcn_s_barrier()
; template <class Epi, class Sched, bool ALIGN_EPI = false, bool SP2 = false>
; __device__ __forceinline__ void gemm_phase(PG8_LAS unsigned char* lds, const Gemm g, const Sched& S, const Epi& E) {
;     ...
;         PG8_STAGE(PG8_SB(0, 0), cB, voffB); PG8_STAGE(PG8_SB(0, 1), cB + hstep, voffB); PG8_STAGE(PG8_SA(0, 0), cA, voffA); PG8_STAGE(PG8_SA(0, 1), cA + hstep, voffA);
;         if (wr == 1) PG8_BAR;
;         PG8_WAIT_V(2); PG8_BAR;
;         PG8_STAGE(PG8_SB(1, 0), cB + kstep, voffB); PG8_STAGE(PG8_SA(1, 0), cA + kstep, voffA); PG8_STAGE(PG8_SB(1, 1), cB + hstep + kstep, voffB);
;         PG8_WAIT_V(6); PG8_BAR;
;     } else {
;         PG8_STAGE(PG8_SB(0, 0), cB, voffB); PG8_STAGE(PG8_SA(0, 0), cA, voffA); PG8_STAGE(PG8_SB(0, 1), cB + hstep, voffB); PG8_STAGE(PG8_SA(0, 1), cA + hstep, voffA);
;         if (wr == 1) PG8_BAR;
;         PG8_WAIT_V(4); PG8_BAR;
;         PG8_STAGE(PG8_SB(1, 0), cB + kstep, voffB); PG8_STAGE(PG8_SA(1, 0), cA + kstep, voffA); PG8_STAGE(PG8_SB(1, 1), cB + hstep + kstep, voffB);
;         PG8_WAIT_V(6); PG8_BAR;
;     }
.LBB0_1308:
	s_lshl_b64 s[8:9], s[56:57], 11
	s_add_u32 s8, s62, s8
	s_addc_u32 s9, s63, s9
	s_add_u32 s8, s8, 0x6400000
	s_addc_u32 s9, s9, 0
	s_lshl_b32 s10, s56, 6
	s_add_u32 s10, s62, s10
	s_addc_u32 s11, s63, 0
	s_add_u32 s10, s10, 0x1e500000
	s_addc_u32 s11, s11, 0
	s_and_b32 s52, s12, 3
	s_lshr_b32 s53, s3, 6
	s_lshl_b32 s54, s2, 6
	s_lshl_b32 s12, s2, 13
	s_lshl_b32 s55, s52, 5
	s_lshl_b32 s13, s52, 12
	s_add_u32 s2, s18, 0x8000
	v_mov_b32_e32 v187, v221
	s_addc_u32 s3, s19, 0
	s_add_i32 m0, s41, 0x18000
	v_lshl_add_u64 v[8:9], s[2:3], 0, v[186:187]
	v_mov_b32_e32 v191, v221
	s_waitcnt vmcnt(2)
	global_load_lds_dwordx4 v[8:9], off
	s_add_i32 m0, s41, 0x1a000
	v_lshl_add_u64 v[8:9], s[2:3], 0, v[190:191]
	s_add_u32 s2, s16, 0x8000
	v_mov_b32_e32 v185, v221
	s_addc_u32 s3, s17, 0
	s_add_i32 s56, s41, 0x8000
	v_mov_b32_e32 v189, v221
	global_load_lds_dwordx4 v[8:9], off
	s_mov_b32 m0, s56
	s_add_i32 s57, s41, 0xa000
	global_load_lds_dwordx4 v184, s[2:3]
	v_lshl_add_u64 v[8:9], s[2:3], 0, v[188:189]
	s_add_u32 s2, s18, 0xc000
	s_mov_b32 m0, s57
	s_addc_u32 s3, s19, 0
	global_load_lds_dwordx4 v[8:9], off
	s_add_i32 m0, s41, 0x1c000
	s_nop 0
	global_load_lds_dwordx4 v186, s[2:3]
	s_add_i32 m0, s41, 0x1e000
	v_and_b32_e32 v7, 48, v0
	global_load_lds_dwordx4 v190, s[2:3]
	v_lshlrev_b32_e32 v8, 6, v0
	s_movk_i32 s2, 0x3c0
	v_lshlrev_b32_e32 v0, 2, v0
	v_and_or_b32 v7, v8, s2, v7
	v_and_b32_e32 v0, 32, v0
	v_bitop3_b32 v8, v7, s12, v0 bitop3:0xde
	v_bitop3_b32 v206, v7, s13, v0 bitop3:0xde
	v_lshlrev_b32_e32 v0, 10, v1
	v_and_b32_e32 v0, 0xfffff800, v0
	v_lshl_add_u32 v0, v2, 7, v0
	v_and_b32_e32 v1, 1, v1
	s_add_i32 s59, s53, -2
	v_lshl_or_b32 v0, v1, 6, v0
	s_cmpk_lt_u32 s5, 0x100
	v_lshl_add_u32 v194, v3, 1, v0
	v_lshlrev_b32_e32 v0, 10, v4
	s_cselect_b64 s[12:13], -1, 0
	s_and_b32 s61, s55, 32
	s_ashr_i32 s68, s60, 31
	s_ashr_i32 s69, s58, 31
	v_and_b32_e32 v0, 0xfffff800, v0
	v_cndmask_b32_e64 v192, 1.0, 0.5, s[0:1]
	s_waitcnt vmcnt(6)
	s_and_b64 s[0:1], s[0:1], exec
	v_lshl_add_u32 v0, v5, 7, v0
	v_and_b32_e32 v1, 1, v4
	s_cselect_b32 s70, 6, 5
	s_lshr_b32 s0, s22, 1
	v_lshl_or_b32 v0, v1, 6, v0
	s_mov_b32 s5, s31
	s_or_b32 s71, s0, 1
	v_mov_b32_e32 v193, v192
	v_mov_b32_e32 v195, v221
	v_lshl_add_u32 v196, v6, 1, v0
	v_mov_b32_e32 v197, v221
	s_mov_b32 s72, 0
	v_add_u32_e32 v207, 0, v8
	s_barrier
	s_branch .LBB0_1311

; #define PG8_STAGE(bufoff, gbase, voff) do { _Pragma("unroll") for (int _i = 0; _i < 2; ++_i) \
;         __builtin_amdgcn_global_load_lds((const unsigned*)((const char*)(gbase) + (voff)[_i]), (PG8_LAS unsigned*)(lds + (bufoff) + ldsw + _i * 8192), 16, 0, 0); } while (0)
; #define PG8_LDA(dst, b, h) do { _Pragma("unroll") for (int m = 0; m < 4; ++m) _Pragma("unroll") for (int k = 0; k < 2; ++k) dst[m][k] = *(const PG8_LAS bf16x8*)(lds + PG8_SA(b, h) + aoff + m * 2048 + k * 1024); } while (0)
; #define PG8_LDB(dst, b, h) do { _Pragma("unroll") for (int n = 0; n < 2; ++n) _Pragma("unroll") for (int k = 0; k < 2; ++k) dst[n][k] = *(const PG8_LAS bf16x8*)(lds + PG8_SB(b, h) + boff + n * 2048 + k * 1024); } while (0)
; template <class Epi, class Sched, bool ALIGN_EPI = false, bool SP2 = false>
; __device__ __forceinline__ void gemm_phase(PG8_LAS unsigned char* lds, const Gemm g, const Sched& S, const Epi& E) {
;     ...
;         for (int t = 0; t < nt; t += 2) {
;             const bool last = (t == nt - 2);
;             const char* a1 = cA + (size_t)(t + 1) * kstep;
;             const char* a2 = last ? nA : cA + (size_t)(t + 2) * kstep; const char* b2 = last ? nB : cB + (size_t)(t + 2) * kstep;
;             const char* a3 = a2 + kstep; const char* b3 = b2 + kstep;
;             if (last && has_next) S.a_ready(nxt);
;             if constexpr (SP2) {
;             PG8_LDB(B0, 0, 0); PG8_LDB(B1, 0, 1); PG8_SCHED; PG8_LDA(At, 0, 0); PG8_STAGE(PG8_SA(1, 1), a1 + hstep, voffA);
;             PG8_WAIT_V(8); PG8_WAIT_L(0); PG8_BAR; PG8_MMA(0, 0, At, B0); PG8_MMA(0, 1, At, B1); PG8_BAR; PG8_SCHED;
;             PG8_LDA(At, 0, 1); PG8_STAGE(PG8_SB(0, 0), b2, voffB); PG8_STAGE(PG8_SB(0, 1), b2 + hstep, voffB); PG8_STAGE(PG8_SA(0, 0), a2, voffA);
;             PG8_WAIT_V(8); PG8_WAIT_L(0); PG8_BAR; PG8_MMA(1, 0, At, B0); PG8_MMA(1, 1, At, B1); PG8_BAR; PG8_SCHED;
;             PG8_LDB(B0, 1, 0); PG8_LDB(B1, 1, 1); PG8_SCHED; PG8_LDA(At, 1, 0); PG8_STAGE(PG8_SA(0, 1), a2 + hstep, voffA);
;             PG8_WAIT_V(8); PG8_WAIT_L(0); PG8_BAR; PG8_MMA(0, 0, At, B0); PG8_MMA(0, 1, At, B1); PG8_BAR; PG8_SCHED;
;             PG8_LDA(At, 1, 1); PG8_STAGE(PG8_SB(1, 0), b3, voffB); PG8_STAGE(PG8_SB(1, 1), b3 + hstep, voffB); PG8_STAGE(PG8_SA(1, 0), a3, voffA);
;             PG8_WAIT_V(8); PG8_WAIT_L(0); PG8_BAR; PG8_MMA(1, 0, At, B0); PG8_MMA(1, 1, At, B1); PG8_BAR; PG8_SCHED;
.LBB0_1322:
	s_and_b64 vcc, exec, s[12:13]
	s_cbranch_vccz .Lk1_trail
.Lk1_lead:
	s_add_i32 s75, s18, 2
	s_add_u32 s19, s16, 0x4000
	s_addc_u32 s20, s17, 0
	s_cmp_eq_u32 s59, s18
	s_cselect_b32 s64, s0, s19
	s_cselect_b32 s65, s1, s20
	s_cselect_b32 s20, s14, s66
	s_cselect_b32 s21, s15, s67
	s_add_u32 s18, s64, 0x8000
	s_addc_u32 s19, s65, 0
	s_add_i32 s76, 0, 0x10000
	s_add_i32 s78, 0, 0x14000
	v_add_u32_e32 v108, s76, v206
	v_add_u32_e32 v156, s78, v206
	ds_read_b128 v[80:83], v108
	ds_read_b128 v[84:87], v108 offset:1024
	ds_read_b128 v[104:107], v108 offset:2048
	ds_read_b128 v[108:111], v108 offset:3072
	ds_read_b128 v[128:131], v156
	ds_read_b128 v[136:139], v156 offset:1024
	ds_read_b128 v[152:155], v156 offset:2048
	ds_read_b128 v[156:159], v156 offset:3072
	s_add_i32 m0, s41, 0xc000
	ds_read_b128 v[160:163], v207
	ds_read_b128 v[164:167], v207 offset:1024
	ds_read_b128 v[168:171], v207 offset:2048
	ds_read_b128 v[172:175], v207 offset:3072
	ds_read_b128 v[176:179], v207 offset:4096
	ds_read_b128 v[180:183], v207 offset:5120
	ds_read_b128 v[198:201], v207 offset:6144
	ds_read_b128 v[202:205], v207 offset:7168
	global_load_lds_dwordx4 v194, s[16:17]
	s_add_i32 m0, s41, 0xe000
	s_nop 0
	global_load_lds_dwordx4 v196, s[16:17]
	s_waitcnt vmcnt(8)
	s_waitcnt lgkmcnt(0)
	s_barrier
	s_waitcnt lgkmcnt(0)
	v_mfma_f32_16x16x32_bf16 v[148:151], v[80:83], v[160:163], v[148:151]
	v_mfma_f32_16x16x32_bf16 v[144:147], v[104:107], v[160:163], v[144:147]
	v_mfma_f32_16x16x32_bf16 v[124:127], v[80:83], v[168:171], v[124:127]
	v_mfma_f32_16x16x32_bf16 v[120:123], v[104:107], v[168:171], v[120:123]
	v_mfma_f32_16x16x32_bf16 v[100:103], v[80:83], v[176:179], v[100:103]
	v_mfma_f32_16x16x32_bf16 v[96:99], v[104:107], v[176:179], v[96:99]
	v_mfma_f32_16x16x32_bf16 v[76:79], v[80:83], v[198:201], v[76:79]
	v_mfma_f32_16x16x32_bf16 v[72:75], v[104:107], v[198:201], v[72:75]
	v_mfma_f32_16x16x32_bf16 v[148:151], v[84:87], v[164:167], v[148:151]
	v_mfma_f32_16x16x32_bf16 v[144:147], v[108:111], v[164:167], v[144:147]
	v_mfma_f32_16x16x32_bf16 v[124:127], v[84:87], v[172:175], v[124:127]
	v_mfma_f32_16x16x32_bf16 v[120:123], v[108:111], v[172:175], v[120:123]
	v_mfma_f32_16x16x32_bf16 v[100:103], v[84:87], v[180:183], v[100:103]
	v_mfma_f32_16x16x32_bf16 v[96:99], v[108:111], v[180:183], v[96:99]
	v_mfma_f32_16x16x32_bf16 v[76:79], v[84:87], v[202:205], v[76:79]
	v_mfma_f32_16x16x32_bf16 v[72:75], v[108:111], v[202:205], v[72:75]
	v_mfma_f32_16x16x32_bf16 v[140:143], v[128:131], v[160:163], v[140:143]
	v_mfma_f32_16x16x32_bf16 v[132:135], v[152:155], v[160:163], v[132:135]
	v_mfma_f32_16x16x32_bf16 v[116:119], v[128:131], v[168:171], v[116:119]
	v_mfma_f32_16x16x32_bf16 v[112:115], v[152:155], v[168:171], v[112:115]
	v_mfma_f32_16x16x32_bf16 v[92:95], v[128:131], v[176:179], v[92:95]
	v_mfma_f32_16x16x32_bf16 v[88:91], v[152:155], v[176:179], v[88:91]
	v_mfma_f32_16x16x32_bf16 v[68:71], v[128:131], v[198:201], v[68:71]
	v_mfma_f32_16x16x32_bf16 v[64:67], v[152:155], v[198:201], v[64:67]
	v_mfma_f32_16x16x32_bf16 v[140:143], v[136:139], v[164:167], v[140:143]
	v_mfma_f32_16x16x32_bf16 v[132:135], v[156:159], v[164:167], v[132:135]
	v_mfma_f32_16x16x32_bf16 v[116:119], v[136:139], v[172:175], v[116:119]
	v_mfma_f32_16x16x32_bf16 v[112:115], v[156:159], v[172:175], v[112:115]
	v_mfma_f32_16x16x32_bf16 v[92:95], v[136:139], v[180:183], v[92:95]
	v_mfma_f32_16x16x32_bf16 v[88:91], v[156:159], v[180:183], v[88:91]
	v_mfma_f32_16x16x32_bf16 v[68:71], v[136:139], v[202:205], v[68:71]
	v_mfma_f32_16x16x32_bf16 v[64:67], v[156:159], v[202:205], v[64:67]
	s_add_i32 s76, s76, s39
	s_mov_b32 m0, s76
	ds_read_b128 v[160:163], v207 offset:16384
	ds_read_b128 v[164:167], v207 offset:17408
	ds_read_b128 v[168:171], v207 offset:18432
	ds_read_b128 v[172:175], v207 offset:19456
	ds_read_b128 v[176:179], v207 offset:20480
	ds_read_b128 v[180:183], v207 offset:21504
	ds_read_b128 v[198:201], v207 offset:22528
	ds_read_b128 v[202:205], v207 offset:23552
	global_load_lds_dwordx4 v186, s[20:21]
	s_add_i32 m0, s76, 0x2000
	s_add_u32 s76, s20, 0x4000
	s_addc_u32 s77, s21, 0
	s_add_i32 s78, s78, s39
	global_load_lds_dwordx4 v190, s[20:21]
	s_mov_b32 m0, s78
	s_nop 0
	global_load_lds_dwordx4 v186, s[76:77]
	s_add_i32 m0, s78, 0x2000
	s_nop 0
	global_load_lds_dwordx4 v190, s[76:77]
	s_mov_b32 m0, s41
	s_nop 0
	global_load_lds_dwordx4 v184, s[64:65]
	s_mov_b32 m0, s42
	s_nop 0
	global_load_lds_dwordx4 v188, s[64:65]
	s_waitcnt vmcnt(8)
	s_waitcnt lgkmcnt(0)
	s_barrier
; #define PG8_STAGE(bufoff, gbase, voff) do { _Pragma("unroll") for (int _i = 0; _i < 2; ++_i) \
;         __builtin_amdgcn_global_load_lds((const unsigned*)((const char*)(gbase) + (voff)[_i]), (PG8_LAS unsigned*)(lds + (bufoff) + ldsw + _i * 8192), 16, 0, 0); } while (0)
; #define PG8_LDA(dst, b, h) do { _Pragma("unroll") for (int m = 0; m < 4; ++m) _Pragma("unroll") for (int k = 0; k < 2; ++k) dst[m][k] = *(const PG8_LAS bf16x8*)(lds + PG8_SA(b, h) + aoff + m * 2048 + k * 1024); } while (0)
; #define PG8_LDB(dst, b, h) do { _Pragma("unroll") for (int n = 0; n < 2; ++n) _Pragma("unroll") for (int k = 0; k < 2; ++k) dst[n][k] = *(const PG8_LAS bf16x8*)(lds + PG8_SB(b, h) + boff + n * 2048 + k * 1024); } while (0)
; #define PG8_MMA(ai, bj, At, Bt) do { __builtin_amdgcn_s_setprio(1); _Pragma("unroll") for (int m = 0; m < 4; ++m) _Pragma("unroll") for (int n = 0; n < 2; ++n) _Pragma("unroll") for (int k = 0; k < 2; ++k) \
;         acc[ai][bj][m][n] = __builtin_amdgcn_mfma_f32_16x16x32_bf16(Bt[n][k], At[m][k], acc[ai][bj][m][n], 0, 0, 0); __builtin_amdgcn_s_setprio(0); } while (0)
; #define PG8_WAIT_V(n) asm volatile("s_waitcnt vmcnt(" #n ")" ::: "memory")
; template <class Epi, class Sched, bool ALIGN_EPI = false, bool SP2 = false>
; __device__ __forceinline__ void gemm_phase(PG8_LAS unsigned char* lds, const Gemm g, const Sched& S, const Epi& E) {
;     ...
;             PG8_LDB(B0, 0, 0); PG8_LDB(B1, 0, 1); PG8_SCHED; PG8_LDA(At, 0, 0); PG8_STAGE(PG8_SA(1, 1), a1 + hstep, voffA);
;             PG8_WAIT_V(8); PG8_WAIT_L(0); PG8_BAR; PG8_MMA(0, 0, At, B0); PG8_MMA(0, 1, At, B1); PG8_BAR; PG8_SCHED;
;             PG8_LDA(At, 0, 1); PG8_STAGE(PG8_SB(0, 0), b2, voffB); PG8_STAGE(PG8_SB(0, 1), b2 + hstep, voffB); PG8_STAGE(PG8_SA(0, 0), a2, voffA);
;             PG8_WAIT_V(8); PG8_WAIT_L(0); PG8_BAR; PG8_MMA(1, 0, At, B0); PG8_MMA(1, 1, At, B1); PG8_BAR; PG8_SCHED;
;             PG8_LDB(B0, 1, 0); PG8_LDB(B1, 1, 1); PG8_SCHED; PG8_LDA(At, 1, 0); PG8_STAGE(PG8_SA(0, 1), a2 + hstep, voffA);
;             PG8_WAIT_V(8); PG8_WAIT_L(0); PG8_BAR; PG8_MMA(0, 0, At, B0); PG8_MMA(0, 1, At, B1); PG8_BAR; PG8_SCHED;
;             PG8_LDA(At, 1, 1); PG8_STAGE(PG8_SB(1, 0), b3, voffB); PG8_STAGE(PG8_SB(1, 1), b3 + hstep, voffB); PG8_STAGE(PG8_SA(1, 0), a3, voffA);
;             PG8_WAIT_V(8); PG8_WAIT_L(0); PG8_BAR; PG8_MMA(1, 0, At, B0); PG8_MMA(1, 1, At, B1); PG8_BAR; PG8_SCHED;
	s_waitcnt lgkmcnt(0)
	v_mfma_f32_16x16x32_bf16 v[60:63], v[80:83], v[160:163], v[60:63]
	v_mfma_f32_16x16x32_bf16 v[56:59], v[104:107], v[160:163], v[56:59]
	v_mfma_f32_16x16x32_bf16 v[44:47], v[80:83], v[168:171], v[44:47]
	v_mfma_f32_16x16x32_bf16 v[40:43], v[104:107], v[168:171], v[40:43]
	v_mfma_f32_16x16x32_bf16 v[28:31], v[80:83], v[176:179], v[28:31]
	v_mfma_f32_16x16x32_bf16 v[24:27], v[104:107], v[176:179], v[24:27]
	v_mfma_f32_16x16x32_bf16 v[12:15], v[80:83], v[198:201], v[12:15]
	v_mfma_f32_16x16x32_bf16 v[8:11], v[104:107], v[198:201], v[8:11]
	v_mfma_f32_16x16x32_bf16 v[60:63], v[84:87], v[164:167], v[60:63]
	v_mfma_f32_16x16x32_bf16 v[56:59], v[108:111], v[164:167], v[56:59]
	v_mfma_f32_16x16x32_bf16 v[44:47], v[84:87], v[172:175], v[44:47]
	v_mfma_f32_16x16x32_bf16 v[40:43], v[108:111], v[172:175], v[40:43]
	v_mfma_f32_16x16x32_bf16 v[28:31], v[84:87], v[180:183], v[28:31]
	v_mfma_f32_16x16x32_bf16 v[24:27], v[108:111], v[180:183], v[24:27]
	v_mfma_f32_16x16x32_bf16 v[12:15], v[84:87], v[202:205], v[12:15]
	v_mfma_f32_16x16x32_bf16 v[8:11], v[108:111], v[202:205], v[8:11]
	v_mfma_f32_16x16x32_bf16 v[52:55], v[128:131], v[160:163], v[52:55]
	v_mfma_f32_16x16x32_bf16 v[48:51], v[152:155], v[160:163], v[48:51]
	v_mfma_f32_16x16x32_bf16 v[36:39], v[128:131], v[168:171], v[36:39]
	v_mfma_f32_16x16x32_bf16 v[32:35], v[152:155], v[168:171], v[32:35]
	v_mfma_f32_16x16x32_bf16 v[20:23], v[128:131], v[176:179], v[20:23]
	v_mfma_f32_16x16x32_bf16 v[16:19], v[152:155], v[176:179], v[16:19]
	v_mfma_f32_16x16x32_bf16 v[4:7], v[128:131], v[198:201], v[4:7]
	v_mfma_f32_16x16x32_bf16 v[0:3], v[152:155], v[198:201], v[0:3]
	v_mfma_f32_16x16x32_bf16 v[52:55], v[136:139], v[164:167], v[52:55]
	v_mfma_f32_16x16x32_bf16 v[48:51], v[156:159], v[164:167], v[48:51]
	v_mfma_f32_16x16x32_bf16 v[36:39], v[136:139], v[172:175], v[36:39]
	v_mfma_f32_16x16x32_bf16 v[32:35], v[156:159], v[172:175], v[32:35]
	v_mfma_f32_16x16x32_bf16 v[20:23], v[136:139], v[180:183], v[20:23]
	v_mfma_f32_16x16x32_bf16 v[16:19], v[156:159], v[180:183], v[16:19]
	v_mfma_f32_16x16x32_bf16 v[4:7], v[136:139], v[202:205], v[4:7]
	v_mfma_f32_16x16x32_bf16 v[0:3], v[156:159], v[202:205], v[0:3]
	s_add_i32 s76, 0, 0x18000
	s_add_i32 s77, 0, 0x1c000
	v_add_u32_e32 v108, s76, v206
	v_add_u32_e32 v156, s77, v206
	ds_read_b128 v[80:83], v108
	ds_read_b128 v[84:87], v108 offset:1024
	ds_read_b128 v[104:107], v108 offset:2048
	ds_read_b128 v[108:111], v108 offset:3072
	ds_read_b128 v[128:131], v156
	ds_read_b128 v[136:139], v156 offset:1024
	ds_read_b128 v[152:155], v156 offset:2048
	ds_read_b128 v[156:159], v156 offset:3072
	s_add_u32 s64, s64, 0x4000
	s_addc_u32 s65, s65, 0
	s_mov_b32 m0, s50
	ds_read_b128 v[160:163], v207 offset:32768
	ds_read_b128 v[164:167], v207 offset:33792
	ds_read_b128 v[168:171], v207 offset:34816
	ds_read_b128 v[172:175], v207 offset:35840
	ds_read_b128 v[176:179], v207 offset:36864
	ds_read_b128 v[180:183], v207 offset:37888
	ds_read_b128 v[198:201], v207 offset:38912
	ds_read_b128 v[202:205], v207 offset:39936
	global_load_lds_dwordx4 v184, s[64:65]
	s_mov_b32 m0, s51
	s_nop 0
	global_load_lds_dwordx4 v188, s[64:65]
	s_waitcnt vmcnt(8)
	s_waitcnt lgkmcnt(0)
	s_barrier
	s_waitcnt lgkmcnt(0)
	v_mfma_f32_16x16x32_bf16 v[148:151], v[80:83], v[160:163], v[148:151]
	v_mfma_f32_16x16x32_bf16 v[144:147], v[104:107], v[160:163], v[144:147]
	v_mfma_f32_16x16x32_bf16 v[124:127], v[80:83], v[168:171], v[124:127]
	v_mfma_f32_16x16x32_bf16 v[120:123], v[104:107], v[168:171], v[120:123]
	v_mfma_f32_16x16x32_bf16 v[100:103], v[80:83], v[176:179], v[100:103]
	v_mfma_f32_16x16x32_bf16 v[96:99], v[104:107], v[176:179], v[96:99]
	v_mfma_f32_16x16x32_bf16 v[76:79], v[80:83], v[198:201], v[76:79]
	v_mfma_f32_16x16x32_bf16 v[72:75], v[104:107], v[198:201], v[72:75]
	v_mfma_f32_16x16x32_bf16 v[148:151], v[84:87], v[164:167], v[148:151]
	v_mfma_f32_16x16x32_bf16 v[144:147], v[108:111], v[164:167], v[144:147]
	v_mfma_f32_16x16x32_bf16 v[124:127], v[84:87], v[172:175], v[124:127]
	v_mfma_f32_16x16x32_bf16 v[120:123], v[108:111], v[172:175], v[120:123]
	v_mfma_f32_16x16x32_bf16 v[100:103], v[84:87], v[180:183], v[100:103]
	v_mfma_f32_16x16x32_bf16 v[96:99], v[108:111], v[180:183], v[96:99]
	v_mfma_f32_16x16x32_bf16 v[76:79], v[84:87], v[202:205], v[76:79]
	v_mfma_f32_16x16x32_bf16 v[72:75], v[108:111], v[202:205], v[72:75]
	v_mfma_f32_16x16x32_bf16 v[140:143], v[128:131], v[160:163], v[140:143]
	v_mfma_f32_16x16x32_bf16 v[132:135], v[152:155], v[160:163], v[132:135]
	v_mfma_f32_16x16x32_bf16 v[116:119], v[128:131], v[168:171], v[116:119]
	v_mfma_f32_16x16x32_bf16 v[112:115], v[152:155], v[168:171], v[112:115]
	v_mfma_f32_16x16x32_bf16 v[92:95], v[128:131], v[176:179], v[92:95]
	v_mfma_f32_16x16x32_bf16 v[88:91], v[152:155], v[176:179], v[88:91]
	v_mfma_f32_16x16x32_bf16 v[68:71], v[128:131], v[198:201], v[68:71]
	v_mfma_f32_16x16x32_bf16 v[64:67], v[152:155], v[198:201], v[64:67]
	v_mfma_f32_16x16x32_bf16 v[140:143], v[136:139], v[164:167], v[140:143]
	v_mfma_f32_16x16x32_bf16 v[132:135], v[156:159], v[164:167], v[132:135]
	v_mfma_f32_16x16x32_bf16 v[116:119], v[136:139], v[172:175], v[116:119]
	v_mfma_f32_16x16x32_bf16 v[112:115], v[156:159], v[172:175], v[112:115]
	v_mfma_f32_16x16x32_bf16 v[92:95], v[136:139], v[180:183], v[92:95]
	v_mfma_f32_16x16x32_bf16 v[88:91], v[156:159], v[180:183], v[88:91]
	v_mfma_f32_16x16x32_bf16 v[68:71], v[136:139], v[202:205], v[68:71]
	v_mfma_f32_16x16x32_bf16 v[64:67], v[156:159], v[202:205], v[64:67]
	s_add_u32 s64, s20, 0x8000
	s_addc_u32 s65, s21, 0
	s_add_i32 s76, s76, s39
	s_mov_b32 m0, s76
	ds_read_b128 v[160:163], v207 offset:49152
	ds_read_b128 v[164:167], v207 offset:50176
	ds_read_b128 v[168:171], v207 offset:51200
	ds_read_b128 v[172:175], v207 offset:52224
	ds_read_b128 v[176:179], v207 offset:53248
	ds_read_b128 v[180:183], v207 offset:54272
	ds_read_b128 v[198:201], v207 offset:55296
	ds_read_b128 v[202:205], v207 offset:56320
	global_load_lds_dwordx4 v186, s[64:65]
	s_add_i32 m0, s76, 0x2000
	s_add_u32 s20, s20, 0xc000
	v_lshl_add_u64 v[208:209], s[64:65], 0, v[190:191]
	s_addc_u32 s21, s21, 0
	s_add_i32 s64, s77, s39
	global_load_lds_dwordx4 v[208:209], off
	s_mov_b32 m0, s64
	s_nop 0
	global_load_lds_dwordx4 v186, s[20:21]
	s_add_i32 m0, s64, 0x2000
	s_nop 0
	global_load_lds_dwordx4 v190, s[20:21]
	s_mov_b32 m0, s56
	s_nop 0
	global_load_lds_dwordx4 v184, s[18:19]
	s_mov_b32 m0, s57
	s_nop 0
	global_load_lds_dwordx4 v188, s[18:19]
	s_waitcnt vmcnt(8)
	s_waitcnt lgkmcnt(0)
	s_barrier
; #define PG8_STAGE(bufoff, gbase, voff) do { _Pragma("unroll") for (int _i = 0; _i < 2; ++_i) \
;         __builtin_amdgcn_global_load_lds((const unsigned*)((const char*)(gbase) + (voff)[_i]), (PG8_LAS unsigned*)(lds + (bufoff) + ldsw + _i * 8192), 16, 0, 0); } while (0)
; #define PG8_LDA(dst, b, h) do { _Pragma("unroll") for (int m = 0; m < 4; ++m) _Pragma("unroll") for (int k = 0; k < 2; ++k) dst[m][k] = *(const PG8_LAS bf16x8*)(lds + PG8_SA(b, h) + aoff + m * 2048 + k * 1024); } while (0)
; #define PG8_LDB(dst, b, h) do { _Pragma("unroll") for (int n = 0; n < 2; ++n) _Pragma("unroll") for (int k = 0; k < 2; ++k) dst[n][k] = *(const PG8_LAS bf16x8*)(lds + PG8_SB(b, h) + boff + n * 2048 + k * 1024); } while (0)
; template <class Epi, class Sched, bool ALIGN_EPI = false, bool SP2 = false>
; __device__ __forceinline__ void gemm_phase(PG8_LAS unsigned char* lds, const Gemm g, const Sched& S, const Epi& E) {
;     ...
;         for (int t = 0; t < nt; t += 2) {
;             const bool last = (t == nt - 2);
;             const char* a1 = cA + (size_t)(t + 1) * kstep;
;             const char* a2 = last ? nA : cA + (size_t)(t + 2) * kstep; const char* b2 = last ? nB : cB + (size_t)(t + 2) * kstep;
;             const char* a3 = a2 + kstep; const char* b3 = b2 + kstep;
;             if (last && has_next) S.a_ready(nxt);
;             if constexpr (SP2) {
;             PG8_LDB(B0, 0, 0); PG8_LDB(B1, 0, 1); PG8_SCHED; PG8_LDA(At, 0, 0); PG8_STAGE(PG8_SA(1, 1), a1 + hstep, voffA);
;             PG8_WAIT_V(8); PG8_WAIT_L(0); PG8_BAR; PG8_MMA(0, 0, At, B0); PG8_MMA(0, 1, At, B1); PG8_BAR; PG8_SCHED;
;             PG8_LDA(At, 0, 1); PG8_STAGE(PG8_SB(0, 0), b2, voffB); PG8_STAGE(PG8_SB(0, 1), b2 + hstep, voffB); PG8_STAGE(PG8_SA(0, 0), a2, voffA);
;             PG8_WAIT_V(8); PG8_WAIT_L(0); PG8_BAR; PG8_MMA(1, 0, At, B0); PG8_MMA(1, 1, At, B1); PG8_BAR; PG8_SCHED;
;             PG8_LDB(B0, 1, 0); PG8_LDB(B1, 1, 1); PG8_SCHED; PG8_LDA(At, 1, 0); PG8_STAGE(PG8_SA(0, 1), a2 + hstep, voffA);
;             PG8_WAIT_V(8); PG8_WAIT_L(0); PG8_BAR; PG8_MMA(0, 0, At, B0); PG8_MMA(0, 1, At, B1); PG8_BAR; PG8_SCHED;
;             PG8_LDA(At, 1, 1); PG8_STAGE(PG8_SB(1, 0), b3, voffB); PG8_STAGE(PG8_SB(1, 1), b3 + hstep, voffB); PG8_STAGE(PG8_SA(1, 0), a3, voffA);
;             PG8_WAIT_V(8); PG8_WAIT_L(0); PG8_BAR; PG8_MMA(1, 0, At, B0); PG8_MMA(1, 1, At, B1); PG8_BAR; PG8_SCHED;
	s_waitcnt lgkmcnt(0)
	v_mfma_f32_16x16x32_bf16 v[60:63], v[80:83], v[160:163], v[60:63]
	v_mfma_f32_16x16x32_bf16 v[56:59], v[104:107], v[160:163], v[56:59]
	v_mfma_f32_16x16x32_bf16 v[44:47], v[80:83], v[168:171], v[44:47]
	v_mfma_f32_16x16x32_bf16 v[40:43], v[104:107], v[168:171], v[40:43]
	v_mfma_f32_16x16x32_bf16 v[28:31], v[80:83], v[176:179], v[28:31]
	v_mfma_f32_16x16x32_bf16 v[24:27], v[104:107], v[176:179], v[24:27]
	v_mfma_f32_16x16x32_bf16 v[12:15], v[80:83], v[198:201], v[12:15]
	v_mfma_f32_16x16x32_bf16 v[8:11], v[104:107], v[198:201], v[8:11]
	v_mfma_f32_16x16x32_bf16 v[60:63], v[84:87], v[164:167], v[60:63]
	v_mfma_f32_16x16x32_bf16 v[56:59], v[108:111], v[164:167], v[56:59]
	v_mfma_f32_16x16x32_bf16 v[44:47], v[84:87], v[172:175], v[44:47]
	v_mfma_f32_16x16x32_bf16 v[40:43], v[108:111], v[172:175], v[40:43]
	v_mfma_f32_16x16x32_bf16 v[28:31], v[84:87], v[180:183], v[28:31]
	v_mfma_f32_16x16x32_bf16 v[24:27], v[108:111], v[180:183], v[24:27]
	v_mfma_f32_16x16x32_bf16 v[12:15], v[84:87], v[202:205], v[12:15]
	v_mfma_f32_16x16x32_bf16 v[8:11], v[108:111], v[202:205], v[8:11]
	v_mfma_f32_16x16x32_bf16 v[52:55], v[128:131], v[160:163], v[52:55]
	v_mfma_f32_16x16x32_bf16 v[48:51], v[152:155], v[160:163], v[48:51]
	v_mfma_f32_16x16x32_bf16 v[36:39], v[128:131], v[168:171], v[36:39]
	v_mfma_f32_16x16x32_bf16 v[32:35], v[152:155], v[168:171], v[32:35]
	v_mfma_f32_16x16x32_bf16 v[20:23], v[128:131], v[176:179], v[20:23]
	v_mfma_f32_16x16x32_bf16 v[16:19], v[152:155], v[176:179], v[16:19]
	v_mfma_f32_16x16x32_bf16 v[4:7], v[128:131], v[198:201], v[4:7]
	v_mfma_f32_16x16x32_bf16 v[0:3], v[152:155], v[198:201], v[0:3]
	v_mfma_f32_16x16x32_bf16 v[52:55], v[136:139], v[164:167], v[52:55]
	v_mfma_f32_16x16x32_bf16 v[48:51], v[156:159], v[164:167], v[48:51]
	v_mfma_f32_16x16x32_bf16 v[36:39], v[136:139], v[172:175], v[36:39]
	v_mfma_f32_16x16x32_bf16 v[32:35], v[156:159], v[172:175], v[32:35]
	v_mfma_f32_16x16x32_bf16 v[20:23], v[136:139], v[180:183], v[20:23]
	v_mfma_f32_16x16x32_bf16 v[16:19], v[156:159], v[180:183], v[16:19]
	v_mfma_f32_16x16x32_bf16 v[4:7], v[136:139], v[202:205], v[4:7]
	v_mfma_f32_16x16x32_bf16 v[0:3], v[156:159], v[202:205], v[0:3]
	s_add_u32 s16, s16, 0x10000
	s_addc_u32 s17, s17, 0
	s_add_u32 s66, s66, 0x10000
	s_addc_u32 s67, s67, 0
	s_cmp_ge_u32 s75, s53
	s_mov_b32 s18, s75
	s_cbranch_scc0 .Lk1_lead
	s_branch .Lk1_done
.Lk1_trail:
	s_add_i32 s75, s18, 2
	s_add_u32 s19, s16, 0x4000
	s_addc_u32 s20, s17, 0
	s_cmp_eq_u32 s59, s18
	s_cselect_b32 s64, s0, s19
	s_cselect_b32 s65, s1, s20
	s_cselect_b32 s20, s14, s66
	s_cselect_b32 s21, s15, s67
	s_add_u32 s18, s64, 0x8000
	s_addc_u32 s19, s65, 0
	s_add_i32 s76, 0, 0x10000
	s_add_i32 s78, 0, 0x14000
	v_add_u32_e32 v108, s76, v206
	v_add_u32_e32 v156, s78, v206
	ds_read_b128 v[80:83], v108
	ds_read_b128 v[84:87], v108 offset:1024
	ds_read_b128 v[104:107], v108 offset:2048
	ds_read_b128 v[108:111], v108 offset:3072
	ds_read_b128 v[128:131], v156
	ds_read_b128 v[136:139], v156 offset:1024
	ds_read_b128 v[152:155], v156 offset:2048
	ds_read_b128 v[156:159], v156 offset:3072
	s_add_i32 m0, s41, 0xc000
	ds_read_b128 v[160:163], v207
	ds_read_b128 v[164:167], v207 offset:1024
	ds_read_b128 v[168:171], v207 offset:2048
	ds_read_b128 v[172:175], v207 offset:3072
	ds_read_b128 v[176:179], v207 offset:4096
	ds_read_b128 v[180:183], v207 offset:5120
	ds_read_b128 v[198:201], v207 offset:6144
	ds_read_b128 v[202:205], v207 offset:7168
	global_load_lds_dwordx4 v194, s[16:17]
	s_add_i32 m0, s41, 0xe000
	s_nop 0
	global_load_lds_dwordx4 v196, s[16:17]
	s_waitcnt vmcnt(8)
	s_waitcnt lgkmcnt(0)
	s_waitcnt lgkmcnt(0)
	v_mfma_f32_16x16x32_bf16 v[148:151], v[80:83], v[160:163], v[148:151]
	v_mfma_f32_16x16x32_bf16 v[144:147], v[104:107], v[160:163], v[144:147]
	v_mfma_f32_16x16x32_bf16 v[124:127], v[80:83], v[168:171], v[124:127]
	v_mfma_f32_16x16x32_bf16 v[120:123], v[104:107], v[168:171], v[120:123]
	v_mfma_f32_16x16x32_bf16 v[100:103], v[80:83], v[176:179], v[100:103]
	v_mfma_f32_16x16x32_bf16 v[96:99], v[104:107], v[176:179], v[96:99]
	v_mfma_f32_16x16x32_bf16 v[76:79], v[80:83], v[198:201], v[76:79]
	v_mfma_f32_16x16x32_bf16 v[72:75], v[104:107], v[198:201], v[72:75]
	v_mfma_f32_16x16x32_bf16 v[148:151], v[84:87], v[164:167], v[148:151]
	v_mfma_f32_16x16x32_bf16 v[144:147], v[108:111], v[164:167], v[144:147]
	v_mfma_f32_16x16x32_bf16 v[124:127], v[84:87], v[172:175], v[124:127]
	v_mfma_f32_16x16x32_bf16 v[120:123], v[108:111], v[172:175], v[120:123]
	v_mfma_f32_16x16x32_bf16 v[100:103], v[84:87], v[180:183], v[100:103]
	v_mfma_f32_16x16x32_bf16 v[96:99], v[108:111], v[180:183], v[96:99]
	v_mfma_f32_16x16x32_bf16 v[76:79], v[84:87], v[202:205], v[76:79]
	v_mfma_f32_16x16x32_bf16 v[72:75], v[108:111], v[202:205], v[72:75]
	v_mfma_f32_16x16x32_bf16 v[140:143], v[128:131], v[160:163], v[140:143]
	v_mfma_f32_16x16x32_bf16 v[132:135], v[152:155], v[160:163], v[132:135]
	v_mfma_f32_16x16x32_bf16 v[116:119], v[128:131], v[168:171], v[116:119]
	v_mfma_f32_16x16x32_bf16 v[112:115], v[152:155], v[168:171], v[112:115]
	v_mfma_f32_16x16x32_bf16 v[92:95], v[128:131], v[176:179], v[92:95]
	v_mfma_f32_16x16x32_bf16 v[88:91], v[152:155], v[176:179], v[88:91]
	v_mfma_f32_16x16x32_bf16 v[68:71], v[128:131], v[198:201], v[68:71]
	v_mfma_f32_16x16x32_bf16 v[64:67], v[152:155], v[198:201], v[64:67]
	v_mfma_f32_16x16x32_bf16 v[140:143], v[136:139], v[164:167], v[140:143]
	v_mfma_f32_16x16x32_bf16 v[132:135], v[156:159], v[164:167], v[132:135]
	v_mfma_f32_16x16x32_bf16 v[116:119], v[136:139], v[172:175], v[116:119]
	v_mfma_f32_16x16x32_bf16 v[112:115], v[156:159], v[172:175], v[112:115]
	v_mfma_f32_16x16x32_bf16 v[92:95], v[136:139], v[180:183], v[92:95]
	v_mfma_f32_16x16x32_bf16 v[88:91], v[156:159], v[180:183], v[88:91]
	v_mfma_f32_16x16x32_bf16 v[68:71], v[136:139], v[202:205], v[68:71]
	v_mfma_f32_16x16x32_bf16 v[64:67], v[156:159], v[202:205], v[64:67]
	s_barrier
; #define PG8_STAGE(bufoff, gbase, voff) do { _Pragma("unroll") for (int _i = 0; _i < 2; ++_i) \
;         __builtin_amdgcn_global_load_lds((const unsigned*)((const char*)(gbase) + (voff)[_i]), (PG8_LAS unsigned*)(lds + (bufoff) + ldsw + _i * 8192), 16, 0, 0); } while (0)
; #define PG8_LDA(dst, b, h) do { _Pragma("unroll") for (int m = 0; m < 4; ++m) _Pragma("unroll") for (int k = 0; k < 2; ++k) dst[m][k] = *(const PG8_LAS bf16x8*)(lds + PG8_SA(b, h) + aoff + m * 2048 + k * 1024); } while (0)
; #define PG8_LDB(dst, b, h) do { _Pragma("unroll") for (int n = 0; n < 2; ++n) _Pragma("unroll") for (int k = 0; k < 2; ++k) dst[n][k] = *(const PG8_LAS bf16x8*)(lds + PG8_SB(b, h) + boff + n * 2048 + k * 1024); } while (0)
; #define PG8_MMA(ai, bj, At, Bt) do { __builtin_amdgcn_s_setprio(1); _Pragma("unroll") for (int m = 0; m < 4; ++m) _Pragma("unroll") for (int n = 0; n < 2; ++n) _Pragma("unroll") for (int k = 0; k < 2; ++k) \
;         acc[ai][bj][m][n] = __builtin_amdgcn_mfma_f32_16x16x32_bf16(Bt[n][k], At[m][k], acc[ai][bj][m][n], 0, 0, 0); __builtin_amdgcn_s_setprio(0); } while (0)
; #define PG8_WAIT_V(n) asm volatile("s_waitcnt vmcnt(" #n ")" ::: "memory")
; template <class Epi, class Sched, bool ALIGN_EPI = false, bool SP2 = false>
; __device__ __forceinline__ void gemm_phase(PG8_LAS unsigned char* lds, const Gemm g, const Sched& S, const Epi& E) {
;     ...
;             PG8_LDB(B0, 0, 0); PG8_LDB(B1, 0, 1); PG8_SCHED; PG8_LDA(At, 0, 0); PG8_STAGE(PG8_SA(1, 1), a1 + hstep, voffA);
;             PG8_WAIT_V(8); PG8_WAIT_L(0); PG8_BAR; PG8_MMA(0, 0, At, B0); PG8_MMA(0, 1, At, B1); PG8_BAR; PG8_SCHED;
;             PG8_LDA(At, 0, 1); PG8_STAGE(PG8_SB(0, 0), b2, voffB); PG8_STAGE(PG8_SB(0, 1), b2 + hstep, voffB); PG8_STAGE(PG8_SA(0, 0), a2, voffA);
;             PG8_WAIT_V(8); PG8_WAIT_L(0); PG8_BAR; PG8_MMA(1, 0, At, B0); PG8_MMA(1, 1, At, B1); PG8_BAR; PG8_SCHED;
;             PG8_LDB(B0, 1, 0); PG8_LDB(B1, 1, 1); PG8_SCHED; PG8_LDA(At, 1, 0); PG8_STAGE(PG8_SA(0, 1), a2 + hstep, voffA);
;             PG8_WAIT_V(8); PG8_WAIT_L(0); PG8_BAR; PG8_MMA(0, 0, At, B0); PG8_MMA(0, 1, At, B1); PG8_BAR; PG8_SCHED;
;             PG8_LDA(At, 1, 1); PG8_STAGE(PG8_SB(1, 0), b3, voffB); PG8_STAGE(PG8_SB(1, 1), b3 + hstep, voffB); PG8_STAGE(PG8_SA(1, 0), a3, voffA);
;             PG8_WAIT_V(8); PG8_WAIT_L(0); PG8_BAR; PG8_MMA(1, 0, At, B0); PG8_MMA(1, 1, At, B1); PG8_BAR; PG8_SCHED;
	s_add_i32 s76, s76, s39
	s_mov_b32 m0, s76
	ds_read_b128 v[160:163], v207 offset:16384
	ds_read_b128 v[164:167], v207 offset:17408
	ds_read_b128 v[168:171], v207 offset:18432
	ds_read_b128 v[172:175], v207 offset:19456
	ds_read_b128 v[176:179], v207 offset:20480
	ds_read_b128 v[180:183], v207 offset:21504
	ds_read_b128 v[198:201], v207 offset:22528
	ds_read_b128 v[202:205], v207 offset:23552
	global_load_lds_dwordx4 v186, s[20:21]
	s_add_i32 m0, s76, 0x2000
	s_add_u32 s76, s20, 0x4000
	s_addc_u32 s77, s21, 0
	s_add_i32 s78, s78, s39
	global_load_lds_dwordx4 v190, s[20:21]
	s_mov_b32 m0, s78
	s_nop 0
	global_load_lds_dwordx4 v186, s[76:77]
	s_add_i32 m0, s78, 0x2000
	s_nop 0
	global_load_lds_dwordx4 v190, s[76:77]
	s_mov_b32 m0, s41
	s_nop 0
	global_load_lds_dwordx4 v184, s[64:65]
	s_mov_b32 m0, s42
	s_nop 0
	global_load_lds_dwordx4 v188, s[64:65]
	s_waitcnt vmcnt(8)
	s_waitcnt lgkmcnt(0)
	s_waitcnt lgkmcnt(0)
	v_mfma_f32_16x16x32_bf16 v[60:63], v[80:83], v[160:163], v[60:63]
	v_mfma_f32_16x16x32_bf16 v[56:59], v[104:107], v[160:163], v[56:59]
	v_mfma_f32_16x16x32_bf16 v[44:47], v[80:83], v[168:171], v[44:47]
	v_mfma_f32_16x16x32_bf16 v[40:43], v[104:107], v[168:171], v[40:43]
	v_mfma_f32_16x16x32_bf16 v[28:31], v[80:83], v[176:179], v[28:31]
	v_mfma_f32_16x16x32_bf16 v[24:27], v[104:107], v[176:179], v[24:27]
	v_mfma_f32_16x16x32_bf16 v[12:15], v[80:83], v[198:201], v[12:15]
	v_mfma_f32_16x16x32_bf16 v[8:11], v[104:107], v[198:201], v[8:11]
	v_mfma_f32_16x16x32_bf16 v[60:63], v[84:87], v[164:167], v[60:63]
	v_mfma_f32_16x16x32_bf16 v[56:59], v[108:111], v[164:167], v[56:59]
	v_mfma_f32_16x16x32_bf16 v[44:47], v[84:87], v[172:175], v[44:47]
	v_mfma_f32_16x16x32_bf16 v[40:43], v[108:111], v[172:175], v[40:43]
	v_mfma_f32_16x16x32_bf16 v[28:31], v[84:87], v[180:183], v[28:31]
	v_mfma_f32_16x16x32_bf16 v[24:27], v[108:111], v[180:183], v[24:27]
	v_mfma_f32_16x16x32_bf16 v[12:15], v[84:87], v[202:205], v[12:15]
	v_mfma_f32_16x16x32_bf16 v[8:11], v[108:111], v[202:205], v[8:11]
	v_mfma_f32_16x16x32_bf16 v[52:55], v[128:131], v[160:163], v[52:55]
	v_mfma_f32_16x16x32_bf16 v[48:51], v[152:155], v[160:163], v[48:51]
	v_mfma_f32_16x16x32_bf16 v[36:39], v[128:131], v[168:171], v[36:39]
	v_mfma_f32_16x16x32_bf16 v[32:35], v[152:155], v[168:171], v[32:35]
	v_mfma_f32_16x16x32_bf16 v[20:23], v[128:131], v[176:179], v[20:23]
	v_mfma_f32_16x16x32_bf16 v[16:19], v[152:155], v[176:179], v[16:19]
	v_mfma_f32_16x16x32_bf16 v[4:7], v[128:131], v[198:201], v[4:7]
	v_mfma_f32_16x16x32_bf16 v[0:3], v[152:155], v[198:201], v[0:3]
	v_mfma_f32_16x16x32_bf16 v[52:55], v[136:139], v[164:167], v[52:55]
	v_mfma_f32_16x16x32_bf16 v[48:51], v[156:159], v[164:167], v[48:51]
	v_mfma_f32_16x16x32_bf16 v[36:39], v[136:139], v[172:175], v[36:39]
	v_mfma_f32_16x16x32_bf16 v[32:35], v[156:159], v[172:175], v[32:35]
	v_mfma_f32_16x16x32_bf16 v[20:23], v[136:139], v[180:183], v[20:23]
	v_mfma_f32_16x16x32_bf16 v[16:19], v[156:159], v[180:183], v[16:19]
	v_mfma_f32_16x16x32_bf16 v[4:7], v[136:139], v[202:205], v[4:7]
	v_mfma_f32_16x16x32_bf16 v[0:3], v[156:159], v[202:205], v[0:3]
	s_barrier
	s_add_i32 s76, 0, 0x18000
	s_add_i32 s77, 0, 0x1c000
	v_add_u32_e32 v108, s76, v206
	v_add_u32_e32 v156, s77, v206
	ds_read_b128 v[80:83], v108
	ds_read_b128 v[84:87], v108 offset:1024
	ds_read_b128 v[104:107], v108 offset:2048
	ds_read_b128 v[108:111], v108 offset:3072
	ds_read_b128 v[128:131], v156
	ds_read_b128 v[136:139], v156 offset:1024
	ds_read_b128 v[152:155], v156 offset:2048
	ds_read_b128 v[156:159], v156 offset:3072
	s_add_u32 s64, s64, 0x4000
	s_addc_u32 s65, s65, 0
	s_mov_b32 m0, s50
	ds_read_b128 v[160:163], v207 offset:32768
	ds_read_b128 v[164:167], v207 offset:33792
	ds_read_b128 v[168:171], v207 offset:34816
	ds_read_b128 v[172:175], v207 offset:35840
	ds_read_b128 v[176:179], v207 offset:36864
	ds_read_b128 v[180:183], v207 offset:37888
	ds_read_b128 v[198:201], v207 offset:38912
	ds_read_b128 v[202:205], v207 offset:39936
	global_load_lds_dwordx4 v184, s[64:65]
	s_mov_b32 m0, s51
	s_nop 0
	global_load_lds_dwordx4 v188, s[64:65]
	s_waitcnt vmcnt(8)
	s_waitcnt lgkmcnt(0)
	s_waitcnt lgkmcnt(0)
	v_mfma_f32_16x16x32_bf16 v[148:151], v[80:83], v[160:163], v[148:151]
	v_mfma_f32_16x16x32_bf16 v[144:147], v[104:107], v[160:163], v[144:147]
	v_mfma_f32_16x16x32_bf16 v[124:127], v[80:83], v[168:171], v[124:127]
	v_mfma_f32_16x16x32_bf16 v[120:123], v[104:107], v[168:171], v[120:123]
	v_mfma_f32_16x16x32_bf16 v[100:103], v[80:83], v[176:179], v[100:103]
	v_mfma_f32_16x16x32_bf16 v[96:99], v[104:107], v[176:179], v[96:99]
	v_mfma_f32_16x16x32_bf16 v[76:79], v[80:83], v[198:201], v[76:79]
	v_mfma_f32_16x16x32_bf16 v[72:75], v[104:107], v[198:201], v[72:75]
	v_mfma_f32_16x16x32_bf16 v[148:151], v[84:87], v[164:167], v[148:151]
	v_mfma_f32_16x16x32_bf16 v[144:147], v[108:111], v[164:167], v[144:147]
	v_mfma_f32_16x16x32_bf16 v[124:127], v[84:87], v[172:175], v[124:127]
	v_mfma_f32_16x16x32_bf16 v[120:123], v[108:111], v[172:175], v[120:123]
	v_mfma_f32_16x16x32_bf16 v[100:103], v[84:87], v[180:183], v[100:103]
	v_mfma_f32_16x16x32_bf16 v[96:99], v[108:111], v[180:183], v[96:99]
	v_mfma_f32_16x16x32_bf16 v[76:79], v[84:87], v[202:205], v[76:79]
	v_mfma_f32_16x16x32_bf16 v[72:75], v[108:111], v[202:205], v[72:75]
	v_mfma_f32_16x16x32_bf16 v[140:143], v[128:131], v[160:163], v[140:143]
	v_mfma_f32_16x16x32_bf16 v[132:135], v[152:155], v[160:163], v[132:135]
	v_mfma_f32_16x16x32_bf16 v[116:119], v[128:131], v[168:171], v[116:119]
	v_mfma_f32_16x16x32_bf16 v[112:115], v[152:155], v[168:171], v[112:115]
	v_mfma_f32_16x16x32_bf16 v[92:95], v[128:131], v[176:179], v[92:95]
	v_mfma_f32_16x16x32_bf16 v[88:91], v[152:155], v[176:179], v[88:91]
	v_mfma_f32_16x16x32_bf16 v[68:71], v[128:131], v[198:201], v[68:71]
	v_mfma_f32_16x16x32_bf16 v[64:67], v[152:155], v[198:201], v[64:67]
	v_mfma_f32_16x16x32_bf16 v[140:143], v[136:139], v[164:167], v[140:143]
	v_mfma_f32_16x16x32_bf16 v[132:135], v[156:159], v[164:167], v[132:135]
	v_mfma_f32_16x16x32_bf16 v[116:119], v[136:139], v[172:175], v[116:119]
	v_mfma_f32_16x16x32_bf16 v[112:115], v[156:159], v[172:175], v[112:115]
	v_mfma_f32_16x16x32_bf16 v[92:95], v[136:139], v[180:183], v[92:95]
	v_mfma_f32_16x16x32_bf16 v[88:91], v[156:159], v[180:183], v[88:91]
	v_mfma_f32_16x16x32_bf16 v[68:71], v[136:139], v[202:205], v[68:71]
	v_mfma_f32_16x16x32_bf16 v[64:67], v[156:159], v[202:205], v[64:67]
	s_barrier
; #define PG8_STAGE(bufoff, gbase, voff) do { _Pragma("unroll") for (int _i = 0; _i < 2; ++_i) \
;         __builtin_amdgcn_global_load_lds((const unsigned*)((const char*)(gbase) + (voff)[_i]), (PG8_LAS unsigned*)(lds + (bufoff) + ldsw + _i * 8192), 16, 0, 0); } while (0)
; #define PG8_LDA(dst, b, h) do { _Pragma("unroll") for (int m = 0; m < 4; ++m) _Pragma("unroll") for (int k = 0; k < 2; ++k) dst[m][k] = *(const PG8_LAS bf16x8*)(lds + PG8_SA(b, h) + aoff + m * 2048 + k * 1024); } while (0)
; #define PG8_MMA(ai, bj, At, Bt) do { __builtin_amdgcn_s_setprio(1); _Pragma("unroll") for (int m = 0; m < 4; ++m) _Pragma("unroll") for (int n = 0; n < 2; ++n) _Pragma("unroll") for (int k = 0; k < 2; ++k) \
;         acc[ai][bj][m][n] = __builtin_amdgcn_mfma_f32_16x16x32_bf16(Bt[n][k], At[m][k], acc[ai][bj][m][n], 0, 0, 0); __builtin_amdgcn_s_setprio(0); } while (0)
; #define PG8_WAIT_V(n) asm volatile("s_waitcnt vmcnt(" #n ")" ::: "memory")
; #define PG8_WAIT_L(n) asm volatile("s_waitcnt lgkmcnt(" #n ")" ::: "memory")
; #define PG8_BAR __builtin_amdgcn_s_barrier()
; #define PG8_SCHED __builtin_amdgcn_sched_barrier(0)
; template <class Epi, class Sched, bool ALIGN_EPI = false, bool SP2 = false>
; __device__ __forceinline__ void gemm_phase(PG8_LAS unsigned char* lds, const Gemm g, const Sched& S, const Epi& E) {
;     ...
;             PG8_LDA(At, 1, 1); PG8_STAGE(PG8_SB(1, 0), b3, voffB); PG8_STAGE(PG8_SB(1, 1), b3 + hstep, voffB); PG8_STAGE(PG8_SA(1, 0), a3, voffA);
;             PG8_WAIT_V(8); PG8_WAIT_L(0); PG8_BAR; PG8_MMA(1, 0, At, B0); PG8_MMA(1, 1, At, B1); PG8_BAR; PG8_SCHED;
	s_add_u32 s64, s20, 0x8000
	s_addc_u32 s65, s21, 0
	s_add_i32 s76, s76, s39
	s_mov_b32 m0, s76
	ds_read_b128 v[160:163], v207 offset:49152
	ds_read_b128 v[164:167], v207 offset:50176
	ds_read_b128 v[168:171], v207 offset:51200
	ds_read_b128 v[172:175], v207 offset:52224
	ds_read_b128 v[176:179], v207 offset:53248
	ds_read_b128 v[180:183], v207 offset:54272
	ds_read_b128 v[198:201], v207 offset:55296
	ds_read_b128 v[202:205], v207 offset:56320
	global_load_lds_dwordx4 v186, s[64:65]
	s_add_i32 m0, s76, 0x2000
	s_add_u32 s20, s20, 0xc000
	v_lshl_add_u64 v[208:209], s[64:65], 0, v[190:191]
	s_addc_u32 s21, s21, 0
	s_add_i32 s64, s77, s39
	global_load_lds_dwordx4 v[208:209], off
	s_mov_b32 m0, s64
	s_nop 0
	global_load_lds_dwordx4 v186, s[20:21]
	s_add_i32 m0, s64, 0x2000
	s_nop 0
	global_load_lds_dwordx4 v190, s[20:21]
	s_mov_b32 m0, s56
	s_nop 0
	global_load_lds_dwordx4 v184, s[18:19]
	s_mov_b32 m0, s57
	s_nop 0
	global_load_lds_dwordx4 v188, s[18:19]
	s_waitcnt vmcnt(8)
	s_waitcnt lgkmcnt(0)
	s_waitcnt lgkmcnt(0)
	v_mfma_f32_16x16x32_bf16 v[60:63], v[80:83], v[160:163], v[60:63]
	v_mfma_f32_16x16x32_bf16 v[56:59], v[104:107], v[160:163], v[56:59]
	v_mfma_f32_16x16x32_bf16 v[44:47], v[80:83], v[168:171], v[44:47]
	v_mfma_f32_16x16x32_bf16 v[40:43], v[104:107], v[168:171], v[40:43]
	v_mfma_f32_16x16x32_bf16 v[28:31], v[80:83], v[176:179], v[28:31]
	v_mfma_f32_16x16x32_bf16 v[24:27], v[104:107], v[176:179], v[24:27]
	v_mfma_f32_16x16x32_bf16 v[12:15], v[80:83], v[198:201], v[12:15]
	v_mfma_f32_16x16x32_bf16 v[8:11], v[104:107], v[198:201], v[8:11]
	v_mfma_f32_16x16x32_bf16 v[60:63], v[84:87], v[164:167], v[60:63]
	v_mfma_f32_16x16x32_bf16 v[56:59], v[108:111], v[164:167], v[56:59]
	v_mfma_f32_16x16x32_bf16 v[44:47], v[84:87], v[172:175], v[44:47]
	v_mfma_f32_16x16x32_bf16 v[40:43], v[108:111], v[172:175], v[40:43]
	v_mfma_f32_16x16x32_bf16 v[28:31], v[84:87], v[180:183], v[28:31]
	v_mfma_f32_16x16x32_bf16 v[24:27], v[108:111], v[180:183], v[24:27]
	v_mfma_f32_16x16x32_bf16 v[12:15], v[84:87], v[202:205], v[12:15]
	v_mfma_f32_16x16x32_bf16 v[8:11], v[108:111], v[202:205], v[8:11]
	v_mfma_f32_16x16x32_bf16 v[52:55], v[128:131], v[160:163], v[52:55]
	v_mfma_f32_16x16x32_bf16 v[48:51], v[152:155], v[160:163], v[48:51]
	v_mfma_f32_16x16x32_bf16 v[36:39], v[128:131], v[168:171], v[36:39]
	v_mfma_f32_16x16x32_bf16 v[32:35], v[152:155], v[168:171], v[32:35]
	v_mfma_f32_16x16x32_bf16 v[20:23], v[128:131], v[176:179], v[20:23]
	v_mfma_f32_16x16x32_bf16 v[16:19], v[152:155], v[176:179], v[16:19]
	v_mfma_f32_16x16x32_bf16 v[4:7], v[128:131], v[198:201], v[4:7]
	v_mfma_f32_16x16x32_bf16 v[0:3], v[152:155], v[198:201], v[0:3]
	v_mfma_f32_16x16x32_bf16 v[52:55], v[136:139], v[164:167], v[52:55]
	v_mfma_f32_16x16x32_bf16 v[48:51], v[156:159], v[164:167], v[48:51]
	v_mfma_f32_16x16x32_bf16 v[36:39], v[136:139], v[172:175], v[36:39]
	v_mfma_f32_16x16x32_bf16 v[32:35], v[156:159], v[172:175], v[32:35]
	v_mfma_f32_16x16x32_bf16 v[20:23], v[136:139], v[180:183], v[20:23]
	v_mfma_f32_16x16x32_bf16 v[16:19], v[156:159], v[180:183], v[16:19]
	v_mfma_f32_16x16x32_bf16 v[4:7], v[136:139], v[202:205], v[4:7]
	v_mfma_f32_16x16x32_bf16 v[0:3], v[156:159], v[202:205], v[0:3]
	s_barrier
	s_add_u32 s16, s16, 0x10000
	s_addc_u32 s17, s17, 0
	s_add_u32 s66, s66, 0x10000
	s_addc_u32 s67, s67, 0
	s_cmp_ge_u32 s75, s53
	s_mov_b32 s18, s75
	s_cbranch_scc0 .Lk1_trail

; #define PG8_BAR __builtin_amdgcn_s_barrier()
; template <class Epi, class Sched, bool ALIGN_EPI = false, bool SP2 = false>
; __device__ __forceinline__ void gemm_phase(PG8_LAS unsigned char* lds, const Gemm g, const Sched& S, const Epi& E) {
;     ...
;         if (!has_next) break;
;         if (!keep)
; #pragma unroll
;         for (int a = 0; a < 2; ++a)
; #pragma unroll
;             for (int b = 0; b < 2; ++b)
; #pragma unroll
;                 for (int m = 0; m < 4; ++m)
; #pragma unroll
;                     for (int n = 0; n < 2; ++n) acc[a][b][m][n] = (f32x4){0.f, 0.f, 0.f, 0.f};
;         cur = nxt; cA = nA; cB = nB; ++ui;
;         if constexpr (ALIGN_EPI) { if (wr == 1) PG8_BAR; }
.LBB0_1341:
	s_or_b64 exec, exec, s[18:19]
	s_and_b64 vcc, exec, s[2:3]
	s_mov_b64 s[2:3], -1
	s_cbranch_vccnz .LBB0_1310
	s_andn2_b64 vcc, exec, s[6:7]
	s_cbranch_vccnz .LBB0_1309
	s_branch .LBB0_1309

; #define PG8_STAGE(bufoff, gbase, voff) do { _Pragma("unroll") for (int _i = 0; _i < 2; ++_i) \
;         __builtin_amdgcn_global_load_lds((const unsigned*)((const char*)(gbase) + (voff)[_i]), (PG8_LAS unsigned*)(lds + (bufoff) + ldsw + _i * 8192), 16, 0, 0); } while (0)
; #define PG8_WAIT_V(n) asm volatile("s_waitcnt vmcnt(" #n ")" ::: "memory")
; #define PG8_BAR __builtin_amdgcn_s_barrier()
; template <class Epi, class Sched, bool ALIGN_EPI = false, bool SP2 = false>
; __device__ __forceinline__ void gemm_phase(PG8_LAS unsigned char* lds, const Gemm g, const Sched& S, const Epi& E) {
;     ...
;     for (int i = 0; i < 2; ++i) { int R, C; stage_rc(tid * 16 + i * 8192, R, C); const int Rb = Epi::PERM ? ((R & ~31) + perm32(R & 31)) : R;
;         voffA[i] = (unsigned)(R * BK + C) * 2u; voffB[i] = (unsigned)(Rb * BK + C) * 2u; }
;     const size_t kstep = (size_t)(BM * BK * 2);
;     const size_t hstep = (size_t)HALF * BK * 2;
;     const size_t tstep = (size_t)BM * K * 2;
;     const unsigned ldsw = (unsigned)wid * 1024u;
;     const int aoff = lds_byte(wr * 64 + fr, fq * 8), boff = lds_byte(wc * 32 + fr, fq * 8);
;     ...
;     if constexpr (SP2) {
;         PG8_STAGE(PG8_SB(0, 0), cB, voffB); PG8_STAGE(PG8_SB(0, 1), cB + hstep, voffB); PG8_STAGE(PG8_SA(0, 0), cA, voffA); PG8_STAGE(PG8_SA(0, 1), cA + hstep, voffA);
;         if (wr == 1) PG8_BAR;
;         PG8_WAIT_V(2); PG8_BAR;
;         PG8_STAGE(PG8_SB(1, 0), cB + kstep, voffB); PG8_STAGE(PG8_SA(1, 0), cA + kstep, voffA); PG8_STAGE(PG8_SB(1, 1), cB + hstep + kstep, voffB);
;         PG8_WAIT_V(6); PG8_BAR;
.LBB0_1350:
	s_add_u32 s50, s62, 0xa400000
	s_addc_u32 s51, s63, 0
	s_add_u32 s4, s62, 0x1e500000
	s_addc_u32 s5, s63, 0
	s_lshl_b32 s9, s6, 5
	s_and_b32 s53, s9, 0x60
	s_lshl_b32 s52, s7, 6
	s_lshl_b32 s8, s7, 13
	s_lshl_b32 s10, s53, 7
	s_add_u32 s6, s20, 0x8000
	v_mov_b32_e32 v149, v221
	s_addc_u32 s7, s21, 0
	s_add_i32 m0, s37, 0x18000
	v_lshl_add_u64 v[8:9], s[6:7], 0, v[148:149]
	v_mov_b32_e32 v145, v221
	s_waitcnt vmcnt(2)
	global_load_lds_dwordx4 v[8:9], off
	s_add_i32 m0, s37, 0x1a000
	v_lshl_add_u64 v[8:9], s[6:7], 0, v[144:145]
	s_add_u32 s6, s18, 0x8000
	v_mov_b32_e32 v151, v221
	s_addc_u32 s7, s19, 0
	s_add_i32 s54, s37, 0x8000
	v_mov_b32_e32 v147, v221
	global_load_lds_dwordx4 v[8:9], off
	s_mov_b32 m0, s54
	s_add_i32 s55, s37, 0xa000
	global_load_lds_dwordx4 v150, s[6:7]
	v_lshl_add_u64 v[8:9], s[6:7], 0, v[146:147]
	s_add_u32 s6, s20, 0xc000
	s_mov_b32 m0, s55
	s_addc_u32 s7, s21, 0
	global_load_lds_dwordx4 v[8:9], off
	s_add_i32 m0, s37, 0x1c000
	s_nop 0
	global_load_lds_dwordx4 v148, s[6:7]
	s_add_i32 m0, s37, 0x1e000
	s_sext_i32_i16 s17, s2
	global_load_lds_dwordx4 v144, s[6:7]
	v_and_b32_e32 v7, 48, v0
	v_lshlrev_b32_e32 v8, 6, v0
	s_movk_i32 s2, 0x3c0
	v_lshlrev_b32_e32 v0, 2, v0
	v_and_or_b32 v7, v8, s2, v7
	v_and_b32_e32 v0, 32, v0
	v_bitop3_b32 v8, v7, s8, v0 bitop3:0xde
	v_bitop3_b32 v162, s10, v7, v0 bitop3:0xf6
	v_lshlrev_b32_e32 v0, 10, v5
	v_and_b32_e32 v0, 0xfffff800, v0
	v_lshl_add_u32 v0, v4, 7, v0
	v_and_b32_e32 v4, 1, v5
	v_lshl_or_b32 v0, v4, 6, v0
	v_lshl_add_u32 v152, v6, 1, v0
	v_lshlrev_b32_e32 v0, 10, v1
	v_and_b32_e32 v0, 0xfffff800, v0
	s_waitcnt vmcnt(6)
	v_lshl_add_u32 v0, v2, 7, v0
	v_and_b32_e32 v1, 1, v1
	s_cmpk_lt_u32 s3, 0x100
	v_lshl_or_b32 v0, v1, 6, v0
	s_cselect_b64 s[6:7], -1, 0
	s_and_b32 s56, s9, 32
	s_ashr_i32 s57, s60, 31
	v_mov_b32_e32 v153, v221
	v_lshl_add_u32 v154, v3, 1, v0
	v_mov_b32_e32 v155, v221
	s_mov_b32 s59, 0
	v_add_u32_e32 v163, 0, v8
	s_mov_b32 s74, 0x3a800000
	s_barrier
	s_branch .LBB0_1353

; #define PG8_STAGE(bufoff, gbase, voff) do { _Pragma("unroll") for (int _i = 0; _i < 2; ++_i) \
;         __builtin_amdgcn_global_load_lds((const unsigned*)((const char*)(gbase) + (voff)[_i]), (PG8_LAS unsigned*)(lds + (bufoff) + ldsw + _i * 8192), 16, 0, 0); } while (0)
; #define PG8_LDA(dst, b, h) do { _Pragma("unroll") for (int m = 0; m < 4; ++m) _Pragma("unroll") for (int k = 0; k < 2; ++k) dst[m][k] = *(const PG8_LAS bf16x8*)(lds + PG8_SA(b, h) + aoff + m * 2048 + k * 1024); } while (0)
; #define PG8_LDB(dst, b, h) do { _Pragma("unroll") for (int n = 0; n < 2; ++n) _Pragma("unroll") for (int k = 0; k < 2; ++k) dst[n][k] = *(const PG8_LAS bf16x8*)(lds + PG8_SB(b, h) + boff + n * 2048 + k * 1024); } while (0)
; #define PG8_MMA(ai, bj, At, Bt) do { __builtin_amdgcn_s_setprio(1); _Pragma("unroll") for (int m = 0; m < 4; ++m) _Pragma("unroll") for (int n = 0; n < 2; ++n) _Pragma("unroll") for (int k = 0; k < 2; ++k) \
;         acc[ai][bj][m][n] = __builtin_amdgcn_mfma_f32_16x16x32_bf16(Bt[n][k], At[m][k], acc[ai][bj][m][n], 0, 0, 0); __builtin_amdgcn_s_setprio(0); } while (0)
; #define PG8_WAIT_V(n) asm volatile("s_waitcnt vmcnt(" #n ")" ::: "memory")
; #define PG8_BAR __builtin_amdgcn_s_barrier()
; template <class Epi, class Sched, bool ALIGN_EPI = false, bool SP2 = false>
; __device__ __forceinline__ void gemm_phase(PG8_LAS unsigned char* lds, const Gemm g, const Sched& S, const Epi& E) {
;     ...
;         for (int t = 0; t < nt; t += 2) {
;             const bool last = (t == nt - 2);
;             const char* a1 = cA + (size_t)(t + 1) * kstep;
;             const char* a2 = last ? nA : cA + (size_t)(t + 2) * kstep; const char* b2 = last ? nB : cB + (size_t)(t + 2) * kstep;
;             const char* a3 = a2 + kstep; const char* b3 = b2 + kstep;
;             if (last && has_next) S.a_ready(nxt);
;             if constexpr (SP2) {
;             PG8_LDB(B0, 0, 0); PG8_LDB(B1, 0, 1); PG8_SCHED; PG8_LDA(At, 0, 0); PG8_STAGE(PG8_SA(1, 1), a1 + hstep, voffA);
;             PG8_WAIT_V(8); PG8_WAIT_L(0); PG8_BAR; PG8_MMA(0, 0, At, B0); PG8_MMA(0, 1, At, B1); PG8_BAR; PG8_SCHED;
;             PG8_LDA(At, 0, 1); PG8_STAGE(PG8_SB(0, 0), b2, voffB); PG8_STAGE(PG8_SB(0, 1), b2 + hstep, voffB); PG8_STAGE(PG8_SA(0, 0), a2, voffA);
;             PG8_WAIT_V(8); PG8_WAIT_L(0); PG8_BAR; PG8_MMA(1, 0, At, B0); PG8_MMA(1, 1, At, B1); PG8_BAR; PG8_SCHED;
.LBB0_1356:
	s_and_b64 vcc, exec, s[6:7]
	s_cbranch_vccz .Lk0_trail
.Lk0_lead:
	s_add_u32 s20, s18, 0x4000
	s_addc_u32 s21, s19, 0
	s_cmp_eq_u32 s68, 12
	s_cselect_b32 s64, s40, s20
	s_cselect_b32 s65, s11, s21
	s_cselect_b32 s62, s61, s66
	s_cselect_b32 s63, s9, s67
	s_add_u32 s20, s64, 0x8000
	s_addc_u32 s21, s65, 0
	s_add_i32 s69, 0, 0x10000
	s_add_i32 s72, 0, 0x14000
	v_add_u32_e32 v140, s69, v162
	v_add_u32_e32 v160, s72, v162
	ds_read_b128 v[128:131], v140
	ds_read_b128 v[132:135], v140 offset:1024
	ds_read_b128 v[136:139], v140 offset:2048
	ds_read_b128 v[140:143], v140 offset:3072
	ds_read_b128 v[156:159], v160
	ds_read_b128 v[164:167], v160 offset:1024
	ds_read_b128 v[168:171], v160 offset:2048
	ds_read_b128 v[172:175], v160 offset:3072
	s_add_i32 m0, s37, 0xc000
	ds_read_b128 v[176:179], v163
	ds_read_b128 v[180:183], v163 offset:1024
	ds_read_b128 v[184:187], v163 offset:2048
	ds_read_b128 v[188:191], v163 offset:3072
	ds_read_b128 v[192:195], v163 offset:4096
	ds_read_b128 v[196:199], v163 offset:5120
	ds_read_b128 v[200:203], v163 offset:6144
	ds_read_b128 v[204:207], v163 offset:7168
	global_load_lds_dwordx4 v152, s[18:19]
	s_add_i32 m0, s37, 0xe000
	s_nop 0
	global_load_lds_dwordx4 v154, s[18:19]
	s_waitcnt vmcnt(8)
	s_waitcnt lgkmcnt(0)
	s_barrier
	s_waitcnt lgkmcnt(0)
	v_mfma_f32_16x16x32_bf16 v[124:127], v[128:131], v[176:179], v[124:127]
	v_mfma_f32_16x16x32_bf16 v[120:123], v[136:139], v[176:179], v[120:123]
	v_mfma_f32_16x16x32_bf16 v[108:111], v[128:131], v[184:187], v[108:111]
	v_mfma_f32_16x16x32_bf16 v[104:107], v[136:139], v[184:187], v[104:107]
	v_mfma_f32_16x16x32_bf16 v[92:95], v[128:131], v[192:195], v[92:95]
	v_mfma_f32_16x16x32_bf16 v[88:91], v[136:139], v[192:195], v[88:91]
	v_mfma_f32_16x16x32_bf16 v[76:79], v[128:131], v[200:203], v[76:79]
	v_mfma_f32_16x16x32_bf16 v[72:75], v[136:139], v[200:203], v[72:75]
	v_mfma_f32_16x16x32_bf16 v[124:127], v[132:135], v[180:183], v[124:127]
	v_mfma_f32_16x16x32_bf16 v[120:123], v[140:143], v[180:183], v[120:123]
	v_mfma_f32_16x16x32_bf16 v[108:111], v[132:135], v[188:191], v[108:111]
	v_mfma_f32_16x16x32_bf16 v[104:107], v[140:143], v[188:191], v[104:107]
	v_mfma_f32_16x16x32_bf16 v[92:95], v[132:135], v[196:199], v[92:95]
	v_mfma_f32_16x16x32_bf16 v[88:91], v[140:143], v[196:199], v[88:91]
	v_mfma_f32_16x16x32_bf16 v[76:79], v[132:135], v[204:207], v[76:79]
	v_mfma_f32_16x16x32_bf16 v[72:75], v[140:143], v[204:207], v[72:75]
	v_mfma_f32_16x16x32_bf16 v[116:119], v[156:159], v[176:179], v[116:119]
	v_mfma_f32_16x16x32_bf16 v[112:115], v[168:171], v[176:179], v[112:115]
	v_mfma_f32_16x16x32_bf16 v[100:103], v[156:159], v[184:187], v[100:103]
	v_mfma_f32_16x16x32_bf16 v[96:99], v[168:171], v[184:187], v[96:99]
	v_mfma_f32_16x16x32_bf16 v[84:87], v[156:159], v[192:195], v[84:87]
	v_mfma_f32_16x16x32_bf16 v[80:83], v[168:171], v[192:195], v[80:83]
	v_mfma_f32_16x16x32_bf16 v[68:71], v[156:159], v[200:203], v[68:71]
	v_mfma_f32_16x16x32_bf16 v[64:67], v[168:171], v[200:203], v[64:67]
	v_mfma_f32_16x16x32_bf16 v[116:119], v[164:167], v[180:183], v[116:119]
	v_mfma_f32_16x16x32_bf16 v[112:115], v[172:175], v[180:183], v[112:115]
	v_mfma_f32_16x16x32_bf16 v[100:103], v[164:167], v[188:191], v[100:103]
	v_mfma_f32_16x16x32_bf16 v[96:99], v[172:175], v[188:191], v[96:99]
	v_mfma_f32_16x16x32_bf16 v[84:87], v[164:167], v[196:199], v[84:87]
	v_mfma_f32_16x16x32_bf16 v[80:83], v[172:175], v[196:199], v[80:83]
	v_mfma_f32_16x16x32_bf16 v[68:71], v[164:167], v[204:207], v[68:71]
	v_mfma_f32_16x16x32_bf16 v[64:67], v[172:175], v[204:207], v[64:67]
	s_add_i32 s69, s69, s30
	s_mov_b32 m0, s69
	ds_read_b128 v[176:179], v163 offset:16384
	ds_read_b128 v[180:183], v163 offset:17408
	ds_read_b128 v[184:187], v163 offset:18432
	ds_read_b128 v[188:191], v163 offset:19456
	ds_read_b128 v[192:195], v163 offset:20480
	ds_read_b128 v[196:199], v163 offset:21504
	ds_read_b128 v[200:203], v163 offset:22528
	ds_read_b128 v[204:207], v163 offset:23552
	global_load_lds_dwordx4 v148, s[62:63]
	s_add_i32 m0, s69, 0x2000
	s_add_u32 s70, s62, 0x4000
	s_addc_u32 s71, s63, 0
	s_add_i32 s69, s72, s30
	global_load_lds_dwordx4 v144, s[62:63]
	s_mov_b32 m0, s69
	s_nop 0
	global_load_lds_dwordx4 v148, s[70:71]
	s_add_i32 m0, s69, 0x2000
	s_nop 0
	global_load_lds_dwordx4 v144, s[70:71]
	s_mov_b32 m0, s37
	s_nop 0
	global_load_lds_dwordx4 v150, s[64:65]
	s_mov_b32 m0, s39
	s_nop 0
	global_load_lds_dwordx4 v146, s[64:65]
	s_waitcnt vmcnt(8)
	s_waitcnt lgkmcnt(0)
	s_barrier
; #define PG8_STAGE(bufoff, gbase, voff) do { _Pragma("unroll") for (int _i = 0; _i < 2; ++_i) \
;         __builtin_amdgcn_global_load_lds((const unsigned*)((const char*)(gbase) + (voff)[_i]), (PG8_LAS unsigned*)(lds + (bufoff) + ldsw + _i * 8192), 16, 0, 0); } while (0)
; #define PG8_LDA(dst, b, h) do { _Pragma("unroll") for (int m = 0; m < 4; ++m) _Pragma("unroll") for (int k = 0; k < 2; ++k) dst[m][k] = *(const PG8_LAS bf16x8*)(lds + PG8_SA(b, h) + aoff + m * 2048 + k * 1024); } while (0)
; #define PG8_LDB(dst, b, h) do { _Pragma("unroll") for (int n = 0; n < 2; ++n) _Pragma("unroll") for (int k = 0; k < 2; ++k) dst[n][k] = *(const PG8_LAS bf16x8*)(lds + PG8_SB(b, h) + boff + n * 2048 + k * 1024); } while (0)
; #define PG8_MMA(ai, bj, At, Bt) do { __builtin_amdgcn_s_setprio(1); _Pragma("unroll") for (int m = 0; m < 4; ++m) _Pragma("unroll") for (int n = 0; n < 2; ++n) _Pragma("unroll") for (int k = 0; k < 2; ++k) \
;         acc[ai][bj][m][n] = __builtin_amdgcn_mfma_f32_16x16x32_bf16(Bt[n][k], At[m][k], acc[ai][bj][m][n], 0, 0, 0); __builtin_amdgcn_s_setprio(0); } while (0)
; #define PG8_WAIT_V(n) asm volatile("s_waitcnt vmcnt(" #n ")" ::: "memory")
; #define PG8_WAIT_L(n) asm volatile("s_waitcnt lgkmcnt(" #n ")" ::: "memory")
; #define PG8_BAR __builtin_amdgcn_s_barrier()
; #define PG8_SCHED __builtin_amdgcn_sched_barrier(0)
; template <class Epi, class Sched, bool ALIGN_EPI = false, bool SP2 = false>
; __device__ __forceinline__ void gemm_phase(PG8_LAS unsigned char* lds, const Gemm g, const Sched& S, const Epi& E) {
;     ...
;             PG8_WAIT_V(8); PG8_WAIT_L(0); PG8_BAR; PG8_MMA(1, 0, At, B0); PG8_MMA(1, 1, At, B1); PG8_BAR; PG8_SCHED;
;             PG8_LDB(B0, 1, 0); PG8_LDB(B1, 1, 1); PG8_SCHED; PG8_LDA(At, 1, 0); PG8_STAGE(PG8_SA(0, 1), a2 + hstep, voffA);
;             PG8_WAIT_V(8); PG8_WAIT_L(0); PG8_BAR; PG8_MMA(0, 0, At, B0); PG8_MMA(0, 1, At, B1); PG8_BAR; PG8_SCHED;
;             PG8_LDA(At, 1, 1); PG8_STAGE(PG8_SB(1, 0), b3, voffB); PG8_STAGE(PG8_SB(1, 1), b3 + hstep, voffB); PG8_STAGE(PG8_SA(1, 0), a3, voffA);
;             PG8_WAIT_V(8); PG8_WAIT_L(0); PG8_BAR; PG8_MMA(1, 0, At, B0); PG8_MMA(1, 1, At, B1); PG8_BAR; PG8_SCHED;
	s_waitcnt lgkmcnt(0)
	v_mfma_f32_16x16x32_bf16 v[60:63], v[128:131], v[176:179], v[60:63]
	v_mfma_f32_16x16x32_bf16 v[56:59], v[136:139], v[176:179], v[56:59]
	v_mfma_f32_16x16x32_bf16 v[44:47], v[128:131], v[184:187], v[44:47]
	v_mfma_f32_16x16x32_bf16 v[40:43], v[136:139], v[184:187], v[40:43]
	v_mfma_f32_16x16x32_bf16 v[28:31], v[128:131], v[192:195], v[28:31]
	v_mfma_f32_16x16x32_bf16 v[24:27], v[136:139], v[192:195], v[24:27]
	v_mfma_f32_16x16x32_bf16 v[12:15], v[128:131], v[200:203], v[12:15]
	v_mfma_f32_16x16x32_bf16 v[8:11], v[136:139], v[200:203], v[8:11]
	v_mfma_f32_16x16x32_bf16 v[60:63], v[132:135], v[180:183], v[60:63]
	v_mfma_f32_16x16x32_bf16 v[56:59], v[140:143], v[180:183], v[56:59]
	v_mfma_f32_16x16x32_bf16 v[44:47], v[132:135], v[188:191], v[44:47]
	v_mfma_f32_16x16x32_bf16 v[40:43], v[140:143], v[188:191], v[40:43]
	v_mfma_f32_16x16x32_bf16 v[28:31], v[132:135], v[196:199], v[28:31]
	v_mfma_f32_16x16x32_bf16 v[24:27], v[140:143], v[196:199], v[24:27]
	v_mfma_f32_16x16x32_bf16 v[12:15], v[132:135], v[204:207], v[12:15]
	v_mfma_f32_16x16x32_bf16 v[8:11], v[140:143], v[204:207], v[8:11]
	v_mfma_f32_16x16x32_bf16 v[52:55], v[156:159], v[176:179], v[52:55]
	v_mfma_f32_16x16x32_bf16 v[48:51], v[168:171], v[176:179], v[48:51]
	v_mfma_f32_16x16x32_bf16 v[36:39], v[156:159], v[184:187], v[36:39]
	v_mfma_f32_16x16x32_bf16 v[32:35], v[168:171], v[184:187], v[32:35]
	v_mfma_f32_16x16x32_bf16 v[20:23], v[156:159], v[192:195], v[20:23]
	v_mfma_f32_16x16x32_bf16 v[16:19], v[168:171], v[192:195], v[16:19]
	v_mfma_f32_16x16x32_bf16 v[4:7], v[156:159], v[200:203], v[4:7]
	v_mfma_f32_16x16x32_bf16 v[0:3], v[168:171], v[200:203], v[0:3]
	v_mfma_f32_16x16x32_bf16 v[52:55], v[164:167], v[180:183], v[52:55]
	v_mfma_f32_16x16x32_bf16 v[48:51], v[172:175], v[180:183], v[48:51]
	v_mfma_f32_16x16x32_bf16 v[36:39], v[164:167], v[188:191], v[36:39]
	v_mfma_f32_16x16x32_bf16 v[32:35], v[172:175], v[188:191], v[32:35]
	v_mfma_f32_16x16x32_bf16 v[20:23], v[164:167], v[196:199], v[20:23]
	v_mfma_f32_16x16x32_bf16 v[16:19], v[172:175], v[196:199], v[16:19]
	v_mfma_f32_16x16x32_bf16 v[4:7], v[164:167], v[204:207], v[4:7]
	v_mfma_f32_16x16x32_bf16 v[0:3], v[172:175], v[204:207], v[0:3]
	s_add_i32 s69, 0, 0x18000
	s_add_i32 s70, 0, 0x1c000
	v_add_u32_e32 v140, s69, v162
	v_add_u32_e32 v160, s70, v162
	ds_read_b128 v[128:131], v140
	ds_read_b128 v[132:135], v140 offset:1024
	ds_read_b128 v[136:139], v140 offset:2048
	ds_read_b128 v[140:143], v140 offset:3072
	ds_read_b128 v[156:159], v160
	ds_read_b128 v[164:167], v160 offset:1024
	ds_read_b128 v[168:171], v160 offset:2048
	ds_read_b128 v[172:175], v160 offset:3072
	s_add_u32 s64, s64, 0x4000
	s_addc_u32 s65, s65, 0
	s_mov_b32 m0, s41
	ds_read_b128 v[176:179], v163 offset:32768
	ds_read_b128 v[180:183], v163 offset:33792
	ds_read_b128 v[184:187], v163 offset:34816
	ds_read_b128 v[188:191], v163 offset:35840
	ds_read_b128 v[192:195], v163 offset:36864
	ds_read_b128 v[196:199], v163 offset:37888
	ds_read_b128 v[200:203], v163 offset:38912
	ds_read_b128 v[204:207], v163 offset:39936
	global_load_lds_dwordx4 v150, s[64:65]
	s_mov_b32 m0, s42
	s_nop 0
	global_load_lds_dwordx4 v146, s[64:65]
	s_waitcnt vmcnt(8)
	s_waitcnt lgkmcnt(0)
	s_barrier
	s_waitcnt lgkmcnt(0)
	v_mfma_f32_16x16x32_bf16 v[124:127], v[128:131], v[176:179], v[124:127]
	v_mfma_f32_16x16x32_bf16 v[120:123], v[136:139], v[176:179], v[120:123]
	v_mfma_f32_16x16x32_bf16 v[108:111], v[128:131], v[184:187], v[108:111]
	v_mfma_f32_16x16x32_bf16 v[104:107], v[136:139], v[184:187], v[104:107]
	v_mfma_f32_16x16x32_bf16 v[92:95], v[128:131], v[192:195], v[92:95]
	v_mfma_f32_16x16x32_bf16 v[88:91], v[136:139], v[192:195], v[88:91]
	v_mfma_f32_16x16x32_bf16 v[76:79], v[128:131], v[200:203], v[76:79]
	v_mfma_f32_16x16x32_bf16 v[72:75], v[136:139], v[200:203], v[72:75]
	v_mfma_f32_16x16x32_bf16 v[124:127], v[132:135], v[180:183], v[124:127]
	v_mfma_f32_16x16x32_bf16 v[120:123], v[140:143], v[180:183], v[120:123]
	v_mfma_f32_16x16x32_bf16 v[108:111], v[132:135], v[188:191], v[108:111]
	v_mfma_f32_16x16x32_bf16 v[104:107], v[140:143], v[188:191], v[104:107]
	v_mfma_f32_16x16x32_bf16 v[92:95], v[132:135], v[196:199], v[92:95]
	v_mfma_f32_16x16x32_bf16 v[88:91], v[140:143], v[196:199], v[88:91]
	v_mfma_f32_16x16x32_bf16 v[76:79], v[132:135], v[204:207], v[76:79]
	v_mfma_f32_16x16x32_bf16 v[72:75], v[140:143], v[204:207], v[72:75]
	v_mfma_f32_16x16x32_bf16 v[116:119], v[156:159], v[176:179], v[116:119]
	v_mfma_f32_16x16x32_bf16 v[112:115], v[168:171], v[176:179], v[112:115]
	v_mfma_f32_16x16x32_bf16 v[100:103], v[156:159], v[184:187], v[100:103]
	v_mfma_f32_16x16x32_bf16 v[96:99], v[168:171], v[184:187], v[96:99]
	v_mfma_f32_16x16x32_bf16 v[84:87], v[156:159], v[192:195], v[84:87]
	v_mfma_f32_16x16x32_bf16 v[80:83], v[168:171], v[192:195], v[80:83]
	v_mfma_f32_16x16x32_bf16 v[68:71], v[156:159], v[200:203], v[68:71]
	v_mfma_f32_16x16x32_bf16 v[64:67], v[168:171], v[200:203], v[64:67]
	v_mfma_f32_16x16x32_bf16 v[116:119], v[164:167], v[180:183], v[116:119]
	v_mfma_f32_16x16x32_bf16 v[112:115], v[172:175], v[180:183], v[112:115]
	v_mfma_f32_16x16x32_bf16 v[100:103], v[164:167], v[188:191], v[100:103]
	v_mfma_f32_16x16x32_bf16 v[96:99], v[172:175], v[188:191], v[96:99]
	v_mfma_f32_16x16x32_bf16 v[84:87], v[164:167], v[196:199], v[84:87]
	v_mfma_f32_16x16x32_bf16 v[80:83], v[172:175], v[196:199], v[80:83]
	v_mfma_f32_16x16x32_bf16 v[68:71], v[164:167], v[204:207], v[68:71]
	v_mfma_f32_16x16x32_bf16 v[64:67], v[172:175], v[204:207], v[64:67]
	s_add_u32 s64, s62, 0x8000
	s_addc_u32 s65, s63, 0
	s_add_i32 s69, s69, s30
	s_mov_b32 m0, s69
	ds_read_b128 v[176:179], v163 offset:49152
	ds_read_b128 v[180:183], v163 offset:50176
	ds_read_b128 v[184:187], v163 offset:51200
	ds_read_b128 v[188:191], v163 offset:52224
	ds_read_b128 v[192:195], v163 offset:53248
	ds_read_b128 v[196:199], v163 offset:54272
	ds_read_b128 v[200:203], v163 offset:55296
	ds_read_b128 v[204:207], v163 offset:56320
	global_load_lds_dwordx4 v148, s[64:65]
	s_add_i32 m0, s69, 0x2000
	s_add_u32 s62, s62, 0xc000
	v_lshl_add_u64 v[160:161], s[64:65], 0, v[144:145]
	s_addc_u32 s63, s63, 0
	s_add_i32 s64, s70, s30
	global_load_lds_dwordx4 v[160:161], off
	s_mov_b32 m0, s64
	s_nop 0
	global_load_lds_dwordx4 v148, s[62:63]
	s_add_i32 m0, s64, 0x2000
	s_nop 0
	global_load_lds_dwordx4 v144, s[62:63]
	s_mov_b32 m0, s54
	s_nop 0
	global_load_lds_dwordx4 v150, s[20:21]
	s_mov_b32 m0, s55
	s_nop 0
	global_load_lds_dwordx4 v146, s[20:21]
	s_waitcnt vmcnt(8)
	s_waitcnt lgkmcnt(0)
	s_barrier
; #define PG8_STAGE(bufoff, gbase, voff) do { _Pragma("unroll") for (int _i = 0; _i < 2; ++_i) \
;         __builtin_amdgcn_global_load_lds((const unsigned*)((const char*)(gbase) + (voff)[_i]), (PG8_LAS unsigned*)(lds + (bufoff) + ldsw + _i * 8192), 16, 0, 0); } while (0)
; #define PG8_LDA(dst, b, h) do { _Pragma("unroll") for (int m = 0; m < 4; ++m) _Pragma("unroll") for (int k = 0; k < 2; ++k) dst[m][k] = *(const PG8_LAS bf16x8*)(lds + PG8_SA(b, h) + aoff + m * 2048 + k * 1024); } while (0)
; #define PG8_LDB(dst, b, h) do { _Pragma("unroll") for (int n = 0; n < 2; ++n) _Pragma("unroll") for (int k = 0; k < 2; ++k) dst[n][k] = *(const PG8_LAS bf16x8*)(lds + PG8_SB(b, h) + boff + n * 2048 + k * 1024); } while (0)
; template <class Epi, class Sched, bool ALIGN_EPI = false, bool SP2 = false>
; __device__ __forceinline__ void gemm_phase(PG8_LAS unsigned char* lds, const Gemm g, const Sched& S, const Epi& E) {
;     ...
;         for (int t = 0; t < nt; t += 2) {
;             const bool last = (t == nt - 2);
;             const char* a1 = cA + (size_t)(t + 1) * kstep;
;             const char* a2 = last ? nA : cA + (size_t)(t + 2) * kstep; const char* b2 = last ? nB : cB + (size_t)(t + 2) * kstep;
;             const char* a3 = a2 + kstep; const char* b3 = b2 + kstep;
;             if (last && has_next) S.a_ready(nxt);
;             if constexpr (SP2) {
;             PG8_LDB(B0, 0, 0); PG8_LDB(B1, 0, 1); PG8_SCHED; PG8_LDA(At, 0, 0); PG8_STAGE(PG8_SA(1, 1), a1 + hstep, voffA);
;             PG8_WAIT_V(8); PG8_WAIT_L(0); PG8_BAR; PG8_MMA(0, 0, At, B0); PG8_MMA(0, 1, At, B1); PG8_BAR; PG8_SCHED;
;             PG8_LDA(At, 0, 1); PG8_STAGE(PG8_SB(0, 0), b2, voffB); PG8_STAGE(PG8_SB(0, 1), b2 + hstep, voffB); PG8_STAGE(PG8_SA(0, 0), a2, voffA);
;             PG8_WAIT_V(8); PG8_WAIT_L(0); PG8_BAR; PG8_MMA(1, 0, At, B0); PG8_MMA(1, 1, At, B1); PG8_BAR; PG8_SCHED;
;             PG8_LDB(B0, 1, 0); PG8_LDB(B1, 1, 1); PG8_SCHED; PG8_LDA(At, 1, 0); PG8_STAGE(PG8_SA(0, 1), a2 + hstep, voffA);
;             PG8_WAIT_V(8); PG8_WAIT_L(0); PG8_BAR; PG8_MMA(0, 0, At, B0); PG8_MMA(0, 1, At, B1); PG8_BAR; PG8_SCHED;
;             PG8_LDA(At, 1, 1); PG8_STAGE(PG8_SB(1, 0), b3, voffB); PG8_STAGE(PG8_SB(1, 1), b3 + hstep, voffB); PG8_STAGE(PG8_SA(1, 0), a3, voffA);
;             PG8_WAIT_V(8); PG8_WAIT_L(0); PG8_BAR; PG8_MMA(1, 0, At, B0); PG8_MMA(1, 1, At, B1); PG8_BAR; PG8_SCHED;
	s_waitcnt lgkmcnt(0)
	v_mfma_f32_16x16x32_bf16 v[60:63], v[128:131], v[176:179], v[60:63]
	v_mfma_f32_16x16x32_bf16 v[56:59], v[136:139], v[176:179], v[56:59]
	v_mfma_f32_16x16x32_bf16 v[44:47], v[128:131], v[184:187], v[44:47]
	v_mfma_f32_16x16x32_bf16 v[40:43], v[136:139], v[184:187], v[40:43]
	v_mfma_f32_16x16x32_bf16 v[28:31], v[128:131], v[192:195], v[28:31]
	v_mfma_f32_16x16x32_bf16 v[24:27], v[136:139], v[192:195], v[24:27]
	v_mfma_f32_16x16x32_bf16 v[12:15], v[128:131], v[200:203], v[12:15]
	v_mfma_f32_16x16x32_bf16 v[8:11], v[136:139], v[200:203], v[8:11]
	v_mfma_f32_16x16x32_bf16 v[60:63], v[132:135], v[180:183], v[60:63]
	v_mfma_f32_16x16x32_bf16 v[56:59], v[140:143], v[180:183], v[56:59]
	v_mfma_f32_16x16x32_bf16 v[44:47], v[132:135], v[188:191], v[44:47]
	v_mfma_f32_16x16x32_bf16 v[40:43], v[140:143], v[188:191], v[40:43]
	v_mfma_f32_16x16x32_bf16 v[28:31], v[132:135], v[196:199], v[28:31]
	v_mfma_f32_16x16x32_bf16 v[24:27], v[140:143], v[196:199], v[24:27]
	v_mfma_f32_16x16x32_bf16 v[12:15], v[132:135], v[204:207], v[12:15]
	v_mfma_f32_16x16x32_bf16 v[8:11], v[140:143], v[204:207], v[8:11]
	v_mfma_f32_16x16x32_bf16 v[52:55], v[156:159], v[176:179], v[52:55]
	v_mfma_f32_16x16x32_bf16 v[48:51], v[168:171], v[176:179], v[48:51]
	v_mfma_f32_16x16x32_bf16 v[36:39], v[156:159], v[184:187], v[36:39]
	v_mfma_f32_16x16x32_bf16 v[32:35], v[168:171], v[184:187], v[32:35]
	v_mfma_f32_16x16x32_bf16 v[20:23], v[156:159], v[192:195], v[20:23]
	v_mfma_f32_16x16x32_bf16 v[16:19], v[168:171], v[192:195], v[16:19]
	v_mfma_f32_16x16x32_bf16 v[4:7], v[156:159], v[200:203], v[4:7]
	v_mfma_f32_16x16x32_bf16 v[0:3], v[168:171], v[200:203], v[0:3]
	v_mfma_f32_16x16x32_bf16 v[52:55], v[164:167], v[180:183], v[52:55]
	v_mfma_f32_16x16x32_bf16 v[48:51], v[172:175], v[180:183], v[48:51]
	v_mfma_f32_16x16x32_bf16 v[36:39], v[164:167], v[188:191], v[36:39]
	v_mfma_f32_16x16x32_bf16 v[32:35], v[172:175], v[188:191], v[32:35]
	v_mfma_f32_16x16x32_bf16 v[20:23], v[164:167], v[196:199], v[20:23]
	v_mfma_f32_16x16x32_bf16 v[16:19], v[172:175], v[196:199], v[16:19]
	v_mfma_f32_16x16x32_bf16 v[4:7], v[164:167], v[204:207], v[4:7]
	v_mfma_f32_16x16x32_bf16 v[0:3], v[172:175], v[204:207], v[0:3]
	s_add_i32 s68, s68, 2
	s_add_u32 s18, s18, 0x10000
	s_addc_u32 s19, s19, 0
	s_add_u32 s66, s66, 0x10000
	s_addc_u32 s67, s67, 0
	s_cmp_gt_u32 s68, 13
	s_cbranch_scc0 .Lk0_lead
	s_branch .Lk0_done
.Lk0_trail:
	s_add_u32 s20, s18, 0x4000
	s_addc_u32 s21, s19, 0
	s_cmp_eq_u32 s68, 12
	s_cselect_b32 s64, s40, s20
	s_cselect_b32 s65, s11, s21
	s_cselect_b32 s62, s61, s66
	s_cselect_b32 s63, s9, s67
	s_add_u32 s20, s64, 0x8000
	s_addc_u32 s21, s65, 0
	s_add_i32 s69, 0, 0x10000
	s_add_i32 s72, 0, 0x14000
	v_add_u32_e32 v140, s69, v162
	v_add_u32_e32 v160, s72, v162
	ds_read_b128 v[128:131], v140
	ds_read_b128 v[132:135], v140 offset:1024
	ds_read_b128 v[136:139], v140 offset:2048
	ds_read_b128 v[140:143], v140 offset:3072
	ds_read_b128 v[156:159], v160
	ds_read_b128 v[164:167], v160 offset:1024
	ds_read_b128 v[168:171], v160 offset:2048
	ds_read_b128 v[172:175], v160 offset:3072
	s_add_i32 m0, s37, 0xc000
	ds_read_b128 v[176:179], v163
	ds_read_b128 v[180:183], v163 offset:1024
	ds_read_b128 v[184:187], v163 offset:2048
	ds_read_b128 v[188:191], v163 offset:3072
	ds_read_b128 v[192:195], v163 offset:4096
	ds_read_b128 v[196:199], v163 offset:5120
	ds_read_b128 v[200:203], v163 offset:6144
	ds_read_b128 v[204:207], v163 offset:7168
	global_load_lds_dwordx4 v152, s[18:19]
	s_add_i32 m0, s37, 0xe000
	s_nop 0
	global_load_lds_dwordx4 v154, s[18:19]
	s_waitcnt vmcnt(8)
	s_waitcnt lgkmcnt(0)
	s_waitcnt lgkmcnt(0)
	v_mfma_f32_16x16x32_bf16 v[124:127], v[128:131], v[176:179], v[124:127]
	v_mfma_f32_16x16x32_bf16 v[120:123], v[136:139], v[176:179], v[120:123]
	v_mfma_f32_16x16x32_bf16 v[108:111], v[128:131], v[184:187], v[108:111]
	v_mfma_f32_16x16x32_bf16 v[104:107], v[136:139], v[184:187], v[104:107]
	v_mfma_f32_16x16x32_bf16 v[92:95], v[128:131], v[192:195], v[92:95]
	v_mfma_f32_16x16x32_bf16 v[88:91], v[136:139], v[192:195], v[88:91]
	v_mfma_f32_16x16x32_bf16 v[76:79], v[128:131], v[200:203], v[76:79]
	v_mfma_f32_16x16x32_bf16 v[72:75], v[136:139], v[200:203], v[72:75]
	v_mfma_f32_16x16x32_bf16 v[124:127], v[132:135], v[180:183], v[124:127]
	v_mfma_f32_16x16x32_bf16 v[120:123], v[140:143], v[180:183], v[120:123]
	v_mfma_f32_16x16x32_bf16 v[108:111], v[132:135], v[188:191], v[108:111]
	v_mfma_f32_16x16x32_bf16 v[104:107], v[140:143], v[188:191], v[104:107]
	v_mfma_f32_16x16x32_bf16 v[92:95], v[132:135], v[196:199], v[92:95]
	v_mfma_f32_16x16x32_bf16 v[88:91], v[140:143], v[196:199], v[88:91]
	v_mfma_f32_16x16x32_bf16 v[76:79], v[132:135], v[204:207], v[76:79]
	v_mfma_f32_16x16x32_bf16 v[72:75], v[140:143], v[204:207], v[72:75]
	v_mfma_f32_16x16x32_bf16 v[116:119], v[156:159], v[176:179], v[116:119]
	v_mfma_f32_16x16x32_bf16 v[112:115], v[168:171], v[176:179], v[112:115]
	v_mfma_f32_16x16x32_bf16 v[100:103], v[156:159], v[184:187], v[100:103]
	v_mfma_f32_16x16x32_bf16 v[96:99], v[168:171], v[184:187], v[96:99]
	v_mfma_f32_16x16x32_bf16 v[84:87], v[156:159], v[192:195], v[84:87]
	v_mfma_f32_16x16x32_bf16 v[80:83], v[168:171], v[192:195], v[80:83]
	v_mfma_f32_16x16x32_bf16 v[68:71], v[156:159], v[200:203], v[68:71]
	v_mfma_f32_16x16x32_bf16 v[64:67], v[168:171], v[200:203], v[64:67]
	v_mfma_f32_16x16x32_bf16 v[116:119], v[164:167], v[180:183], v[116:119]
	v_mfma_f32_16x16x32_bf16 v[112:115], v[172:175], v[180:183], v[112:115]
	v_mfma_f32_16x16x32_bf16 v[100:103], v[164:167], v[188:191], v[100:103]
	v_mfma_f32_16x16x32_bf16 v[96:99], v[172:175], v[188:191], v[96:99]
	v_mfma_f32_16x16x32_bf16 v[84:87], v[164:167], v[196:199], v[84:87]
	v_mfma_f32_16x16x32_bf16 v[80:83], v[172:175], v[196:199], v[80:83]
	v_mfma_f32_16x16x32_bf16 v[68:71], v[164:167], v[204:207], v[68:71]
	v_mfma_f32_16x16x32_bf16 v[64:67], v[172:175], v[204:207], v[64:67]
	s_barrier
; #define PG8_STAGE(bufoff, gbase, voff) do { _Pragma("unroll") for (int _i = 0; _i < 2; ++_i) \
;         __builtin_amdgcn_global_load_lds((const unsigned*)((const char*)(gbase) + (voff)[_i]), (PG8_LAS unsigned*)(lds + (bufoff) + ldsw + _i * 8192), 16, 0, 0); } while (0)
; #define PG8_LDA(dst, b, h) do { _Pragma("unroll") for (int m = 0; m < 4; ++m) _Pragma("unroll") for (int k = 0; k < 2; ++k) dst[m][k] = *(const PG8_LAS bf16x8*)(lds + PG8_SA(b, h) + aoff + m * 2048 + k * 1024); } while (0)
; #define PG8_LDB(dst, b, h) do { _Pragma("unroll") for (int n = 0; n < 2; ++n) _Pragma("unroll") for (int k = 0; k < 2; ++k) dst[n][k] = *(const PG8_LAS bf16x8*)(lds + PG8_SB(b, h) + boff + n * 2048 + k * 1024); } while (0)
; #define PG8_MMA(ai, bj, At, Bt) do { __builtin_amdgcn_s_setprio(1); _Pragma("unroll") for (int m = 0; m < 4; ++m) _Pragma("unroll") for (int n = 0; n < 2; ++n) _Pragma("unroll") for (int k = 0; k < 2; ++k) \
;         acc[ai][bj][m][n] = __builtin_amdgcn_mfma_f32_16x16x32_bf16(Bt[n][k], At[m][k], acc[ai][bj][m][n], 0, 0, 0); __builtin_amdgcn_s_setprio(0); } while (0)
; #define PG8_WAIT_V(n) asm volatile("s_waitcnt vmcnt(" #n ")" ::: "memory")
; #define PG8_WAIT_L(n) asm volatile("s_waitcnt lgkmcnt(" #n ")" ::: "memory")
; #define PG8_BAR __builtin_amdgcn_s_barrier()
; #define PG8_SCHED __builtin_amdgcn_sched_barrier(0)
; template <class Epi, class Sched, bool ALIGN_EPI = false, bool SP2 = false>
; __device__ __forceinline__ void gemm_phase(PG8_LAS unsigned char* lds, const Gemm g, const Sched& S, const Epi& E) {
;     ...
;             PG8_LDA(At, 0, 1); PG8_STAGE(PG8_SB(0, 0), b2, voffB); PG8_STAGE(PG8_SB(0, 1), b2 + hstep, voffB); PG8_STAGE(PG8_SA(0, 0), a2, voffA);
;             PG8_WAIT_V(8); PG8_WAIT_L(0); PG8_BAR; PG8_MMA(1, 0, At, B0); PG8_MMA(1, 1, At, B1); PG8_BAR; PG8_SCHED;
;             PG8_LDB(B0, 1, 0); PG8_LDB(B1, 1, 1); PG8_SCHED; PG8_LDA(At, 1, 0); PG8_STAGE(PG8_SA(0, 1), a2 + hstep, voffA);
;             PG8_WAIT_V(8); PG8_WAIT_L(0); PG8_BAR; PG8_MMA(0, 0, At, B0); PG8_MMA(0, 1, At, B1); PG8_BAR; PG8_SCHED;
;             PG8_LDA(At, 1, 1); PG8_STAGE(PG8_SB(1, 0), b3, voffB); PG8_STAGE(PG8_SB(1, 1), b3 + hstep, voffB); PG8_STAGE(PG8_SA(1, 0), a3, voffA);
;             PG8_WAIT_V(8); PG8_WAIT_L(0); PG8_BAR; PG8_MMA(1, 0, At, B0); PG8_MMA(1, 1, At, B1); PG8_BAR; PG8_SCHED;
	s_add_i32 s69, s69, s30
	s_mov_b32 m0, s69
	ds_read_b128 v[176:179], v163 offset:16384
	ds_read_b128 v[180:183], v163 offset:17408
	ds_read_b128 v[184:187], v163 offset:18432
	ds_read_b128 v[188:191], v163 offset:19456
	ds_read_b128 v[192:195], v163 offset:20480
	ds_read_b128 v[196:199], v163 offset:21504
	ds_read_b128 v[200:203], v163 offset:22528
	ds_read_b128 v[204:207], v163 offset:23552
	global_load_lds_dwordx4 v148, s[62:63]
	s_add_i32 m0, s69, 0x2000
	s_add_u32 s70, s62, 0x4000
	s_addc_u32 s71, s63, 0
	s_add_i32 s69, s72, s30
	global_load_lds_dwordx4 v144, s[62:63]
	s_mov_b32 m0, s69
	s_nop 0
	global_load_lds_dwordx4 v148, s[70:71]
	s_add_i32 m0, s69, 0x2000
	s_nop 0
	global_load_lds_dwordx4 v144, s[70:71]
	s_mov_b32 m0, s37
	s_nop 0
	global_load_lds_dwordx4 v150, s[64:65]
	s_mov_b32 m0, s39
	s_nop 0
	global_load_lds_dwordx4 v146, s[64:65]
	s_waitcnt vmcnt(8)
	s_waitcnt lgkmcnt(0)
	s_waitcnt lgkmcnt(0)
	v_mfma_f32_16x16x32_bf16 v[60:63], v[128:131], v[176:179], v[60:63]
	v_mfma_f32_16x16x32_bf16 v[56:59], v[136:139], v[176:179], v[56:59]
	v_mfma_f32_16x16x32_bf16 v[44:47], v[128:131], v[184:187], v[44:47]
	v_mfma_f32_16x16x32_bf16 v[40:43], v[136:139], v[184:187], v[40:43]
	v_mfma_f32_16x16x32_bf16 v[28:31], v[128:131], v[192:195], v[28:31]
	v_mfma_f32_16x16x32_bf16 v[24:27], v[136:139], v[192:195], v[24:27]
	v_mfma_f32_16x16x32_bf16 v[12:15], v[128:131], v[200:203], v[12:15]
	v_mfma_f32_16x16x32_bf16 v[8:11], v[136:139], v[200:203], v[8:11]
	v_mfma_f32_16x16x32_bf16 v[60:63], v[132:135], v[180:183], v[60:63]
	v_mfma_f32_16x16x32_bf16 v[56:59], v[140:143], v[180:183], v[56:59]
	v_mfma_f32_16x16x32_bf16 v[44:47], v[132:135], v[188:191], v[44:47]
	v_mfma_f32_16x16x32_bf16 v[40:43], v[140:143], v[188:191], v[40:43]
	v_mfma_f32_16x16x32_bf16 v[28:31], v[132:135], v[196:199], v[28:31]
	v_mfma_f32_16x16x32_bf16 v[24:27], v[140:143], v[196:199], v[24:27]
	v_mfma_f32_16x16x32_bf16 v[12:15], v[132:135], v[204:207], v[12:15]
	v_mfma_f32_16x16x32_bf16 v[8:11], v[140:143], v[204:207], v[8:11]
	v_mfma_f32_16x16x32_bf16 v[52:55], v[156:159], v[176:179], v[52:55]
	v_mfma_f32_16x16x32_bf16 v[48:51], v[168:171], v[176:179], v[48:51]
	v_mfma_f32_16x16x32_bf16 v[36:39], v[156:159], v[184:187], v[36:39]
	v_mfma_f32_16x16x32_bf16 v[32:35], v[168:171], v[184:187], v[32:35]
	v_mfma_f32_16x16x32_bf16 v[20:23], v[156:159], v[192:195], v[20:23]
	v_mfma_f32_16x16x32_bf16 v[16:19], v[168:171], v[192:195], v[16:19]
	v_mfma_f32_16x16x32_bf16 v[4:7], v[156:159], v[200:203], v[4:7]
	v_mfma_f32_16x16x32_bf16 v[0:3], v[168:171], v[200:203], v[0:3]
	v_mfma_f32_16x16x32_bf16 v[52:55], v[164:167], v[180:183], v[52:55]
	v_mfma_f32_16x16x32_bf16 v[48:51], v[172:175], v[180:183], v[48:51]
	v_mfma_f32_16x16x32_bf16 v[36:39], v[164:167], v[188:191], v[36:39]
	v_mfma_f32_16x16x32_bf16 v[32:35], v[172:175], v[188:191], v[32:35]
	v_mfma_f32_16x16x32_bf16 v[20:23], v[164:167], v[196:199], v[20:23]
	v_mfma_f32_16x16x32_bf16 v[16:19], v[172:175], v[196:199], v[16:19]
	v_mfma_f32_16x16x32_bf16 v[4:7], v[164:167], v[204:207], v[4:7]
	v_mfma_f32_16x16x32_bf16 v[0:3], v[172:175], v[204:207], v[0:3]
	s_barrier
	s_add_i32 s69, 0, 0x18000
	s_add_i32 s70, 0, 0x1c000
	v_add_u32_e32 v140, s69, v162
	v_add_u32_e32 v160, s70, v162
	ds_read_b128 v[128:131], v140
	ds_read_b128 v[132:135], v140 offset:1024
	ds_read_b128 v[136:139], v140 offset:2048
	ds_read_b128 v[140:143], v140 offset:3072
	ds_read_b128 v[156:159], v160
	ds_read_b128 v[164:167], v160 offset:1024
	ds_read_b128 v[168:171], v160 offset:2048
	ds_read_b128 v[172:175], v160 offset:3072
	s_add_u32 s64, s64, 0x4000
	s_addc_u32 s65, s65, 0
	s_mov_b32 m0, s41
	ds_read_b128 v[176:179], v163 offset:32768
	ds_read_b128 v[180:183], v163 offset:33792
	ds_read_b128 v[184:187], v163 offset:34816
	ds_read_b128 v[188:191], v163 offset:35840
	ds_read_b128 v[192:195], v163 offset:36864
	ds_read_b128 v[196:199], v163 offset:37888
	ds_read_b128 v[200:203], v163 offset:38912
	ds_read_b128 v[204:207], v163 offset:39936
	global_load_lds_dwordx4 v150, s[64:65]
	s_mov_b32 m0, s42
	s_nop 0
	global_load_lds_dwordx4 v146, s[64:65]
	s_waitcnt vmcnt(8)
	s_waitcnt lgkmcnt(0)
	s_waitcnt lgkmcnt(0)
	v_mfma_f32_16x16x32_bf16 v[124:127], v[128:131], v[176:179], v[124:127]
	v_mfma_f32_16x16x32_bf16 v[120:123], v[136:139], v[176:179], v[120:123]
	v_mfma_f32_16x16x32_bf16 v[108:111], v[128:131], v[184:187], v[108:111]
	v_mfma_f32_16x16x32_bf16 v[104:107], v[136:139], v[184:187], v[104:107]
	v_mfma_f32_16x16x32_bf16 v[92:95], v[128:131], v[192:195], v[92:95]
	v_mfma_f32_16x16x32_bf16 v[88:91], v[136:139], v[192:195], v[88:91]
	v_mfma_f32_16x16x32_bf16 v[76:79], v[128:131], v[200:203], v[76:79]
	v_mfma_f32_16x16x32_bf16 v[72:75], v[136:139], v[200:203], v[72:75]
	v_mfma_f32_16x16x32_bf16 v[124:127], v[132:135], v[180:183], v[124:127]
	v_mfma_f32_16x16x32_bf16 v[120:123], v[140:143], v[180:183], v[120:123]
	v_mfma_f32_16x16x32_bf16 v[108:111], v[132:135], v[188:191], v[108:111]
	v_mfma_f32_16x16x32_bf16 v[104:107], v[140:143], v[188:191], v[104:107]
	v_mfma_f32_16x16x32_bf16 v[92:95], v[132:135], v[196:199], v[92:95]
	v_mfma_f32_16x16x32_bf16 v[88:91], v[140:143], v[196:199], v[88:91]
	v_mfma_f32_16x16x32_bf16 v[76:79], v[132:135], v[204:207], v[76:79]
	v_mfma_f32_16x16x32_bf16 v[72:75], v[140:143], v[204:207], v[72:75]
	v_mfma_f32_16x16x32_bf16 v[116:119], v[156:159], v[176:179], v[116:119]
	v_mfma_f32_16x16x32_bf16 v[112:115], v[168:171], v[176:179], v[112:115]
	v_mfma_f32_16x16x32_bf16 v[100:103], v[156:159], v[184:187], v[100:103]
	v_mfma_f32_16x16x32_bf16 v[96:99], v[168:171], v[184:187], v[96:99]
	v_mfma_f32_16x16x32_bf16 v[84:87], v[156:159], v[192:195], v[84:87]
	v_mfma_f32_16x16x32_bf16 v[80:83], v[168:171], v[192:195], v[80:83]
	v_mfma_f32_16x16x32_bf16 v[68:71], v[156:159], v[200:203], v[68:71]
	v_mfma_f32_16x16x32_bf16 v[64:67], v[168:171], v[200:203], v[64:67]
	v_mfma_f32_16x16x32_bf16 v[116:119], v[164:167], v[180:183], v[116:119]
	v_mfma_f32_16x16x32_bf16 v[112:115], v[172:175], v[180:183], v[112:115]
	v_mfma_f32_16x16x32_bf16 v[100:103], v[164:167], v[188:191], v[100:103]
	v_mfma_f32_16x16x32_bf16 v[96:99], v[172:175], v[188:191], v[96:99]
	v_mfma_f32_16x16x32_bf16 v[84:87], v[164:167], v[196:199], v[84:87]
	v_mfma_f32_16x16x32_bf16 v[80:83], v[172:175], v[196:199], v[80:83]
	v_mfma_f32_16x16x32_bf16 v[68:71], v[164:167], v[204:207], v[68:71]
	v_mfma_f32_16x16x32_bf16 v[64:67], v[172:175], v[204:207], v[64:67]
	s_barrier
; #define PG8_STAGE(bufoff, gbase, voff) do { _Pragma("unroll") for (int _i = 0; _i < 2; ++_i) \
;         __builtin_amdgcn_global_load_lds((const unsigned*)((const char*)(gbase) + (voff)[_i]), (PG8_LAS unsigned*)(lds + (bufoff) + ldsw + _i * 8192), 16, 0, 0); } while (0)
; #define PG8_LDA(dst, b, h) do { _Pragma("unroll") for (int m = 0; m < 4; ++m) _Pragma("unroll") for (int k = 0; k < 2; ++k) dst[m][k] = *(const PG8_LAS bf16x8*)(lds + PG8_SA(b, h) + aoff + m * 2048 + k * 1024); } while (0)
; #define PG8_MMA(ai, bj, At, Bt) do { __builtin_amdgcn_s_setprio(1); _Pragma("unroll") for (int m = 0; m < 4; ++m) _Pragma("unroll") for (int n = 0; n < 2; ++n) _Pragma("unroll") for (int k = 0; k < 2; ++k) \
;         acc[ai][bj][m][n] = __builtin_amdgcn_mfma_f32_16x16x32_bf16(Bt[n][k], At[m][k], acc[ai][bj][m][n], 0, 0, 0); __builtin_amdgcn_s_setprio(0); } while (0)
; #define PG8_WAIT_V(n) asm volatile("s_waitcnt vmcnt(" #n ")" ::: "memory")
; #define PG8_WAIT_L(n) asm volatile("s_waitcnt lgkmcnt(" #n ")" ::: "memory")
; #define PG8_BAR __builtin_amdgcn_s_barrier()
; #define PG8_SCHED __builtin_amdgcn_sched_barrier(0)
; template <class Epi, class Sched, bool ALIGN_EPI = false, bool SP2 = false>
; __device__ __forceinline__ void gemm_phase(PG8_LAS unsigned char* lds, const Gemm g, const Sched& S, const Epi& E) {
;     ...
;             PG8_LDA(At, 1, 1); PG8_STAGE(PG8_SB(1, 0), b3, voffB); PG8_STAGE(PG8_SB(1, 1), b3 + hstep, voffB); PG8_STAGE(PG8_SA(1, 0), a3, voffA);
;             PG8_WAIT_V(8); PG8_WAIT_L(0); PG8_BAR; PG8_MMA(1, 0, At, B0); PG8_MMA(1, 1, At, B1); PG8_BAR; PG8_SCHED;
	s_add_u32 s64, s62, 0x8000
	s_addc_u32 s65, s63, 0
	s_add_i32 s69, s69, s30
	s_mov_b32 m0, s69
	ds_read_b128 v[176:179], v163 offset:49152
	ds_read_b128 v[180:183], v163 offset:50176
	ds_read_b128 v[184:187], v163 offset:51200
	ds_read_b128 v[188:191], v163 offset:52224
	ds_read_b128 v[192:195], v163 offset:53248
	ds_read_b128 v[196:199], v163 offset:54272
	ds_read_b128 v[200:203], v163 offset:55296
	ds_read_b128 v[204:207], v163 offset:56320
	global_load_lds_dwordx4 v148, s[64:65]
	s_add_i32 m0, s69, 0x2000
	s_add_u32 s62, s62, 0xc000
	v_lshl_add_u64 v[160:161], s[64:65], 0, v[144:145]
	s_addc_u32 s63, s63, 0
	s_add_i32 s64, s70, s30
	global_load_lds_dwordx4 v[160:161], off
	s_mov_b32 m0, s64
	s_nop 0
	global_load_lds_dwordx4 v148, s[62:63]
	s_add_i32 m0, s64, 0x2000
	s_nop 0
	global_load_lds_dwordx4 v144, s[62:63]
	s_mov_b32 m0, s54
	s_nop 0
	global_load_lds_dwordx4 v150, s[20:21]
	s_mov_b32 m0, s55
	s_nop 0
	global_load_lds_dwordx4 v146, s[20:21]
	s_waitcnt vmcnt(8)
	s_waitcnt lgkmcnt(0)
	s_waitcnt lgkmcnt(0)
	v_mfma_f32_16x16x32_bf16 v[60:63], v[128:131], v[176:179], v[60:63]
	v_mfma_f32_16x16x32_bf16 v[56:59], v[136:139], v[176:179], v[56:59]
	v_mfma_f32_16x16x32_bf16 v[44:47], v[128:131], v[184:187], v[44:47]
	v_mfma_f32_16x16x32_bf16 v[40:43], v[136:139], v[184:187], v[40:43]
	v_mfma_f32_16x16x32_bf16 v[28:31], v[128:131], v[192:195], v[28:31]
	v_mfma_f32_16x16x32_bf16 v[24:27], v[136:139], v[192:195], v[24:27]
	v_mfma_f32_16x16x32_bf16 v[12:15], v[128:131], v[200:203], v[12:15]
	v_mfma_f32_16x16x32_bf16 v[8:11], v[136:139], v[200:203], v[8:11]
	v_mfma_f32_16x16x32_bf16 v[60:63], v[132:135], v[180:183], v[60:63]
	v_mfma_f32_16x16x32_bf16 v[56:59], v[140:143], v[180:183], v[56:59]
	v_mfma_f32_16x16x32_bf16 v[44:47], v[132:135], v[188:191], v[44:47]
	v_mfma_f32_16x16x32_bf16 v[40:43], v[140:143], v[188:191], v[40:43]
	v_mfma_f32_16x16x32_bf16 v[28:31], v[132:135], v[196:199], v[28:31]
	v_mfma_f32_16x16x32_bf16 v[24:27], v[140:143], v[196:199], v[24:27]
	v_mfma_f32_16x16x32_bf16 v[12:15], v[132:135], v[204:207], v[12:15]
	v_mfma_f32_16x16x32_bf16 v[8:11], v[140:143], v[204:207], v[8:11]
	v_mfma_f32_16x16x32_bf16 v[52:55], v[156:159], v[176:179], v[52:55]
	v_mfma_f32_16x16x32_bf16 v[48:51], v[168:171], v[176:179], v[48:51]
	v_mfma_f32_16x16x32_bf16 v[36:39], v[156:159], v[184:187], v[36:39]
	v_mfma_f32_16x16x32_bf16 v[32:35], v[168:171], v[184:187], v[32:35]
	v_mfma_f32_16x16x32_bf16 v[20:23], v[156:159], v[192:195], v[20:23]
	v_mfma_f32_16x16x32_bf16 v[16:19], v[168:171], v[192:195], v[16:19]
	v_mfma_f32_16x16x32_bf16 v[4:7], v[156:159], v[200:203], v[4:7]
	v_mfma_f32_16x16x32_bf16 v[0:3], v[168:171], v[200:203], v[0:3]
	v_mfma_f32_16x16x32_bf16 v[52:55], v[164:167], v[180:183], v[52:55]
	v_mfma_f32_16x16x32_bf16 v[48:51], v[172:175], v[180:183], v[48:51]
	v_mfma_f32_16x16x32_bf16 v[36:39], v[164:167], v[188:191], v[36:39]
	v_mfma_f32_16x16x32_bf16 v[32:35], v[172:175], v[188:191], v[32:35]
	v_mfma_f32_16x16x32_bf16 v[20:23], v[164:167], v[196:199], v[20:23]
	v_mfma_f32_16x16x32_bf16 v[16:19], v[172:175], v[196:199], v[16:19]
	v_mfma_f32_16x16x32_bf16 v[4:7], v[164:167], v[204:207], v[4:7]
	v_mfma_f32_16x16x32_bf16 v[0:3], v[172:175], v[204:207], v[0:3]
	s_barrier
	s_add_i32 s68, s68, 2
	s_add_u32 s18, s18, 0x10000
	s_addc_u32 s19, s19, 0
	s_add_u32 s66, s66, 0x10000
	s_addc_u32 s67, s67, 0
	s_cmp_gt_u32 s68, 13
	s_cbranch_scc0 .Lk0_trail

; __device__ __forceinline__ v4u pack8(const float* x) { v4u o; o.x = pk2(x[0], x[1]); o.y = pk2(x[2], x[3]); o.z = pk2(x[4], x[5]); o.w = pk2(x[6], x[7]); return o; }
; __device__ __forceinline__ size_t tl(int row, int col, int K) { return (size_t)(row >> 8) * ((size_t)256 * K) + (size_t)(col >> 6) * (256 * 64) + (size_t)((row & 255) * 64 + (col & 63)); }
; __device__ __forceinline__ float rstd_from_quarter(const v4f a, int ln) {
;     float s = (a.x + a.y) + (a.z + a.w);
;     s += __int_as_float(__builtin_amdgcn_ds_bpermute((ln ^ 16) << 2, __float_as_int(s))); s += __int_as_float(__builtin_amdgcn_ds_bpermute((ln ^ 32) << 2, __float_as_int(s)));
;     return rsqrtf(s * (1.0f / DM) + EPS);
; }
;     __device__ __forceinline__ void operator()(const f32x4 (&acc)[2][2][4][2], const Unit& u, int wr, int wc, int, int) const {
;         int t_ = threadIdx.x; asm volatile("" : "+v"(t_)); const int fr = t_ & 15, fq = (t_ >> 4) & 3;
;         const int row0 = u.pm * BM + wr * 64 + fr, col0 = u.pn * HALF + wc * 32 + 8 * fq;
;         v4f pq[2][4];
; #pragma unroll
;         for (int ai = 0; ai < 2; ++ai)
; #pragma unroll
;             for (int m = 0; m < 4; ++m) pq[ai][m] = *(const v4f*)(ssp + (size_t)(row0 + ai * HALF + m * 16) * 16 + 4 * fq);
;         asm volatile("" ::: "memory");
; #pragma unroll
;         for (int ai = 0; ai < 2; ++ai)
; #pragma unroll
;             for (int m = 0; m < 4; ++m) {
;                 const int row = row0 + ai * HALF + m * 16; const float rs = rstd_from_quarter(pq[ai][m], fq * 16 + fr);
;                 float h[8];
; #pragma unroll
;                 for (int n = 0; n < 2; ++n) { const f32x4 g = acc[ai][0][m][n] * rs, uu = acc[ai][1][m][n] * rs; const f32x4 hv = (g * sigmoid4(g)) * uu;
;                     h[n * 4 + 0] = hv[0]; h[n * 4 + 1] = hv[1]; h[n * 4 + 2] = hv[2]; h[n * 4 + 3] = hv[3]; }
;                 __builtin_nontemporal_store(pack8(h), (u32x4*)(O + tl(row, col0, FF)));
.LBB0_1359:
	s_lshl_b32 s9, s16, 8
	v_mov_b32_e32 v142, v230
	s_add_i32 s9, s9, s52
	s_mov_b32 s16, 0x358637bd
	v_and_or_b32 v136, v142, 15, s9
	v_bfe_u32 v143, v142, 4, 2
	v_or_b32_e32 v132, 16, v136
	v_lshlrev_b32_e32 v220, 4, v143
	v_ashrrev_i32_e32 v137, 31, v136
	v_ashrrev_i32_e32 v133, 31, v132
	v_lshl_add_u64 v[138:139], s[4:5], 0, v[220:221]
	v_lshlrev_b64 v[128:129], 6, v[136:137]
	v_lshlrev_b64 v[132:133], 6, v[132:133]
	v_lshl_add_u64 v[140:141], v[138:139], 0, v[128:129]
	v_lshl_add_u64 v[132:133], v[138:139], 0, v[132:133]
	global_load_dwordx4 v[128:131], v[140:141], off
	v_lshlrev_b32_e32 v137, 2, v142
	global_load_dwordx4 v[132:135], v[132:133], off
	v_or_b32_e32 v142, 32, v136
	v_or_b32_e32 v160, 48, v136
	v_add_u32_e32 v158, 0x80, v136
	v_lshl_or_b32 v166, v143, 3, s56
	v_lshlrev_b32_e32 v136, 6, v136
	v_ashrrev_i32_e32 v143, 31, v142
	v_bitop3_b32 v165, v137, 64, v244 bitop3:0x6c
	v_bitop3_b32 v164, v137, s90, v244 bitop3:0x6c
	v_ashrrev_i32_e32 v161, 31, v160
	v_and_or_b32 v167, v136, s84, v166
	v_lshlrev_b64 v[136:137], 6, v[142:143]
	v_lshlrev_b64 v[142:143], 6, v[160:161]
	v_lshl_add_u64 v[136:137], v[138:139], 0, v[136:137]
	v_lshl_add_u64 v[142:143], v[138:139], 0, v[142:143]
	global_load_dwordx4 v[168:171], v[136:137], off
	global_load_dwordx4 v[172:175], v[142:143], off
	v_ashrrev_i32_e32 v159, 31, v158
	v_lshlrev_b64 v[160:161], 6, v[158:159]
	v_lshl_add_u64 v[138:139], v[138:139], 0, v[160:161]
	s_lshl_b32 s11, s17, 7
	v_mov_b64_e32 v[156:157], s[16:17]
	s_or_b32 s11, s11, s53
	s_ashr_i32 s16, s11, 6
	s_ashr_i32 s17, s16, 31
	s_ashr_i32 s9, s9, 8
	s_lshl_b64 s[16:17], s[16:17], 15
	s_add_u32 s16, s50, s16
	v_lshlrev_b32_e32 v220, 1, v167
	s_addc_u32 s17, s51, s17
	v_lshl_add_u64 v[176:177], s[16:17], 0, v[220:221]
	s_waitcnt vmcnt(0)
	v_mov_b32_e32 v160, v129
	v_mov_b32_e32 v161, v130
	v_mov_b32_e32 v129, v131
	v_mov_b32_e32 v130, v133
	v_mov_b32_e32 v131, v134
	v_mov_b32_e32 v133, v135
	v_pk_add_f32 v[128:129], v[160:161], v[128:129]
	v_pk_add_f32 v[130:131], v[130:131], v[132:133]
	v_mov_b32_e32 v133, v128
	v_mov_b32_e32 v132, v130
	v_mov_b32_e32 v128, v131
	v_pk_add_f32 v[128:129], v[132:133], v[128:129]
	ds_bpermute_b32 v131, v165, v129
	ds_bpermute_b32 v130, v165, v128
	v_add_co_u32_e32 v160, vcc, s80, v140
	s_waitcnt lgkmcnt(0)
	v_pk_add_f32 v[178:179], v[128:129], v[130:131]
	ds_bpermute_b32 v181, v164, v179
	ds_bpermute_b32 v180, v164, v178
	v_addc_co_u32_e32 v161, vcc, 0, v141, vcc
	global_load_dwordx4 v[140:143], v[138:139], off
	s_nop 0
	global_load_dwordx4 v[136:139], v[160:161], off offset:1024
	global_load_dwordx4 v[132:135], v[160:161], off offset:2048
	global_load_dwordx4 v[128:131], v[160:161], off offset:3072
	s_waitcnt lgkmcnt(0)
	v_pk_add_f32 v[160:161], v[178:179], v[180:181]
	s_nop 0
	v_pk_fma_f32 v[178:179], v[160:161], s[74:75], v[156:157] op_sel_hi:[1,0,0]
	v_mad_i64_i32 v[160:161], s[18:19], s9, v245, v[176:177]
	v_mul_f32_e32 v159, 0x4b800000, v179
	v_cmp_gt_f32_e32 vcc, s25, v179
	v_mul_f32_e32 v167, 0x4b800000, v178
	s_nop 0
	v_cndmask_b32_e32 v159, v179, v159, vcc
	v_rsq_f32_e32 v159, v159
	s_nop 0
	v_mul_f32_e32 v176, 0x45800000, v159
	v_cndmask_b32_e32 v176, v159, v176, vcc
	v_pk_mul_f32 v[120:121], v[120:121], v[176:177] op_sel_hi:[1,0]
	v_pk_mul_f32 v[122:123], v[122:123], v[176:177] op_sel_hi:[1,0]
	v_pk_mul_f32 v[184:185], v[120:121], s[38:39] op_sel_hi:[1,0]
	v_pk_mul_f32 v[182:183], v[122:123], s[38:39] op_sel_hi:[1,0]
	v_exp_f32_e32 v184, v184
	v_exp_f32_e32 v182, v182
	v_exp_f32_e32 v183, v183
	v_exp_f32_e32 v185, v185
	v_pk_mul_f32 v[124:125], v[124:125], v[176:177] op_sel_hi:[1,0]
	v_pk_mul_f32 v[126:127], v[126:127], v[176:177] op_sel_hi:[1,0]
	v_pk_mul_f32 v[180:181], v[124:125], s[38:39] op_sel_hi:[1,0]
	v_pk_add_f32 v[182:183], v[182:183], 1.0 op_sel_hi:[1,0]
	v_pk_add_f32 v[184:185], v[184:185], 1.0 op_sel_hi:[1,0]
	v_exp_f32_e32 v180, v180
	v_exp_f32_e32 v181, v181
	v_rcp_f32_e32 v184, v184
	v_rcp_f32_e32 v185, v185
	v_rcp_f32_e32 v182, v182
	v_rcp_f32_e32 v183, v183
	v_pk_mul_f32 v[116:117], v[116:117], v[176:177] op_sel_hi:[1,0]
	v_pk_mul_f32 v[118:119], v[118:119], v[176:177] op_sel_hi:[1,0]
	v_pk_mul_f32 v[112:113], v[112:113], v[176:177] op_sel_hi:[1,0]
	v_pk_mul_f32 v[114:115], v[114:115], v[176:177] op_sel_hi:[1,0]
	v_pk_mul_f32 v[176:177], v[126:127], s[38:39] op_sel_hi:[1,0]
	v_pk_add_f32 v[180:181], v[180:181], 1.0 op_sel_hi:[1,0]
	v_exp_f32_e32 v176, v176
	v_exp_f32_e32 v177, v177
	v_pk_mul_f32 v[120:121], v[120:121], v[184:185]
	v_pk_mul_f32 v[122:123], v[122:123], v[182:183]
	v_cmp_gt_f32_e32 vcc, s25, v178
	v_rcp_f32_e32 v180, v180
	v_rcp_f32_e32 v181, v181
	v_pk_mul_f32 v[122:123], v[114:115], v[122:123]
	v_pk_mul_f32 v[114:115], v[112:113], v[120:121]
	v_cndmask_b32_e32 v112, v178, v167, vcc
	v_pk_add_f32 v[176:177], v[176:177], 1.0 op_sel_hi:[1,0]
	v_rsq_f32_e32 v120, v112
	v_rcp_f32_e32 v176, v176
	v_rcp_f32_e32 v177, v177
	v_pk_mul_f32 v[124:125], v[124:125], v[180:181]
	v_cvt_pk_bf16_f32 v114, v114, v115
	v_pk_mul_f32 v[116:117], v[116:117], v[124:125]
	v_mul_f32_e32 v115, 0x45800000, v120
	v_pk_mul_f32 v[126:127], v[126:127], v[176:177]
	v_cvt_pk_bf16_f32 v112, v116, v117
	v_cndmask_b32_e32 v116, v120, v115, vcc
	v_pk_mul_f32 v[118:119], v[118:119], v[126:127]
	v_pk_mul_f32 v[108:109], v[108:109], v[116:117] op_sel_hi:[1,0]
	v_pk_mul_f32 v[110:111], v[110:111], v[116:117] op_sel_hi:[1,0]
	v_cvt_pk_bf16_f32 v113, v118, v119
	v_pk_mul_f32 v[118:119], v[110:111], s[38:39] op_sel_hi:[1,0]
	v_pk_mul_f32 v[120:121], v[108:109], s[38:39] op_sel_hi:[1,0]
	v_exp_f32_e32 v118, v118
	v_exp_f32_e32 v120, v120
	v_exp_f32_e32 v119, v119
	v_exp_f32_e32 v121, v121
; __device__ __forceinline__ v4u pack8(const float* x) { v4u o; o.x = pk2(x[0], x[1]); o.y = pk2(x[2], x[3]); o.z = pk2(x[4], x[5]); o.w = pk2(x[6], x[7]); return o; }
; __device__ __forceinline__ size_t tl(int row, int col, int K) { return (size_t)(row >> 8) * ((size_t)256 * K) + (size_t)(col >> 6) * (256 * 64) + (size_t)((row & 255) * 64 + (col & 63)); }
;     __device__ __forceinline__ void operator()(const f32x4 (&acc)[2][2][4][2], const Unit& u, int wr, int wc, int, int) const {
;     ...
;         for (int ai = 0; ai < 2; ++ai)
; #pragma unroll
;             for (int m = 0; m < 4; ++m) {
;                 const int row = row0 + ai * HALF + m * 16; const float rs = rstd_from_quarter(pq[ai][m], fq * 16 + fr);
;                 float h[8];
; #pragma unroll
;                 for (int n = 0; n < 2; ++n) { const f32x4 g = acc[ai][0][m][n] * rs, uu = acc[ai][1][m][n] * rs; const f32x4 hv = (g * sigmoid4(g)) * uu;
;                     h[n * 4 + 0] = hv[0]; h[n * 4 + 1] = hv[1]; h[n * 4 + 2] = hv[2]; h[n * 4 + 3] = hv[3]; }
;                 __builtin_nontemporal_store(pack8(h), (u32x4*)(O + tl(row, col0, FF)));
;             }
	v_cvt_pk_bf16_f32 v115, v122, v123
	global_store_dwordx4 v[160:161], v[112:115], off nt
	v_pk_mul_f32 v[100:101], v[100:101], v[116:117] op_sel_hi:[1,0]
	v_pk_mul_f32 v[102:103], v[102:103], v[116:117] op_sel_hi:[1,0]
	v_pk_add_f32 v[112:113], v[118:119], 1.0 op_sel_hi:[1,0]
	v_pk_add_f32 v[114:115], v[120:121], 1.0 op_sel_hi:[1,0]
	v_rcp_f32_e32 v112, v112
	v_rcp_f32_e32 v114, v114
	v_rcp_f32_e32 v115, v115
	v_rcp_f32_e32 v113, v113
	v_pk_mul_f32 v[104:105], v[104:105], v[116:117] op_sel_hi:[1,0]
	v_pk_mul_f32 v[106:107], v[106:107], v[116:117] op_sel_hi:[1,0]
	v_pk_mul_f32 v[108:109], v[108:109], v[114:115]
	v_pk_mul_f32 v[110:111], v[110:111], v[112:113]
	v_mov_b32_e32 v112, v169
	v_mov_b32_e32 v113, v170
	v_mov_b32_e32 v169, v171
	v_mov_b32_e32 v114, v173
	v_mov_b32_e32 v115, v174
	v_mov_b32_e32 v173, v175
	v_pk_add_f32 v[112:113], v[112:113], v[168:169]
	v_pk_add_f32 v[114:115], v[114:115], v[172:173]
	v_pk_mul_f32 v[96:97], v[96:97], v[116:117] op_sel_hi:[1,0]
	v_pk_mul_f32 v[98:99], v[98:99], v[116:117] op_sel_hi:[1,0]
	v_mov_b32_e32 v116, v114
	v_mov_b32_e32 v117, v112
	v_mov_b32_e32 v112, v115
	v_pk_add_f32 v[112:113], v[116:117], v[112:113]
	v_pk_mul_f32 v[102:103], v[102:103], v[110:111]
	v_pk_mul_f32 v[100:101], v[100:101], v[108:109]
	v_pk_mul_f32 v[108:109], v[106:107], s[38:39] op_sel_hi:[1,0]
	v_pk_mul_f32 v[110:111], v[104:105], s[38:39] op_sel_hi:[1,0]
	ds_bpermute_b32 v115, v165, v113
	ds_bpermute_b32 v114, v165, v112
	v_exp_f32_e32 v110, v110
	v_exp_f32_e32 v108, v108
	v_exp_f32_e32 v109, v109
	v_exp_f32_e32 v111, v111
	s_waitcnt lgkmcnt(0)
	v_pk_add_f32 v[112:113], v[112:113], v[114:115]
	ds_bpermute_b32 v115, v164, v113
	v_pk_add_f32 v[108:109], v[108:109], 1.0 op_sel_hi:[1,0]
	v_pk_add_f32 v[110:111], v[110:111], 1.0 op_sel_hi:[1,0]
	v_rcp_f32_e32 v108, v108
	v_rcp_f32_e32 v110, v110
	v_rcp_f32_e32 v111, v111
	v_rcp_f32_e32 v109, v109
	ds_bpermute_b32 v114, v164, v112
	v_pk_mul_f32 v[104:105], v[104:105], v[110:111]
	v_pk_mul_f32 v[106:107], v[106:107], v[108:109]
	s_nop 0
	v_pk_mul_f32 v[106:107], v[98:99], v[106:107]
	v_pk_mul_f32 v[98:99], v[96:97], v[104:105]
	s_waitcnt lgkmcnt(0)
	v_pk_add_f32 v[96:97], v[112:113], v[114:115]
	v_cvt_pk_bf16_f32 v98, v98, v99
	v_pk_fma_f32 v[104:105], v[96:97], s[74:75], v[156:157] op_sel_hi:[1,0,0]
	v_cvt_pk_bf16_f32 v97, v102, v103
	v_mul_f32_e32 v96, 0x4b800000, v105
	v_cmp_gt_f32_e32 vcc, s25, v105
	s_nop 1
	v_cndmask_b32_e32 v96, v105, v96, vcc
	v_rsq_f32_e32 v105, v96
	v_cvt_pk_bf16_f32 v96, v100, v101
	v_mul_f32_e32 v99, 0x45800000, v105
	v_cndmask_b32_e32 v100, v105, v99, vcc
	v_pk_mul_f32 v[92:93], v[92:93], v[100:101] op_sel_hi:[1,0]
	v_pk_mul_f32 v[94:95], v[94:95], v[100:101] op_sel_hi:[1,0]
	v_pk_mul_f32 v[108:109], v[92:93], s[38:39] op_sel_hi:[1,0]
	v_pk_mul_f32 v[102:103], v[94:95], s[38:39] op_sel_hi:[1,0]
	v_exp_f32_e32 v108, v108
	v_exp_f32_e32 v102, v102
	v_exp_f32_e32 v103, v103
	v_exp_f32_e32 v109, v109
	v_cvt_pk_bf16_f32 v99, v106, v107
	global_store_dwordx4 v[160:161], v[96:99], off offset:2048 nt
	v_pk_mul_f32 v[88:89], v[88:89], v[100:101] op_sel_hi:[1,0]
	v_pk_mul_f32 v[90:91], v[90:91], v[100:101] op_sel_hi:[1,0]
	v_pk_add_f32 v[96:97], v[102:103], 1.0 op_sel_hi:[1,0]
	v_pk_add_f32 v[98:99], v[108:109], 1.0 op_sel_hi:[1,0]
	v_rcp_f32_e32 v96, v96
	v_rcp_f32_e32 v98, v98
	v_rcp_f32_e32 v99, v99
	v_rcp_f32_e32 v97, v97
	v_pk_mul_f32 v[84:85], v[84:85], v[100:101] op_sel_hi:[1,0]
	v_pk_mul_f32 v[86:87], v[86:87], v[100:101] op_sel_hi:[1,0]
	v_pk_mul_f32 v[92:93], v[92:93], v[98:99]
	v_pk_mul_f32 v[94:95], v[94:95], v[96:97]
	v_pk_mul_f32 v[96:97], v[90:91], s[38:39] op_sel_hi:[1,0]
	v_pk_mul_f32 v[98:99], v[88:89], s[38:39] op_sel_hi:[1,0]
	v_exp_f32_e32 v96, v96
	v_exp_f32_e32 v98, v98
	v_exp_f32_e32 v97, v97
	v_exp_f32_e32 v99, v99
	v_pk_mul_f32 v[86:87], v[86:87], v[94:95]
	v_pk_mul_f32 v[84:85], v[84:85], v[92:93]
	v_pk_add_f32 v[92:93], v[96:97], 1.0 op_sel_hi:[1,0]
	v_pk_add_f32 v[94:95], v[98:99], 1.0 op_sel_hi:[1,0]
	v_rcp_f32_e32 v92, v92
	v_rcp_f32_e32 v94, v94
	v_rcp_f32_e32 v95, v95
	v_rcp_f32_e32 v93, v93
	v_pk_mul_f32 v[80:81], v[80:81], v[100:101] op_sel_hi:[1,0]
	v_pk_mul_f32 v[82:83], v[82:83], v[100:101] op_sel_hi:[1,0]
	v_pk_mul_f32 v[88:89], v[88:89], v[94:95]
	v_pk_mul_f32 v[90:91], v[90:91], v[92:93]
	v_cmp_gt_f32_e32 vcc, s25, v104
	v_pk_mul_f32 v[90:91], v[82:83], v[90:91]
	v_pk_mul_f32 v[82:83], v[80:81], v[88:89]
	v_mul_f32_e32 v81, 0x4b800000, v104
	v_cndmask_b32_e32 v81, v104, v81, vcc
	v_cvt_pk_bf16_f32 v80, v84, v85
	v_rsq_f32_e32 v84, v81
	v_cvt_pk_bf16_f32 v81, v86, v87
	v_cvt_pk_bf16_f32 v82, v82, v83
	v_cvt_pk_bf16_f32 v83, v90, v91
	v_mul_f32_e32 v85, 0x45800000, v84
	v_cndmask_b32_e32 v84, v84, v85, vcc
	v_pk_mul_f32 v[76:77], v[76:77], v[84:85] op_sel_hi:[1,0]
	v_pk_mul_f32 v[78:79], v[78:79], v[84:85] op_sel_hi:[1,0]
	v_pk_mul_f32 v[88:89], v[76:77], s[38:39] op_sel_hi:[1,0]
	v_pk_mul_f32 v[86:87], v[78:79], s[38:39] op_sel_hi:[1,0]
	v_exp_f32_e32 v88, v88
	v_exp_f32_e32 v89, v89
	v_exp_f32_e32 v86, v86
	v_exp_f32_e32 v87, v87
	v_add_co_u32_e32 v90, vcc, s85, v160
	v_pk_mul_f32 v[72:73], v[72:73], v[84:85] op_sel_hi:[1,0]
	s_nop 0
	v_addc_co_u32_e32 v91, vcc, 0, v161, vcc
	global_store_dwordx4 v[90:91], v[80:83], off nt
	v_pk_mul_f32 v[74:75], v[74:75], v[84:85] op_sel_hi:[1,0]
	v_pk_mul_f32 v[68:69], v[68:69], v[84:85] op_sel_hi:[1,0]
	v_pk_add_f32 v[80:81], v[86:87], 1.0 op_sel_hi:[1,0]
	v_pk_add_f32 v[82:83], v[88:89], 1.0 op_sel_hi:[1,0]
	v_rcp_f32_e32 v80, v80
	v_rcp_f32_e32 v82, v82
	v_rcp_f32_e32 v83, v83
	v_rcp_f32_e32 v81, v81
	v_pk_mul_f32 v[70:71], v[70:71], v[84:85] op_sel_hi:[1,0]
	v_pk_mul_f32 v[64:65], v[64:65], v[84:85] op_sel_hi:[1,0]
	v_pk_mul_f32 v[76:77], v[76:77], v[82:83]
	v_pk_mul_f32 v[78:79], v[78:79], v[80:81]
	v_pk_mul_f32 v[80:81], v[74:75], s[38:39] op_sel_hi:[1,0]
	v_pk_mul_f32 v[82:83], v[72:73], s[38:39] op_sel_hi:[1,0]
	v_exp_f32_e32 v80, v80
	v_exp_f32_e32 v82, v82
	v_exp_f32_e32 v81, v81
	v_exp_f32_e32 v83, v83
	v_pk_mul_f32 v[70:71], v[70:71], v[78:79]
	v_pk_mul_f32 v[68:69], v[68:69], v[76:77]
	v_pk_add_f32 v[76:77], v[80:81], 1.0 op_sel_hi:[1,0]
	v_pk_add_f32 v[78:79], v[82:83], 1.0 op_sel_hi:[1,0]
	v_rcp_f32_e32 v76, v76
	v_rcp_f32_e32 v78, v78
	v_rcp_f32_e32 v79, v79
	v_rcp_f32_e32 v77, v77
	v_pk_mul_f32 v[66:67], v[66:67], v[84:85] op_sel_hi:[1,0]
	v_pk_mul_f32 v[72:73], v[72:73], v[78:79]
	v_pk_mul_f32 v[74:75], v[74:75], v[76:77]
	s_nop 0
	v_pk_mul_f32 v[74:75], v[66:67], v[74:75]
	v_pk_mul_f32 v[66:67], v[64:65], v[72:73]
	s_waitcnt vmcnt(6)
; __device__ __forceinline__ v4u pack8(const float* x) { v4u o; o.x = pk2(x[0], x[1]); o.y = pk2(x[2], x[3]); o.z = pk2(x[4], x[5]); o.w = pk2(x[6], x[7]); return o; }
; __device__ __forceinline__ size_t tl(int row, int col, int K) { return (size_t)(row >> 8) * ((size_t)256 * K) + (size_t)(col >> 6) * (256 * 64) + (size_t)((row & 255) * 64 + (col & 63)); }
;     __device__ __forceinline__ void operator()(const f32x4 (&acc)[2][2][4][2], const Unit& u, int wr, int wc, int, int) const {
;     ...
;         for (int ai = 0; ai < 2; ++ai)
; #pragma unroll
;             for (int m = 0; m < 4; ++m) {
;                 const int row = row0 + ai * HALF + m * 16; const float rs = rstd_from_quarter(pq[ai][m], fq * 16 + fr);
;                 float h[8];
; #pragma unroll
;                 for (int n = 0; n < 2; ++n) { const f32x4 g = acc[ai][0][m][n] * rs, uu = acc[ai][1][m][n] * rs; const f32x4 hv = (g * sigmoid4(g)) * uu;
;                     h[n * 4 + 0] = hv[0]; h[n * 4 + 1] = hv[1]; h[n * 4 + 2] = hv[2]; h[n * 4 + 3] = hv[3]; }
;                 __builtin_nontemporal_store(pack8(h), (u32x4*)(O + tl(row, col0, FF)));
;             }
	v_mov_b32_e32 v64, v141
	v_mov_b32_e32 v65, v142
	v_mov_b32_e32 v141, v143
	s_waitcnt vmcnt(5)
	v_mov_b32_e32 v72, v137
	v_mov_b32_e32 v73, v138
	v_mov_b32_e32 v137, v139
	v_pk_add_f32 v[64:65], v[64:65], v[140:141]
	v_pk_add_f32 v[72:73], v[72:73], v[136:137]
	v_mov_b32_e32 v77, v64
	v_mov_b32_e32 v76, v72
	v_mov_b32_e32 v64, v73
	v_pk_add_f32 v[72:73], v[76:77], v[64:65]
	ds_bpermute_b32 v77, v165, v73
	ds_bpermute_b32 v76, v165, v72
	v_cvt_pk_bf16_f32 v64, v68, v69
	v_cvt_pk_bf16_f32 v65, v70, v71
	v_cvt_pk_bf16_f32 v66, v66, v67
	v_cvt_pk_bf16_f32 v67, v74, v75
	s_waitcnt lgkmcnt(0)
	v_pk_add_f32 v[68:69], v[72:73], v[76:77]
	ds_bpermute_b32 v71, v164, v69
	ds_bpermute_b32 v70, v164, v68
	global_store_dwordx4 v[90:91], v[64:67], off offset:2048 nt
	s_nop 1
	v_lshlrev_b32_e32 v64, 6, v158
	v_and_or_b32 v72, v64, s84, v166
	s_waitcnt lgkmcnt(0)
	v_pk_add_f32 v[64:65], v[68:69], v[70:71]
	v_lshlrev_b32_e32 v220, 1, v72
	v_pk_fma_f32 v[64:65], v[64:65], s[74:75], v[156:157] op_sel_hi:[1,0,0]
	v_lshrrev_b32_e32 v66, 8, v158
	v_mul_f32_e32 v67, 0x4b800000, v65
	v_cmp_gt_f32_e32 vcc, s25, v65
	s_nop 1
	v_cndmask_b32_e32 v65, v65, v67, vcc
	v_rsq_f32_e32 v65, v65
	v_mul_hi_i32_i24_e32 v67, 0x160000, v66
	v_mul_i32_i24_e32 v66, 0x160000, v66
	v_mul_f32_e32 v68, 0x45800000, v65
	v_cndmask_b32_e32 v68, v65, v68, vcc
	v_pk_mul_f32 v[70:71], v[60:61], v[68:69] op_sel_hi:[1,0]
	v_pk_mul_f32 v[62:63], v[62:63], v[68:69] op_sel_hi:[1,0]
	v_pk_mul_f32 v[72:73], v[70:71], s[38:39] op_sel_hi:[1,0]
	v_pk_mul_f32 v[60:61], v[62:63], s[38:39] op_sel_hi:[1,0]
	v_exp_f32_e32 v72, v72
	v_exp_f32_e32 v74, v60
	v_exp_f32_e32 v75, v61
	v_exp_f32_e32 v73, v73
	v_lshl_add_u64 v[60:61], s[16:17], 0, v[220:221]
	v_lshl_add_u64 v[60:61], v[60:61], 0, v[66:67]
	v_pk_add_f32 v[66:67], v[74:75], 1.0 op_sel_hi:[1,0]
	v_pk_add_f32 v[72:73], v[72:73], 1.0 op_sel_hi:[1,0]
	v_rcp_f32_e32 v66, v66
	v_rcp_f32_e32 v72, v72
	v_rcp_f32_e32 v73, v73
	v_rcp_f32_e32 v67, v67
	v_pk_mul_f32 v[56:57], v[56:57], v[68:69] op_sel_hi:[1,0]
	v_pk_mul_f32 v[58:59], v[58:59], v[68:69] op_sel_hi:[1,0]
	v_pk_mul_f32 v[70:71], v[70:71], v[72:73]
	v_pk_mul_f32 v[62:63], v[62:63], v[66:67]
	v_pk_mul_f32 v[66:67], v[58:59], s[38:39] op_sel_hi:[1,0]
	v_pk_mul_f32 v[72:73], v[56:57], s[38:39] op_sel_hi:[1,0]
	v_exp_f32_e32 v66, v66
	v_exp_f32_e32 v72, v72
	v_exp_f32_e32 v67, v67
	v_exp_f32_e32 v73, v73
	v_pk_mul_f32 v[54:55], v[54:55], v[68:69] op_sel_hi:[1,0]
	v_pk_mul_f32 v[48:49], v[48:49], v[68:69] op_sel_hi:[1,0]
	v_pk_mul_f32 v[54:55], v[54:55], v[62:63]
	v_pk_add_f32 v[62:63], v[66:67], 1.0 op_sel_hi:[1,0]
	v_pk_add_f32 v[66:67], v[72:73], 1.0 op_sel_hi:[1,0]
	v_rcp_f32_e32 v62, v62
	v_rcp_f32_e32 v66, v66
	v_rcp_f32_e32 v67, v67
	v_rcp_f32_e32 v63, v63
	v_pk_mul_f32 v[50:51], v[50:51], v[68:69] op_sel_hi:[1,0]
	v_cmp_gt_f32_e32 vcc, s25, v64
	v_pk_mul_f32 v[56:57], v[56:57], v[66:67]
	v_pk_mul_f32 v[58:59], v[58:59], v[62:63]
	v_pk_mul_f32 v[52:53], v[52:53], v[68:69] op_sel_hi:[1,0]
	v_pk_mul_f32 v[58:59], v[50:51], v[58:59]
	v_pk_mul_f32 v[50:51], v[48:49], v[56:57]
	v_mul_f32_e32 v48, 0x4b800000, v64
	v_cndmask_b32_e32 v48, v64, v48, vcc
	v_rsq_f32_e32 v56, v48
	v_pk_mul_f32 v[52:53], v[52:53], v[70:71]
	v_cvt_pk_bf16_f32 v50, v50, v51
	v_cvt_pk_bf16_f32 v48, v52, v53
	v_mul_f32_e32 v51, 0x45800000, v56
	v_cndmask_b32_e32 v52, v56, v51, vcc
	v_pk_mul_f32 v[44:45], v[44:45], v[52:53] op_sel_hi:[1,0]
	v_pk_mul_f32 v[46:47], v[46:47], v[52:53] op_sel_hi:[1,0]
	v_cvt_pk_bf16_f32 v49, v54, v55
	v_pk_mul_f32 v[54:55], v[46:47], s[38:39] op_sel_hi:[1,0]
	v_pk_mul_f32 v[56:57], v[44:45], s[38:39] op_sel_hi:[1,0]
	v_exp_f32_e32 v54, v54
	v_exp_f32_e32 v56, v56
	v_exp_f32_e32 v55, v55
	v_exp_f32_e32 v57, v57
	v_cvt_pk_bf16_f32 v51, v58, v59
	global_store_dwordx4 v[60:61], v[48:51], off nt
	v_pk_mul_f32 v[36:37], v[36:37], v[52:53] op_sel_hi:[1,0]
	v_pk_mul_f32 v[38:39], v[38:39], v[52:53] op_sel_hi:[1,0]
	v_pk_add_f32 v[48:49], v[54:55], 1.0 op_sel_hi:[1,0]
	v_pk_add_f32 v[50:51], v[56:57], 1.0 op_sel_hi:[1,0]
	v_rcp_f32_e32 v48, v48
	v_rcp_f32_e32 v50, v50
	v_rcp_f32_e32 v51, v51
	v_rcp_f32_e32 v49, v49
	v_pk_mul_f32 v[40:41], v[40:41], v[52:53] op_sel_hi:[1,0]
	v_pk_mul_f32 v[42:43], v[42:43], v[52:53] op_sel_hi:[1,0]
	v_pk_mul_f32 v[44:45], v[44:45], v[50:51]
	v_pk_mul_f32 v[46:47], v[46:47], v[48:49]
	s_waitcnt vmcnt(6)
	v_mov_b32_e32 v48, v133
	v_mov_b32_e32 v49, v134
	v_mov_b32_e32 v133, v135
	s_waitcnt vmcnt(5)
	v_mov_b32_e32 v50, v129
	v_mov_b32_e32 v51, v130
	v_mov_b32_e32 v129, v131
	v_pk_add_f32 v[48:49], v[48:49], v[132:133]
	v_pk_add_f32 v[50:51], v[50:51], v[128:129]
	v_pk_mul_f32 v[32:33], v[32:33], v[52:53] op_sel_hi:[1,0]
	v_pk_mul_f32 v[34:35], v[34:35], v[52:53] op_sel_hi:[1,0]
	v_mov_b32_e32 v52, v50
	v_mov_b32_e32 v53, v48
	v_mov_b32_e32 v48, v51
	v_pk_add_f32 v[48:49], v[52:53], v[48:49]
	v_pk_mul_f32 v[38:39], v[38:39], v[46:47]
	v_pk_mul_f32 v[36:37], v[36:37], v[44:45]
	v_pk_mul_f32 v[44:45], v[42:43], s[38:39] op_sel_hi:[1,0]
	v_pk_mul_f32 v[46:47], v[40:41], s[38:39] op_sel_hi:[1,0]
	ds_bpermute_b32 v51, v165, v49
	ds_bpermute_b32 v50, v165, v48
	v_exp_f32_e32 v46, v46
	v_exp_f32_e32 v44, v44
	v_exp_f32_e32 v45, v45
	v_exp_f32_e32 v47, v47
	s_waitcnt lgkmcnt(0)
; #define PG8_BAR __builtin_amdgcn_s_barrier()
; __device__ __forceinline__ v4u pack8(const float* x) { v4u o; o.x = pk2(x[0], x[1]); o.y = pk2(x[2], x[3]); o.z = pk2(x[4], x[5]); o.w = pk2(x[6], x[7]); return o; }
; __device__ __forceinline__ size_t tl(int row, int col, int K) { return (size_t)(row >> 8) * ((size_t)256 * K) + (size_t)(col >> 6) * (256 * 64) + (size_t)((row & 255) * 64 + (col & 63)); }
; template <class Epi, class Sched, bool ALIGN_EPI = false, bool SP2 = false>
; __device__ __forceinline__ void gemm_phase(PG8_LAS unsigned char* lds, const Gemm g, const Sched& S, const Epi& E) {
;     ...
;         if constexpr (!Epi::AFTER_DRAIN) { if (!keep) E(acc, cur, wr, wc, fr, fq); S.done(cur); }
;         if (!has_next) break;
;         if (!keep)
; #pragma unroll
;         for (int a = 0; a < 2; ++a)
; #pragma unroll
;             for (int b = 0; b < 2; ++b)
; #pragma unroll
;                 for (int m = 0; m < 4; ++m)
; #pragma unroll
;                     for (int n = 0; n < 2; ++n) acc[a][b][m][n] = (f32x4){0.f, 0.f, 0.f, 0.f};
;         cur = nxt; cA = nA; cB = nB; ++ui;
;         if constexpr (ALIGN_EPI) { if (wr == 1) PG8_BAR; }
;     __device__ __forceinline__ void operator()(const f32x4 (&acc)[2][2][4][2], const Unit& u, int wr, int wc, int, int) const {
;     ...
;             for (int m = 0; m < 4; ++m) {
;                 const int row = row0 + ai * HALF + m * 16; const float rs = rstd_from_quarter(pq[ai][m], fq * 16 + fr);
;                 float h[8];
; #pragma unroll
;                 for (int n = 0; n < 2; ++n) { const f32x4 g = acc[ai][0][m][n] * rs, uu = acc[ai][1][m][n] * rs; const f32x4 hv = (g * sigmoid4(g)) * uu;
;                     h[n * 4 + 0] = hv[0]; h[n * 4 + 1] = hv[1]; h[n * 4 + 2] = hv[2]; h[n * 4 + 3] = hv[3]; }
;                 __builtin_nontemporal_store(pack8(h), (u32x4*)(O + tl(row, col0, FF)));
;             }
	v_pk_add_f32 v[48:49], v[48:49], v[50:51]
	ds_bpermute_b32 v51, v164, v49
	v_pk_add_f32 v[44:45], v[44:45], 1.0 op_sel_hi:[1,0]
	v_pk_add_f32 v[46:47], v[46:47], 1.0 op_sel_hi:[1,0]
	v_rcp_f32_e32 v44, v44
	v_rcp_f32_e32 v46, v46
	v_rcp_f32_e32 v47, v47
	v_rcp_f32_e32 v45, v45
	ds_bpermute_b32 v50, v164, v48
	v_pk_mul_f32 v[40:41], v[40:41], v[46:47]
	v_pk_mul_f32 v[42:43], v[42:43], v[44:45]
	s_nop 0
	v_pk_mul_f32 v[42:43], v[34:35], v[42:43]
	v_pk_mul_f32 v[34:35], v[32:33], v[40:41]
	s_waitcnt lgkmcnt(0)
	v_pk_add_f32 v[32:33], v[48:49], v[50:51]
	v_cvt_pk_bf16_f32 v34, v34, v35
	v_pk_fma_f32 v[40:41], v[32:33], s[74:75], v[156:157] op_sel_hi:[1,0,0]
	v_cvt_pk_bf16_f32 v33, v38, v39
	v_mul_f32_e32 v32, 0x4b800000, v41
	v_cmp_gt_f32_e32 vcc, s25, v41
	s_nop 1
	v_cndmask_b32_e32 v32, v41, v32, vcc
	v_rsq_f32_e32 v41, v32
	v_cvt_pk_bf16_f32 v32, v36, v37
	v_mul_f32_e32 v35, 0x45800000, v41
	v_cndmask_b32_e32 v36, v41, v35, vcc
	v_pk_mul_f32 v[28:29], v[28:29], v[36:37] op_sel_hi:[1,0]
	v_pk_mul_f32 v[30:31], v[30:31], v[36:37] op_sel_hi:[1,0]
	v_pk_mul_f32 v[44:45], v[28:29], s[38:39] op_sel_hi:[1,0]
	v_pk_mul_f32 v[38:39], v[30:31], s[38:39] op_sel_hi:[1,0]
	v_exp_f32_e32 v44, v44
	v_exp_f32_e32 v38, v38
	v_exp_f32_e32 v39, v39
	v_exp_f32_e32 v45, v45
	v_cvt_pk_bf16_f32 v35, v42, v43
	global_store_dwordx4 v[60:61], v[32:35], off offset:2048 nt
	v_pk_mul_f32 v[24:25], v[24:25], v[36:37] op_sel_hi:[1,0]
	v_pk_mul_f32 v[26:27], v[26:27], v[36:37] op_sel_hi:[1,0]
	v_pk_add_f32 v[32:33], v[38:39], 1.0 op_sel_hi:[1,0]
	v_pk_add_f32 v[34:35], v[44:45], 1.0 op_sel_hi:[1,0]
	v_rcp_f32_e32 v32, v32
	v_rcp_f32_e32 v34, v34
	v_rcp_f32_e32 v35, v35
	v_rcp_f32_e32 v33, v33
	v_pk_mul_f32 v[20:21], v[20:21], v[36:37] op_sel_hi:[1,0]
	v_pk_mul_f32 v[22:23], v[22:23], v[36:37] op_sel_hi:[1,0]
	v_pk_mul_f32 v[28:29], v[28:29], v[34:35]
	v_pk_mul_f32 v[30:31], v[30:31], v[32:33]
	v_pk_mul_f32 v[32:33], v[26:27], s[38:39] op_sel_hi:[1,0]
	v_pk_mul_f32 v[34:35], v[24:25], s[38:39] op_sel_hi:[1,0]
	v_exp_f32_e32 v32, v32
	v_exp_f32_e32 v34, v34
	v_exp_f32_e32 v33, v33
	v_exp_f32_e32 v35, v35
	v_pk_mul_f32 v[22:23], v[22:23], v[30:31]
	v_pk_mul_f32 v[20:21], v[20:21], v[28:29]
	v_pk_add_f32 v[28:29], v[32:33], 1.0 op_sel_hi:[1,0]
	v_pk_add_f32 v[30:31], v[34:35], 1.0 op_sel_hi:[1,0]
	v_rcp_f32_e32 v28, v28
	v_rcp_f32_e32 v30, v30
	v_rcp_f32_e32 v31, v31
	v_rcp_f32_e32 v29, v29
	v_pk_mul_f32 v[16:17], v[16:17], v[36:37] op_sel_hi:[1,0]
	v_pk_mul_f32 v[18:19], v[18:19], v[36:37] op_sel_hi:[1,0]
	v_pk_mul_f32 v[24:25], v[24:25], v[30:31]
	v_pk_mul_f32 v[26:27], v[26:27], v[28:29]
	v_cmp_gt_f32_e32 vcc, s25, v40
	v_pk_mul_f32 v[26:27], v[18:19], v[26:27]
	v_pk_mul_f32 v[18:19], v[16:17], v[24:25]
	v_mul_f32_e32 v17, 0x4b800000, v40
	v_cndmask_b32_e32 v17, v40, v17, vcc
	v_cvt_pk_bf16_f32 v16, v20, v21
	v_rsq_f32_e32 v20, v17
	v_cvt_pk_bf16_f32 v17, v22, v23
	v_cvt_pk_bf16_f32 v18, v18, v19
	v_cvt_pk_bf16_f32 v19, v26, v27
	v_mul_f32_e32 v21, 0x45800000, v20
	v_cndmask_b32_e32 v20, v20, v21, vcc
	v_pk_mul_f32 v[12:13], v[12:13], v[20:21] op_sel_hi:[1,0]
	v_pk_mul_f32 v[14:15], v[14:15], v[20:21] op_sel_hi:[1,0]
	v_pk_mul_f32 v[24:25], v[12:13], s[38:39] op_sel_hi:[1,0]
	v_pk_mul_f32 v[22:23], v[14:15], s[38:39] op_sel_hi:[1,0]
	v_exp_f32_e32 v24, v24
	v_exp_f32_e32 v25, v25
	v_exp_f32_e32 v22, v22
	v_exp_f32_e32 v23, v23
	v_add_co_u32_e32 v26, vcc, s85, v60
	v_pk_mul_f32 v[8:9], v[8:9], v[20:21] op_sel_hi:[1,0]
	s_nop 0
	v_addc_co_u32_e32 v27, vcc, 0, v61, vcc
	global_store_dwordx4 v[26:27], v[16:19], off nt
	v_pk_mul_f32 v[10:11], v[10:11], v[20:21] op_sel_hi:[1,0]
	v_pk_mul_f32 v[4:5], v[4:5], v[20:21] op_sel_hi:[1,0]
	v_pk_add_f32 v[16:17], v[22:23], 1.0 op_sel_hi:[1,0]
	v_pk_add_f32 v[18:19], v[24:25], 1.0 op_sel_hi:[1,0]
	v_rcp_f32_e32 v16, v16
	v_rcp_f32_e32 v18, v18
	v_rcp_f32_e32 v19, v19
	v_rcp_f32_e32 v17, v17
	v_pk_mul_f32 v[6:7], v[6:7], v[20:21] op_sel_hi:[1,0]
	v_pk_mul_f32 v[0:1], v[0:1], v[20:21] op_sel_hi:[1,0]
	v_pk_mul_f32 v[12:13], v[12:13], v[18:19]
	v_pk_mul_f32 v[14:15], v[14:15], v[16:17]
	v_pk_mul_f32 v[16:17], v[10:11], s[38:39] op_sel_hi:[1,0]
	v_pk_mul_f32 v[18:19], v[8:9], s[38:39] op_sel_hi:[1,0]
	v_exp_f32_e32 v16, v16
	v_exp_f32_e32 v18, v18
	v_exp_f32_e32 v17, v17
	v_exp_f32_e32 v19, v19
	v_pk_mul_f32 v[6:7], v[6:7], v[14:15]
	v_pk_mul_f32 v[4:5], v[4:5], v[12:13]
	v_pk_add_f32 v[12:13], v[16:17], 1.0 op_sel_hi:[1,0]
	v_pk_add_f32 v[14:15], v[18:19], 1.0 op_sel_hi:[1,0]
	v_rcp_f32_e32 v12, v12
	v_rcp_f32_e32 v14, v14
	v_rcp_f32_e32 v15, v15
	v_rcp_f32_e32 v13, v13
	v_pk_mul_f32 v[2:3], v[2:3], v[20:21] op_sel_hi:[1,0]
	s_andn2_b64 vcc, exec, s[2:3]
	v_pk_mul_f32 v[8:9], v[8:9], v[14:15]
	v_pk_mul_f32 v[10:11], v[10:11], v[12:13]
	s_mov_b64 s[2:3], -1
	v_pk_mul_f32 v[10:11], v[2:3], v[10:11]
	v_pk_mul_f32 v[2:3], v[0:1], v[8:9]
	v_cvt_pk_bf16_f32 v0, v4, v5
	v_cvt_pk_bf16_f32 v1, v6, v7
	v_cvt_pk_bf16_f32 v2, v2, v3
	v_cvt_pk_bf16_f32 v3, v10, v11
	global_store_dwordx4 v[26:27], v[0:3], off offset:2048 nt
	s_cbranch_vccnz .LBB0_1352
	s_andn2_b64 vcc, exec, s[0:1]
	s_cbranch_vccnz .LBB0_1351
	s_branch .LBB0_1351
